# first LDS fragment reads of each GEMM unit hoisted above the next-unit index arithmetic
# speedup vs baseline: 1.0045x; 1.0042x over previous
.LBB0_334:
	ds_read_b128 v[152:155], v148
	ds_read_b128 v[156:159], v148 offset:1024
	ds_read_b128 v[160:163], v148 offset:2048
	ds_read_b128 v[164:167], v148 offset:3072
	ds_read_b128 v[168:171], v149
	ds_read_b128 v[172:175], v149 offset:1024
	ds_read_b128 v[176:179], v149 offset:2048
	ds_read_b128 v[180:183], v149 offset:3072
	ds_read_b128 v[184:187], v150
	ds_read_b128 v[188:191], v150 offset:1024
	ds_read_b128 v[192:195], v150 offset:2048
	ds_read_b128 v[196:199], v150 offset:3072
	ds_read_b128 v[200:203], v150 offset:4096
	ds_read_b128 v[204:207], v150 offset:5120
	ds_read_b128 v[208:211], v150 offset:6144
	ds_read_b128 v[212:215], v150 offset:7168
	s_add_i32 s47, s48, 1
	s_mul_i32 s0, s47, s30
	s_mul_hi_u32 s1, s47, s31
	s_add_i32 s1, s1, s0
	s_mul_i32 s0, s47, s31
	s_add_u32 s18, s0, s2
	s_addc_u32 s19, s1, s3
	v_cmp_gt_i64_e32 vcc, s[18:19], v[142:143]
	v_cmp_lt_i64_e64 s[0:1], s[18:19], v[140:141]
	s_cbranch_vccnz .LBB0_336
	s_ashr_i32 s14, s18, 31
	s_lshr_b32 s14, s14, 29
	s_add_i32 s14, s18, s14
	s_ashr_i32 s15, s14, 3
	s_and_b32 s14, s14, -8
	s_sub_i32 s14, s18, s14
	s_cmp_lt_i32 s14, 0
	s_cselect_b32 s16, s38, 0x160
	s_mul_i32 s14, s16, s14
	s_add_i32 s14, s14, s15
	s_mul_hi_i32 s15, s14, 0x2e8ba2e9
	s_lshr_b32 s16, s15, 31
	s_ashr_i32 s15, s15, 5
	s_add_i32 s15, s15, s16
	s_lshl_b32 s16, s15, 3
	s_sub_i32 s17, 0x80, s16
	s_min_i32 s17, s17, 8
	s_abs_i32 s18, s17
	v_cvt_f32_u32_e32 v0, s18
	s_sub_i32 s20, 0, s18
	s_mulk_i32 s15, 0xb0
	s_sub_i32 s15, s14, s15
	v_rcp_iflag_f32_e32 v0, v0
	s_abs_i32 s14, s15
	s_xor_b32 s19, s15, s17
	s_ashr_i32 s19, s19, 31
	v_mul_f32_e32 v0, 0x4f7ffffe, v0
	v_cvt_u32_f32_e32 v0, v0
	s_nop 0
	v_readfirstlane_b32 s21, v0
	s_mul_i32 s20, s20, s21
	s_mul_hi_u32 s20, s21, s20
	s_add_i32 s21, s21, s20
	s_mul_hi_u32 s20, s14, s21
	s_mul_i32 s21, s20, s18
	s_sub_i32 s14, s14, s21
	s_add_i32 s28, s20, 1
	s_sub_i32 s21, s14, s18
	s_cmp_ge_u32 s14, s18
	s_cselect_b32 s20, s28, s20
	s_cselect_b32 s14, s21, s14
	s_add_i32 s21, s20, 1
	s_cmp_ge_u32 s14, s18
	s_cselect_b32 s14, s21, s20
	s_xor_b32 s14, s14, s19
	s_sub_i32 s14, s14, s19
	s_mul_i32 s17, s14, s17
	s_sub_i32 s15, s15, s17
	s_add_i32 s16, s15, s16
.LBB0_336:
	s_ashr_i32 s17, s16, 31
	s_lshl_b64 s[18:19], s[16:17], 19
	s_add_u32 s18, s36, s18
	s_addc_u32 s19, s37, s19
	s_and_b64 s[20:21], s[0:1], exec
	s_cselect_b32 s17, s19, s25
	s_cselect_b32 s50, s18, s24
	s_ashr_i32 s15, s14, 31
	s_lshl_b64 s[20:21], s[14:15], 19
	s_add_u32 s20, s34, s20
	s_addc_u32 s21, s35, s21
	s_and_b64 s[28:29], s[0:1], exec
	s_cselect_b32 s15, s21, s27
	s_cselect_b32 s51, s20, s26
	s_add_u32 s24, s24, 0x40080
	s_addc_u32 s25, s25, 0
	s_add_u32 s52, s26, 0x100
	s_addc_u32 s53, s27, 0
	s_mov_b32 s54, -2
	s_add_u32 s26, s24, 0xfffc0080
	s_addc_u32 s27, s25, -1
	s_cmp_eq_u32 s54, 12
	s_cselect_b32 s29, s17, s27
	s_cselect_b32 s28, s50, s26
	s_cselect_b32 s27, s15, s53
	s_cselect_b32 s26, s51, s52
	v_lshl_add_u64 v[216:217], s[24:25], 0, v[136:137]
	s_add_i32 m0, s23, 0xc000
	global_load_lds_dwordx4 v[216:217], off
	v_lshl_add_u64 v[216:217], s[24:25], 0, v[138:139]
	s_add_i32 m0, s23, 0xe000
	s_nop 0
	global_load_lds_dwordx4 v[216:217], off
	s_waitcnt vmcnt(8)
	s_waitcnt lgkmcnt(0)
	s_barrier
	s_setprio 1
	s_waitcnt lgkmcnt(0)
	v_mfma_f32_16x16x32_bf16 v[124:127], v[152:155], v[184:187], 0
	v_mfma_f32_16x16x32_bf16 v[120:123], v[160:163], v[184:187], 0
	v_mfma_f32_16x16x32_bf16 v[108:111], v[152:155], v[192:195], 0
	v_mfma_f32_16x16x32_bf16 v[104:107], v[160:163], v[192:195], 0
	v_mfma_f32_16x16x32_bf16 v[92:95], v[152:155], v[200:203], 0
	v_mfma_f32_16x16x32_bf16 v[88:91], v[160:163], v[200:203], 0
	v_mfma_f32_16x16x32_bf16 v[76:79], v[152:155], v[208:211], 0
	v_mfma_f32_16x16x32_bf16 v[72:75], v[160:163], v[208:211], 0
	v_mfma_f32_16x16x32_bf16 v[124:127], v[156:159], v[188:191], v[124:127]
	v_mfma_f32_16x16x32_bf16 v[120:123], v[164:167], v[188:191], v[120:123]
	v_mfma_f32_16x16x32_bf16 v[108:111], v[156:159], v[196:199], v[108:111]
	v_mfma_f32_16x16x32_bf16 v[104:107], v[164:167], v[196:199], v[104:107]
	v_mfma_f32_16x16x32_bf16 v[92:95], v[156:159], v[204:207], v[92:95]
	v_mfma_f32_16x16x32_bf16 v[88:91], v[164:167], v[204:207], v[88:91]
	v_mfma_f32_16x16x32_bf16 v[76:79], v[156:159], v[212:215], v[76:79]
	v_mfma_f32_16x16x32_bf16 v[72:75], v[164:167], v[212:215], v[72:75]
	s_setprio 0
	s_setprio 1
	v_mfma_f32_16x16x32_bf16 v[116:119], v[168:171], v[184:187], 0
	v_mfma_f32_16x16x32_bf16 v[112:115], v[176:179], v[184:187], 0
	v_mfma_f32_16x16x32_bf16 v[100:103], v[168:171], v[192:195], 0
	v_mfma_f32_16x16x32_bf16 v[96:99], v[176:179], v[192:195], 0
	v_mfma_f32_16x16x32_bf16 v[84:87], v[168:171], v[200:203], 0
	v_mfma_f32_16x16x32_bf16 v[80:83], v[176:179], v[200:203], 0
	v_mfma_f32_16x16x32_bf16 v[68:71], v[168:171], v[208:211], 0
	v_mfma_f32_16x16x32_bf16 v[64:67], v[176:179], v[208:211], 0
	v_mfma_f32_16x16x32_bf16 v[116:119], v[172:175], v[188:191], v[116:119]
	v_mfma_f32_16x16x32_bf16 v[112:115], v[180:183], v[188:191], v[112:115]
	v_mfma_f32_16x16x32_bf16 v[100:103], v[172:175], v[196:199], v[100:103]
	v_mfma_f32_16x16x32_bf16 v[96:99], v[180:183], v[196:199], v[96:99]
	v_mfma_f32_16x16x32_bf16 v[84:87], v[172:175], v[204:207], v[84:87]
	v_mfma_f32_16x16x32_bf16 v[80:83], v[180:183], v[204:207], v[80:83]
	v_mfma_f32_16x16x32_bf16 v[68:71], v[172:175], v[212:215], v[68:71]
	v_mfma_f32_16x16x32_bf16 v[64:67], v[180:183], v[212:215], v[64:67]
	s_setprio 0
	s_barrier
	s_add_i32 s55, s44, s33
	v_lshl_add_u64 v[216:217], s[26:27], 0, v[132:133]
	s_mov_b32 m0, s55
	ds_read_b128 v[184:187], v150 offset:16384
	ds_read_b128 v[188:191], v150 offset:17408
	ds_read_b128 v[192:195], v150 offset:18432
	ds_read_b128 v[196:199], v150 offset:19456
	ds_read_b128 v[200:203], v150 offset:20480
	ds_read_b128 v[204:207], v150 offset:21504
	ds_read_b128 v[208:211], v150 offset:22528
	ds_read_b128 v[212:215], v150 offset:23552
	global_load_lds_dwordx4 v[216:217], off
	s_add_i32 m0, s55, 0x2000
	s_add_u32 s56, s26, 0x40000
	v_lshl_add_u64 v[218:219], s[26:27], 0, v[128:129]
	s_addc_u32 s57, s27, 0
	s_add_i32 s55, s45, s33
	global_load_lds_dwordx4 v[218:219], off
	v_lshl_add_u64 v[220:221], s[56:57], 0, v[132:133]
	s_mov_b32 m0, s55
	v_lshl_add_u64 v[222:223], s[28:29], 0, v[130:131]
	global_load_lds_dwordx4 v[220:221], off
	v_lshl_add_u64 v[220:221], s[56:57], 0, v[128:129]
	s_add_i32 m0, s55, 0x2000
	s_nop 0
	global_load_lds_dwordx4 v[220:221], off
	v_lshl_add_u64 v[220:221], s[28:29], 0, v[134:135]
	s_mov_b32 m0, s23
	s_nop 0
	global_load_lds_dwordx4 v[220:221], off
	s_mov_b32 m0, s39
	s_nop 0
	global_load_lds_dwordx4 v[222:223], off
	s_waitcnt vmcnt(8)
	s_waitcnt lgkmcnt(0)
	s_barrier
	s_setprio 1
	s_waitcnt lgkmcnt(0)
	v_mfma_f32_16x16x32_bf16 v[60:63], v[152:155], v[184:187], 0
	v_mfma_f32_16x16x32_bf16 v[56:59], v[160:163], v[184:187], 0
	v_mfma_f32_16x16x32_bf16 v[44:47], v[152:155], v[192:195], 0
	v_mfma_f32_16x16x32_bf16 v[40:43], v[160:163], v[192:195], 0
	v_mfma_f32_16x16x32_bf16 v[28:31], v[152:155], v[200:203], 0
	v_mfma_f32_16x16x32_bf16 v[24:27], v[160:163], v[200:203], 0
	v_mfma_f32_16x16x32_bf16 v[12:15], v[152:155], v[208:211], 0
	v_mfma_f32_16x16x32_bf16 v[8:11], v[160:163], v[208:211], 0
	v_mfma_f32_16x16x32_bf16 v[60:63], v[156:159], v[188:191], v[60:63]
	v_mfma_f32_16x16x32_bf16 v[56:59], v[164:167], v[188:191], v[56:59]
	v_mfma_f32_16x16x32_bf16 v[44:47], v[156:159], v[196:199], v[44:47]
	v_mfma_f32_16x16x32_bf16 v[40:43], v[164:167], v[196:199], v[40:43]
	v_mfma_f32_16x16x32_bf16 v[28:31], v[156:159], v[204:207], v[28:31]
	v_mfma_f32_16x16x32_bf16 v[24:27], v[164:167], v[204:207], v[24:27]
	v_mfma_f32_16x16x32_bf16 v[12:15], v[156:159], v[212:215], v[12:15]
	v_mfma_f32_16x16x32_bf16 v[8:11], v[164:167], v[212:215], v[8:11]
	s_setprio 0
	s_setprio 1
	v_mfma_f32_16x16x32_bf16 v[52:55], v[168:171], v[184:187], 0
	v_mfma_f32_16x16x32_bf16 v[48:51], v[176:179], v[184:187], 0
	v_mfma_f32_16x16x32_bf16 v[36:39], v[168:171], v[192:195], 0
	v_mfma_f32_16x16x32_bf16 v[32:35], v[176:179], v[192:195], 0
	v_mfma_f32_16x16x32_bf16 v[20:23], v[168:171], v[200:203], 0
	v_mfma_f32_16x16x32_bf16 v[16:19], v[176:179], v[200:203], 0
	v_mfma_f32_16x16x32_bf16 v[4:7], v[168:171], v[208:211], 0
	v_mfma_f32_16x16x32_bf16 v[0:3], v[176:179], v[208:211], 0
	v_mfma_f32_16x16x32_bf16 v[52:55], v[172:175], v[188:191], v[52:55]
	v_mfma_f32_16x16x32_bf16 v[48:51], v[180:183], v[188:191], v[48:51]
	v_mfma_f32_16x16x32_bf16 v[36:39], v[172:175], v[196:199], v[36:39]
	v_mfma_f32_16x16x32_bf16 v[32:35], v[180:183], v[196:199], v[32:35]
	v_mfma_f32_16x16x32_bf16 v[20:23], v[172:175], v[204:207], v[20:23]
	v_mfma_f32_16x16x32_bf16 v[16:19], v[180:183], v[204:207], v[16:19]
	v_mfma_f32_16x16x32_bf16 v[4:7], v[172:175], v[212:215], v[4:7]
	v_mfma_f32_16x16x32_bf16 v[0:3], v[180:183], v[212:215], v[0:3]
	s_setprio 0
	s_barrier
	s_add_i32 s55, 0, 0x18000
	v_add_u32_e32 v151, s55, v145
	s_add_i32 s56, 0, 0x1c000
	ds_read_b128 v[152:155], v151
	ds_read_b128 v[156:159], v151 offset:1024
	ds_read_b128 v[160:163], v151 offset:2048
	ds_read_b128 v[164:167], v151 offset:3072
	v_add_u32_e32 v151, s56, v145
	ds_read_b128 v[168:171], v151
	ds_read_b128 v[172:175], v151 offset:1024
	ds_read_b128 v[176:179], v151 offset:2048
	ds_read_b128 v[180:183], v151 offset:3072
	s_add_u32 s28, s28, 0x40000
	s_addc_u32 s29, s29, 0
	s_mov_b32 m0, s40
	v_lshl_add_u64 v[224:225], s[28:29], 0, v[134:135]
	ds_read_b128 v[184:187], v150 offset:32768
	ds_read_b128 v[188:191], v150 offset:33792
	ds_read_b128 v[192:195], v150 offset:34816
	ds_read_b128 v[196:199], v150 offset:35840
	ds_read_b128 v[200:203], v150 offset:36864
	ds_read_b128 v[204:207], v150 offset:37888
	ds_read_b128 v[208:211], v150 offset:38912
	ds_read_b128 v[212:215], v150 offset:39936
	global_load_lds_dwordx4 v[224:225], off
	v_lshl_add_u64 v[224:225], s[28:29], 0, v[130:131]
	s_mov_b32 m0, s41
	s_nop 0
	global_load_lds_dwordx4 v[224:225], off
	s_waitcnt vmcnt(8)
	s_waitcnt lgkmcnt(0)
	s_barrier
	s_setprio 1
	s_waitcnt lgkmcnt(0)
	v_mfma_f32_16x16x32_bf16 v[124:127], v[152:155], v[184:187], v[124:127]
	v_mfma_f32_16x16x32_bf16 v[120:123], v[160:163], v[184:187], v[120:123]
	v_mfma_f32_16x16x32_bf16 v[108:111], v[152:155], v[192:195], v[108:111]
	v_mfma_f32_16x16x32_bf16 v[104:107], v[160:163], v[192:195], v[104:107]
	v_mfma_f32_16x16x32_bf16 v[92:95], v[152:155], v[200:203], v[92:95]
	v_mfma_f32_16x16x32_bf16 v[88:91], v[160:163], v[200:203], v[88:91]
	v_mfma_f32_16x16x32_bf16 v[76:79], v[152:155], v[208:211], v[76:79]
	v_mfma_f32_16x16x32_bf16 v[72:75], v[160:163], v[208:211], v[72:75]
	v_mfma_f32_16x16x32_bf16 v[124:127], v[156:159], v[188:191], v[124:127]
	v_mfma_f32_16x16x32_bf16 v[120:123], v[164:167], v[188:191], v[120:123]
	v_mfma_f32_16x16x32_bf16 v[108:111], v[156:159], v[196:199], v[108:111]
	v_mfma_f32_16x16x32_bf16 v[104:107], v[164:167], v[196:199], v[104:107]
	v_mfma_f32_16x16x32_bf16 v[92:95], v[156:159], v[204:207], v[92:95]
	v_mfma_f32_16x16x32_bf16 v[88:91], v[164:167], v[204:207], v[88:91]
	v_mfma_f32_16x16x32_bf16 v[76:79], v[156:159], v[212:215], v[76:79]
	v_mfma_f32_16x16x32_bf16 v[72:75], v[164:167], v[212:215], v[72:75]
	s_setprio 0
	s_setprio 1
	v_mfma_f32_16x16x32_bf16 v[116:119], v[168:171], v[184:187], v[116:119]
	v_mfma_f32_16x16x32_bf16 v[112:115], v[176:179], v[184:187], v[112:115]
	v_mfma_f32_16x16x32_bf16 v[100:103], v[168:171], v[192:195], v[100:103]
	v_mfma_f32_16x16x32_bf16 v[96:99], v[176:179], v[192:195], v[96:99]
	v_mfma_f32_16x16x32_bf16 v[84:87], v[168:171], v[200:203], v[84:87]
	v_mfma_f32_16x16x32_bf16 v[80:83], v[176:179], v[200:203], v[80:83]
	v_mfma_f32_16x16x32_bf16 v[68:71], v[168:171], v[208:211], v[68:71]
	v_mfma_f32_16x16x32_bf16 v[64:67], v[176:179], v[208:211], v[64:67]
	v_mfma_f32_16x16x32_bf16 v[116:119], v[172:175], v[188:191], v[116:119]
	v_mfma_f32_16x16x32_bf16 v[112:115], v[180:183], v[188:191], v[112:115]
	v_mfma_f32_16x16x32_bf16 v[100:103], v[172:175], v[196:199], v[100:103]
	v_mfma_f32_16x16x32_bf16 v[96:99], v[180:183], v[196:199], v[96:99]
	v_mfma_f32_16x16x32_bf16 v[84:87], v[172:175], v[204:207], v[84:87]
	v_mfma_f32_16x16x32_bf16 v[80:83], v[180:183], v[204:207], v[80:83]
	v_mfma_f32_16x16x32_bf16 v[68:71], v[172:175], v[212:215], v[68:71]
	v_mfma_f32_16x16x32_bf16 v[64:67], v[180:183], v[212:215], v[64:67]
	s_setprio 0
	s_barrier
	s_add_i32 s28, s55, s33
	v_lshl_add_u64 v[216:217], v[216:217], 0, s[8:9]
	s_mov_b32 m0, s28
	ds_read_b128 v[184:187], v150 offset:49152
	ds_read_b128 v[188:191], v150 offset:50176
	ds_read_b128 v[192:195], v150 offset:51200
	ds_read_b128 v[196:199], v150 offset:52224
	ds_read_b128 v[200:203], v150 offset:53248
	ds_read_b128 v[204:207], v150 offset:54272
	ds_read_b128 v[208:211], v150 offset:55296
	ds_read_b128 v[212:215], v150 offset:56320
	global_load_lds_dwordx4 v[216:217], off
	s_add_i32 m0, s28, 0x2000
	s_add_u32 s26, s26, 0x40080
	v_lshl_add_u64 v[216:217], v[218:219], 0, s[8:9]
	s_addc_u32 s27, s27, 0
	s_add_i32 s28, s56, s33
	global_load_lds_dwordx4 v[216:217], off
	v_lshl_add_u64 v[216:217], s[26:27], 0, v[132:133]
	s_mov_b32 m0, s28
	s_nop 0
	global_load_lds_dwordx4 v[216:217], off
	v_lshl_add_u64 v[216:217], s[26:27], 0, v[128:129]
	s_add_i32 m0, s28, 0x2000
	s_nop 0
	global_load_lds_dwordx4 v[216:217], off
	v_lshl_add_u64 v[216:217], v[220:221], 0, s[8:9]
	s_mov_b32 m0, s42
	s_nop 0
	global_load_lds_dwordx4 v[216:217], off
	v_lshl_add_u64 v[216:217], v[222:223], 0, s[8:9]
	s_mov_b32 m0, s43
	s_nop 0
	global_load_lds_dwordx4 v[216:217], off
	s_waitcnt vmcnt(8)
	s_waitcnt lgkmcnt(0)
	s_barrier
	s_setprio 1
	s_waitcnt lgkmcnt(0)
	v_mfma_f32_16x16x32_bf16 v[60:63], v[152:155], v[184:187], v[60:63]
	v_mfma_f32_16x16x32_bf16 v[56:59], v[160:163], v[184:187], v[56:59]
	v_mfma_f32_16x16x32_bf16 v[44:47], v[152:155], v[192:195], v[44:47]
	v_mfma_f32_16x16x32_bf16 v[40:43], v[160:163], v[192:195], v[40:43]
	v_mfma_f32_16x16x32_bf16 v[28:31], v[152:155], v[200:203], v[28:31]
	v_mfma_f32_16x16x32_bf16 v[24:27], v[160:163], v[200:203], v[24:27]
	v_mfma_f32_16x16x32_bf16 v[12:15], v[152:155], v[208:211], v[12:15]
	v_mfma_f32_16x16x32_bf16 v[8:11], v[160:163], v[208:211], v[8:11]
	v_mfma_f32_16x16x32_bf16 v[60:63], v[156:159], v[188:191], v[60:63]
	v_mfma_f32_16x16x32_bf16 v[56:59], v[164:167], v[188:191], v[56:59]
	v_mfma_f32_16x16x32_bf16 v[44:47], v[156:159], v[196:199], v[44:47]
	v_mfma_f32_16x16x32_bf16 v[40:43], v[164:167], v[196:199], v[40:43]
	v_mfma_f32_16x16x32_bf16 v[28:31], v[156:159], v[204:207], v[28:31]
	v_mfma_f32_16x16x32_bf16 v[24:27], v[164:167], v[204:207], v[24:27]
	v_mfma_f32_16x16x32_bf16 v[12:15], v[156:159], v[212:215], v[12:15]
	v_mfma_f32_16x16x32_bf16 v[8:11], v[164:167], v[212:215], v[8:11]
	s_setprio 0
	s_setprio 1
	v_mfma_f32_16x16x32_bf16 v[52:55], v[168:171], v[184:187], v[52:55]
	v_mfma_f32_16x16x32_bf16 v[48:51], v[176:179], v[184:187], v[48:51]
	v_mfma_f32_16x16x32_bf16 v[36:39], v[168:171], v[192:195], v[36:39]
	v_mfma_f32_16x16x32_bf16 v[32:35], v[176:179], v[192:195], v[32:35]
	v_mfma_f32_16x16x32_bf16 v[20:23], v[168:171], v[200:203], v[20:23]
	v_mfma_f32_16x16x32_bf16 v[16:19], v[176:179], v[200:203], v[16:19]
	v_mfma_f32_16x16x32_bf16 v[4:7], v[168:171], v[208:211], v[4:7]
	v_mfma_f32_16x16x32_bf16 v[0:3], v[176:179], v[208:211], v[0:3]
	v_mfma_f32_16x16x32_bf16 v[52:55], v[172:175], v[188:191], v[52:55]
	v_mfma_f32_16x16x32_bf16 v[48:51], v[180:183], v[188:191], v[48:51]
	v_mfma_f32_16x16x32_bf16 v[36:39], v[172:175], v[196:199], v[36:39]
	v_mfma_f32_16x16x32_bf16 v[32:35], v[180:183], v[196:199], v[32:35]
	v_mfma_f32_16x16x32_bf16 v[20:23], v[172:175], v[204:207], v[20:23]
	v_mfma_f32_16x16x32_bf16 v[16:19], v[180:183], v[204:207], v[16:19]
	v_mfma_f32_16x16x32_bf16 v[4:7], v[172:175], v[212:215], v[4:7]
	v_mfma_f32_16x16x32_bf16 v[0:3], v[180:183], v[212:215], v[0:3]
	s_setprio 0
	s_barrier
	s_add_i32 s54, s54, 2
	s_add_u32 s24, s24, 0x100
	s_addc_u32 s25, s25, 0
	s_add_u32 s52, s52, 0x100
	s_addc_u32 s53, s53, 0
	s_cmp_gt_u32 s54, 13

.LBB0_407:
	ds_read_b128 v[120:123], v245
	ds_read_b128 v[128:131], v245 offset:1024
	ds_read_b128 v[136:139], v245 offset:2048
	ds_read_b128 v[140:143], v245 offset:3072
	ds_read_b128 v[144:147], v246
	ds_read_b128 v[148:151], v246 offset:1024
	ds_read_b128 v[152:155], v246 offset:2048
	ds_read_b128 v[156:159], v246 offset:3072
	ds_read_b128 v[160:163], v247
	ds_read_b128 v[164:167], v247 offset:1024
	ds_read_b128 v[168:171], v247 offset:2048
	ds_read_b128 v[172:175], v247 offset:3072
	ds_read_b128 v[176:179], v247 offset:4096
	ds_read_b128 v[180:183], v247 offset:5120
	ds_read_b128 v[184:187], v247 offset:6144
	ds_read_b128 v[188:191], v247 offset:7168
	s_add_i32 s47, s47, 1
	s_mul_i32 s4, s47, s42
	s_mul_hi_u32 s5, s47, s43
	s_add_i32 s5, s5, s4
	s_mul_i32 s4, s47, s43
	s_add_u32 s4, s4, s2
	s_addc_u32 s5, s5, s44
	s_waitcnt lgkmcnt(0)
	v_mov_b64_e32 v[0:1], 0x200
	v_cmp_lt_i64_e64 s[6:7], s[4:5], v[0:1]
	v_mov_b64_e32 v[0:1], 0x1ff
	v_cmp_gt_i64_e32 vcc, s[4:5], v[0:1]
	s_cbranch_vccnz .LBB0_413
	s_ashr_i32 s5, s4, 31
	s_lshr_b32 s5, s5, 29
	s_add_i32 s22, s4, s5
	s_and_b32 s5, s22, -8
	s_sub_i32 s23, s4, s5
	s_cmp_gt_i32 s23, -1
	s_mov_b64 s[4:5], -1
	s_cbranch_scc0 .LBB0_410
	s_lshl_b32 s28, s23, 6
	s_mov_b64 s[4:5], 0

.LBB0_417:
	s_add_u32 s24, s24, 0xb0080
	s_addc_u32 s25, s25, 0
	s_add_u32 s51, s26, 0x100
	s_addc_u32 s52, s27, 0
	s_mov_b32 s53, -2
	s_waitcnt lgkmcnt(0)
	s_add_u32 s26, s24, 0xfff50080
	s_addc_u32 s27, s25, -1
	s_cmp_eq_u32 s53, 40
	s_cselect_b32 s29, s7, s27
	s_cselect_b32 s28, s6, s26
	s_cselect_b32 s27, s23, s52
	s_cselect_b32 s26, s22, s51
	v_lshl_add_u64 v[204:205], s[24:25], 0, v[200:201]
	s_add_i32 m0, s35, 0xc000
	global_load_lds_dwordx4 v[204:205], off
	v_lshl_add_u64 v[204:205], s[24:25], 0, v[202:203]
	s_add_i32 m0, s35, 0xe000
	s_nop 0
	global_load_lds_dwordx4 v[204:205], off
	s_waitcnt vmcnt(8)
	s_waitcnt lgkmcnt(0)
	s_barrier
	s_setprio 1
	s_waitcnt lgkmcnt(0)
	v_mfma_f32_16x16x32_bf16 v[132:135], v[120:123], v[160:163], 0
	v_mfma_f32_16x16x32_bf16 v[124:127], v[136:139], v[160:163], 0
	v_mfma_f32_16x16x32_bf16 v[108:111], v[120:123], v[168:171], 0
	v_mfma_f32_16x16x32_bf16 v[104:107], v[136:139], v[168:171], 0
	v_mfma_f32_16x16x32_bf16 v[92:95], v[120:123], v[176:179], 0
	v_mfma_f32_16x16x32_bf16 v[88:91], v[136:139], v[176:179], 0
	v_mfma_f32_16x16x32_bf16 v[76:79], v[120:123], v[184:187], 0
	v_mfma_f32_16x16x32_bf16 v[72:75], v[136:139], v[184:187], 0
	v_mfma_f32_16x16x32_bf16 v[132:135], v[128:131], v[164:167], v[132:135]
	v_mfma_f32_16x16x32_bf16 v[124:127], v[140:143], v[164:167], v[124:127]
	v_mfma_f32_16x16x32_bf16 v[108:111], v[128:131], v[172:175], v[108:111]
	v_mfma_f32_16x16x32_bf16 v[104:107], v[140:143], v[172:175], v[104:107]
	v_mfma_f32_16x16x32_bf16 v[92:95], v[128:131], v[180:183], v[92:95]
	v_mfma_f32_16x16x32_bf16 v[88:91], v[140:143], v[180:183], v[88:91]
	v_mfma_f32_16x16x32_bf16 v[76:79], v[128:131], v[188:191], v[76:79]
	v_mfma_f32_16x16x32_bf16 v[72:75], v[140:143], v[188:191], v[72:75]
	s_setprio 0
	s_setprio 1
	v_mfma_f32_16x16x32_bf16 v[116:119], v[144:147], v[160:163], 0
	v_mfma_f32_16x16x32_bf16 v[112:115], v[152:155], v[160:163], 0
	v_mfma_f32_16x16x32_bf16 v[100:103], v[144:147], v[168:171], 0
	v_mfma_f32_16x16x32_bf16 v[96:99], v[152:155], v[168:171], 0
	v_mfma_f32_16x16x32_bf16 v[84:87], v[144:147], v[176:179], 0
	v_mfma_f32_16x16x32_bf16 v[80:83], v[152:155], v[176:179], 0
	v_mfma_f32_16x16x32_bf16 v[68:71], v[144:147], v[184:187], 0
	v_mfma_f32_16x16x32_bf16 v[64:67], v[152:155], v[184:187], 0
	v_mfma_f32_16x16x32_bf16 v[116:119], v[148:151], v[164:167], v[116:119]
	v_mfma_f32_16x16x32_bf16 v[112:115], v[156:159], v[164:167], v[112:115]
	v_mfma_f32_16x16x32_bf16 v[100:103], v[148:151], v[172:175], v[100:103]
	v_mfma_f32_16x16x32_bf16 v[96:99], v[156:159], v[172:175], v[96:99]
	v_mfma_f32_16x16x32_bf16 v[84:87], v[148:151], v[180:183], v[84:87]
	v_mfma_f32_16x16x32_bf16 v[80:83], v[156:159], v[180:183], v[80:83]
	v_mfma_f32_16x16x32_bf16 v[68:71], v[148:151], v[188:191], v[68:71]
	v_mfma_f32_16x16x32_bf16 v[64:67], v[156:159], v[188:191], v[64:67]
	s_setprio 0
	s_barrier
	s_add_i32 s54, s45, s34
	v_lshl_add_u64 v[204:205], s[26:27], 0, v[194:195]
	s_mov_b32 m0, s54
	ds_read_b128 v[160:163], v247 offset:16384
	ds_read_b128 v[164:167], v247 offset:17408
	ds_read_b128 v[168:171], v247 offset:18432
	ds_read_b128 v[172:175], v247 offset:19456
	ds_read_b128 v[176:179], v247 offset:20480
	ds_read_b128 v[180:183], v247 offset:21504
	ds_read_b128 v[184:187], v247 offset:22528
	ds_read_b128 v[188:191], v247 offset:23552
	global_load_lds_dwordx4 v[204:205], off
	s_add_i32 m0, s54, 0x2000
	s_add_u32 s54, s26, 0xb0000
	v_lshl_add_u64 v[206:207], s[26:27], 0, v[198:199]
	s_addc_u32 s55, s27, 0
	s_add_i32 s56, s46, s34
	global_load_lds_dwordx4 v[206:207], off
	v_lshl_add_u64 v[208:209], s[54:55], 0, v[194:195]
	s_mov_b32 m0, s56
	v_lshl_add_u64 v[210:211], s[28:29], 0, v[196:197]
	global_load_lds_dwordx4 v[208:209], off
	v_lshl_add_u64 v[208:209], s[54:55], 0, v[198:199]
	s_add_i32 m0, s56, 0x2000
	s_nop 0
	global_load_lds_dwordx4 v[208:209], off
	v_lshl_add_u64 v[208:209], s[28:29], 0, v[192:193]
	s_mov_b32 m0, s35
	s_nop 0
	global_load_lds_dwordx4 v[208:209], off
	s_mov_b32 m0, s36
	s_nop 0
	global_load_lds_dwordx4 v[210:211], off
	s_waitcnt vmcnt(8)
	s_waitcnt lgkmcnt(0)
	s_barrier
	s_setprio 1
	s_waitcnt lgkmcnt(0)
	v_mfma_f32_16x16x32_bf16 v[60:63], v[120:123], v[160:163], 0
	v_mfma_f32_16x16x32_bf16 v[56:59], v[136:139], v[160:163], 0
	v_mfma_f32_16x16x32_bf16 v[44:47], v[120:123], v[168:171], 0
	v_mfma_f32_16x16x32_bf16 v[40:43], v[136:139], v[168:171], 0
	v_mfma_f32_16x16x32_bf16 v[28:31], v[120:123], v[176:179], 0
	v_mfma_f32_16x16x32_bf16 v[24:27], v[136:139], v[176:179], 0
	v_mfma_f32_16x16x32_bf16 v[12:15], v[120:123], v[184:187], 0
	v_mfma_f32_16x16x32_bf16 v[8:11], v[136:139], v[184:187], 0
	v_mfma_f32_16x16x32_bf16 v[60:63], v[128:131], v[164:167], v[60:63]
	v_mfma_f32_16x16x32_bf16 v[56:59], v[140:143], v[164:167], v[56:59]
	v_mfma_f32_16x16x32_bf16 v[44:47], v[128:131], v[172:175], v[44:47]
	v_mfma_f32_16x16x32_bf16 v[40:43], v[140:143], v[172:175], v[40:43]
	v_mfma_f32_16x16x32_bf16 v[28:31], v[128:131], v[180:183], v[28:31]
	v_mfma_f32_16x16x32_bf16 v[24:27], v[140:143], v[180:183], v[24:27]
	v_mfma_f32_16x16x32_bf16 v[12:15], v[128:131], v[188:191], v[12:15]
	v_mfma_f32_16x16x32_bf16 v[8:11], v[140:143], v[188:191], v[8:11]
	s_setprio 0
	s_setprio 1
	v_mfma_f32_16x16x32_bf16 v[52:55], v[144:147], v[160:163], 0
	v_mfma_f32_16x16x32_bf16 v[48:51], v[152:155], v[160:163], 0
	v_mfma_f32_16x16x32_bf16 v[36:39], v[144:147], v[168:171], 0
	v_mfma_f32_16x16x32_bf16 v[32:35], v[152:155], v[168:171], 0
	v_mfma_f32_16x16x32_bf16 v[20:23], v[144:147], v[176:179], 0
	v_mfma_f32_16x16x32_bf16 v[16:19], v[152:155], v[176:179], 0
	v_mfma_f32_16x16x32_bf16 v[4:7], v[144:147], v[184:187], 0
	v_mfma_f32_16x16x32_bf16 v[0:3], v[152:155], v[184:187], 0
	v_mfma_f32_16x16x32_bf16 v[52:55], v[148:151], v[164:167], v[52:55]
	v_mfma_f32_16x16x32_bf16 v[48:51], v[156:159], v[164:167], v[48:51]
	v_mfma_f32_16x16x32_bf16 v[36:39], v[148:151], v[172:175], v[36:39]
	v_mfma_f32_16x16x32_bf16 v[32:35], v[156:159], v[172:175], v[32:35]
	v_mfma_f32_16x16x32_bf16 v[20:23], v[148:151], v[180:183], v[20:23]
	v_mfma_f32_16x16x32_bf16 v[16:19], v[156:159], v[180:183], v[16:19]
	v_mfma_f32_16x16x32_bf16 v[4:7], v[148:151], v[188:191], v[4:7]
	v_mfma_f32_16x16x32_bf16 v[0:3], v[156:159], v[188:191], v[0:3]
	s_setprio 0
	s_barrier
	s_add_i32 s54, 0, 0x18000
	s_add_i32 s55, 0, 0x1c000
	v_add_u32_e32 v140, s54, v243
	v_add_u32_e32 v156, s55, v243
	ds_read_b128 v[120:123], v140
	ds_read_b128 v[128:131], v140 offset:1024
	ds_read_b128 v[136:139], v140 offset:2048
	ds_read_b128 v[140:143], v140 offset:3072
	ds_read_b128 v[144:147], v156
	ds_read_b128 v[148:151], v156 offset:1024
	ds_read_b128 v[152:155], v156 offset:2048
	ds_read_b128 v[156:159], v156 offset:3072
	s_add_u32 s28, s28, 0xb0000
	s_addc_u32 s29, s29, 0
	s_mov_b32 m0, s37
	v_lshl_add_u64 v[212:213], s[28:29], 0, v[192:193]
	ds_read_b128 v[160:163], v247 offset:32768
	ds_read_b128 v[164:167], v247 offset:33792
	ds_read_b128 v[168:171], v247 offset:34816
	ds_read_b128 v[172:175], v247 offset:35840
	ds_read_b128 v[176:179], v247 offset:36864
	ds_read_b128 v[180:183], v247 offset:37888
	ds_read_b128 v[184:187], v247 offset:38912
	ds_read_b128 v[188:191], v247 offset:39936
	global_load_lds_dwordx4 v[212:213], off
	v_lshl_add_u64 v[212:213], s[28:29], 0, v[196:197]
	s_mov_b32 m0, s38
	s_nop 0
	global_load_lds_dwordx4 v[212:213], off
	s_waitcnt vmcnt(8)
	s_waitcnt lgkmcnt(0)
	s_barrier
	s_setprio 1
	s_waitcnt lgkmcnt(0)
	v_mfma_f32_16x16x32_bf16 v[132:135], v[120:123], v[160:163], v[132:135]
	v_mfma_f32_16x16x32_bf16 v[124:127], v[136:139], v[160:163], v[124:127]
	v_mfma_f32_16x16x32_bf16 v[108:111], v[120:123], v[168:171], v[108:111]
	v_mfma_f32_16x16x32_bf16 v[104:107], v[136:139], v[168:171], v[104:107]
	v_mfma_f32_16x16x32_bf16 v[92:95], v[120:123], v[176:179], v[92:95]
	v_mfma_f32_16x16x32_bf16 v[88:91], v[136:139], v[176:179], v[88:91]
	v_mfma_f32_16x16x32_bf16 v[76:79], v[120:123], v[184:187], v[76:79]
	v_mfma_f32_16x16x32_bf16 v[72:75], v[136:139], v[184:187], v[72:75]
	v_mfma_f32_16x16x32_bf16 v[132:135], v[128:131], v[164:167], v[132:135]
	v_mfma_f32_16x16x32_bf16 v[124:127], v[140:143], v[164:167], v[124:127]
	v_mfma_f32_16x16x32_bf16 v[108:111], v[128:131], v[172:175], v[108:111]
	v_mfma_f32_16x16x32_bf16 v[104:107], v[140:143], v[172:175], v[104:107]
	v_mfma_f32_16x16x32_bf16 v[92:95], v[128:131], v[180:183], v[92:95]
	v_mfma_f32_16x16x32_bf16 v[88:91], v[140:143], v[180:183], v[88:91]
	v_mfma_f32_16x16x32_bf16 v[76:79], v[128:131], v[188:191], v[76:79]
	v_mfma_f32_16x16x32_bf16 v[72:75], v[140:143], v[188:191], v[72:75]
	s_setprio 0
	s_setprio 1
	v_mfma_f32_16x16x32_bf16 v[116:119], v[144:147], v[160:163], v[116:119]
	v_mfma_f32_16x16x32_bf16 v[112:115], v[152:155], v[160:163], v[112:115]
	v_mfma_f32_16x16x32_bf16 v[100:103], v[144:147], v[168:171], v[100:103]
	v_mfma_f32_16x16x32_bf16 v[96:99], v[152:155], v[168:171], v[96:99]
	v_mfma_f32_16x16x32_bf16 v[84:87], v[144:147], v[176:179], v[84:87]
	v_mfma_f32_16x16x32_bf16 v[80:83], v[152:155], v[176:179], v[80:83]
	v_mfma_f32_16x16x32_bf16 v[68:71], v[144:147], v[184:187], v[68:71]
	v_mfma_f32_16x16x32_bf16 v[64:67], v[152:155], v[184:187], v[64:67]
	v_mfma_f32_16x16x32_bf16 v[116:119], v[148:151], v[164:167], v[116:119]
	v_mfma_f32_16x16x32_bf16 v[112:115], v[156:159], v[164:167], v[112:115]
	v_mfma_f32_16x16x32_bf16 v[100:103], v[148:151], v[172:175], v[100:103]
	v_mfma_f32_16x16x32_bf16 v[96:99], v[156:159], v[172:175], v[96:99]
	v_mfma_f32_16x16x32_bf16 v[84:87], v[148:151], v[180:183], v[84:87]
	v_mfma_f32_16x16x32_bf16 v[80:83], v[156:159], v[180:183], v[80:83]
	v_mfma_f32_16x16x32_bf16 v[68:71], v[148:151], v[188:191], v[68:71]
	v_mfma_f32_16x16x32_bf16 v[64:67], v[156:159], v[188:191], v[64:67]
	s_setprio 0
	s_barrier
	s_add_i32 s28, s54, s34
	v_lshl_add_u64 v[204:205], v[204:205], 0, s[18:19]
	s_mov_b32 m0, s28
	ds_read_b128 v[160:163], v247 offset:49152
	ds_read_b128 v[164:167], v247 offset:50176
	ds_read_b128 v[168:171], v247 offset:51200
	ds_read_b128 v[172:175], v247 offset:52224
	ds_read_b128 v[176:179], v247 offset:53248
	ds_read_b128 v[180:183], v247 offset:54272
	ds_read_b128 v[184:187], v247 offset:55296
	ds_read_b128 v[188:191], v247 offset:56320
	global_load_lds_dwordx4 v[204:205], off
	s_add_i32 m0, s28, 0x2000
	s_add_u32 s26, s26, 0xb0080
	v_lshl_add_u64 v[204:205], v[206:207], 0, s[18:19]
	s_addc_u32 s27, s27, 0
	s_add_i32 s28, s55, s34
	global_load_lds_dwordx4 v[204:205], off
	v_lshl_add_u64 v[204:205], s[26:27], 0, v[194:195]
	s_mov_b32 m0, s28
	s_nop 0
	global_load_lds_dwordx4 v[204:205], off
	v_lshl_add_u64 v[204:205], s[26:27], 0, v[198:199]
	s_add_i32 m0, s28, 0x2000
	s_nop 0
	global_load_lds_dwordx4 v[204:205], off
	v_lshl_add_u64 v[204:205], v[208:209], 0, s[18:19]
	s_mov_b32 m0, s40
	s_nop 0
	global_load_lds_dwordx4 v[204:205], off
	v_lshl_add_u64 v[204:205], v[210:211], 0, s[18:19]
	s_mov_b32 m0, s41
	s_nop 0
	global_load_lds_dwordx4 v[204:205], off
	s_waitcnt vmcnt(8)
	s_waitcnt lgkmcnt(0)
	s_barrier
	s_setprio 1
	s_waitcnt lgkmcnt(0)
	v_mfma_f32_16x16x32_bf16 v[60:63], v[120:123], v[160:163], v[60:63]
	v_mfma_f32_16x16x32_bf16 v[56:59], v[136:139], v[160:163], v[56:59]
	v_mfma_f32_16x16x32_bf16 v[44:47], v[120:123], v[168:171], v[44:47]
	v_mfma_f32_16x16x32_bf16 v[40:43], v[136:139], v[168:171], v[40:43]
	v_mfma_f32_16x16x32_bf16 v[28:31], v[120:123], v[176:179], v[28:31]
	v_mfma_f32_16x16x32_bf16 v[24:27], v[136:139], v[176:179], v[24:27]
	v_mfma_f32_16x16x32_bf16 v[12:15], v[120:123], v[184:187], v[12:15]
	v_mfma_f32_16x16x32_bf16 v[8:11], v[136:139], v[184:187], v[8:11]
	v_mfma_f32_16x16x32_bf16 v[60:63], v[128:131], v[164:167], v[60:63]
	v_mfma_f32_16x16x32_bf16 v[56:59], v[140:143], v[164:167], v[56:59]
	v_mfma_f32_16x16x32_bf16 v[44:47], v[128:131], v[172:175], v[44:47]
	v_mfma_f32_16x16x32_bf16 v[40:43], v[140:143], v[172:175], v[40:43]
	v_mfma_f32_16x16x32_bf16 v[28:31], v[128:131], v[180:183], v[28:31]
	v_mfma_f32_16x16x32_bf16 v[24:27], v[140:143], v[180:183], v[24:27]
	v_mfma_f32_16x16x32_bf16 v[12:15], v[128:131], v[188:191], v[12:15]
	v_mfma_f32_16x16x32_bf16 v[8:11], v[140:143], v[188:191], v[8:11]
	s_setprio 0
	s_setprio 1
	v_mfma_f32_16x16x32_bf16 v[52:55], v[144:147], v[160:163], v[52:55]
	v_mfma_f32_16x16x32_bf16 v[48:51], v[152:155], v[160:163], v[48:51]
	v_mfma_f32_16x16x32_bf16 v[36:39], v[144:147], v[168:171], v[36:39]
	v_mfma_f32_16x16x32_bf16 v[32:35], v[152:155], v[168:171], v[32:35]
	v_mfma_f32_16x16x32_bf16 v[20:23], v[144:147], v[176:179], v[20:23]
	v_mfma_f32_16x16x32_bf16 v[16:19], v[152:155], v[176:179], v[16:19]
	v_mfma_f32_16x16x32_bf16 v[4:7], v[144:147], v[184:187], v[4:7]
	v_mfma_f32_16x16x32_bf16 v[0:3], v[152:155], v[184:187], v[0:3]
	v_mfma_f32_16x16x32_bf16 v[52:55], v[148:151], v[164:167], v[52:55]
	v_mfma_f32_16x16x32_bf16 v[48:51], v[156:159], v[164:167], v[48:51]
	v_mfma_f32_16x16x32_bf16 v[36:39], v[148:151], v[172:175], v[36:39]
	v_mfma_f32_16x16x32_bf16 v[32:35], v[156:159], v[172:175], v[32:35]
	v_mfma_f32_16x16x32_bf16 v[20:23], v[148:151], v[180:183], v[20:23]
	v_mfma_f32_16x16x32_bf16 v[16:19], v[156:159], v[180:183], v[16:19]
	v_mfma_f32_16x16x32_bf16 v[4:7], v[148:151], v[188:191], v[4:7]
	v_mfma_f32_16x16x32_bf16 v[0:3], v[156:159], v[188:191], v[0:3]
	s_setprio 0
	s_barrier
	s_add_i32 s53, s53, 2
	s_add_u32 s24, s24, 0x100
	s_addc_u32 s25, s25, 0
	s_add_u32 s51, s51, 0x100
	s_addc_u32 s52, s52, 0
	s_cmp_gt_u32 s53, 41

.LBB0_506:
	ds_read_b128 v[148:151], v162
	ds_read_b128 v[166:169], v162 offset:1024
	ds_read_b128 v[170:173], v162 offset:2048
	ds_read_b128 v[174:177], v162 offset:3072
	ds_read_b128 v[178:181], v163
	ds_read_b128 v[182:185], v163 offset:1024
	ds_read_b128 v[186:189], v163 offset:2048
	ds_read_b128 v[190:193], v163 offset:3072
	ds_read_b128 v[194:197], v164
	ds_read_b128 v[198:201], v164 offset:1024
	ds_read_b128 v[202:205], v164 offset:2048
	ds_read_b128 v[206:209], v164 offset:3072
	ds_read_b128 v[210:213], v164 offset:4096
	ds_read_b128 v[214:217], v164 offset:5120
	ds_read_b128 v[218:221], v164 offset:6144
	ds_read_b128 v[222:225], v164 offset:7168
	s_add_i32 s69, s7, 1
	s_mul_i32 s4, s69, s46
	s_mul_hi_u32 s5, s69, s47
	s_add_i32 s5, s5, s4
	s_mul_i32 s4, s69, s47
	s_add_u32 s34, s4, s2
	s_addc_u32 s35, s5, s3
	v_cmp_gt_i64_e32 vcc, s[34:35], v[146:147]
	v_cmp_lt_i64_e64 s[4:5], s[34:35], v[144:145]
	s_cbranch_vccnz .LBB0_508
	s_ashr_i32 s9, s34, 31
	s_lshr_b32 s9, s9, 29
	s_add_i32 s9, s34, s9
	s_ashr_i32 s14, s9, 3
	s_and_b32 s9, s9, -8
	s_sub_i32 s9, s34, s9
	s_cmp_lt_i32 s9, 0
	s_cselect_b32 s28, s60, 0x90
	s_mul_i32 s9, s28, s9
	s_add_i32 s9, s9, s14
	s_mul_hi_i32 s14, s9, 0x38e38e39
	s_lshr_b32 s28, s14, 31
	s_ashr_i32 s14, s14, 4
	s_add_i32 s14, s14, s28
	s_lshl_b32 s29, s14, 3
	s_sub_i32 s28, 0x80, s29
	s_min_i32 s30, s28, 8
	s_abs_i32 s28, s30
	v_cvt_f32_u32_e32 v0, s28
	s_sub_i32 s34, 0, s28
	s_mulk_i32 s14, 0x48
	s_sub_i32 s9, s9, s14
	v_rcp_iflag_f32_e32 v0, v0
	s_abs_i32 s14, s9
	s_xor_b32 s31, s9, s30
	s_ashr_i32 s31, s31, 31
	v_mul_f32_e32 v0, 0x4f7ffffe, v0
	v_cvt_u32_f32_e32 v0, v0
	s_nop 0
	v_readfirstlane_b32 s35, v0
	s_mul_i32 s34, s34, s35
	s_mul_hi_u32 s34, s35, s34
	s_add_i32 s35, s35, s34
	s_mul_hi_u32 s34, s14, s35
	s_mul_i32 s35, s34, s28
	s_sub_i32 s14, s14, s35
	s_add_i32 s36, s34, 1
	s_sub_i32 s35, s14, s28
	s_cmp_ge_u32 s14, s28
	s_cselect_b32 s34, s36, s34
	s_cselect_b32 s14, s35, s14
	s_add_i32 s35, s34, 1
	s_cmp_ge_u32 s14, s28
	s_cselect_b32 s14, s35, s34
	s_xor_b32 s14, s14, s31
	s_sub_i32 s28, s14, s31
	s_mul_i32 s14, s28, s30
	s_sub_i32 s9, s9, s14
	s_add_i32 s30, s9, s29
.LBB0_508:
	s_ashr_i32 s31, s30, 31
	s_lshl_b64 s[34:35], s[30:31], 19
	s_add_u32 s34, s48, s34
	s_addc_u32 s35, s49, s35
	s_and_b64 s[36:37], s[4:5], exec
	s_cselect_b32 s9, s35, s39
	s_cselect_b32 s14, s34, s38
	s_ashr_i32 s29, s28, 31
	s_lshl_b64 s[36:37], s[28:29], 19
	s_add_u32 s36, s50, s36
	s_addc_u32 s37, s51, s37
	s_and_b64 s[42:43], s[4:5], exec
	s_cselect_b32 s29, s37, s41
	s_cselect_b32 s31, s36, s40
	s_add_u32 s38, s38, 0x40080
	s_addc_u32 s39, s39, 0
	s_add_u32 s44, s40, 0x100
	s_addc_u32 s45, s41, 0
	s_mov_b32 s70, -2
	s_add_u32 s40, s38, 0xfffc0080
	s_addc_u32 s41, s39, -1
	s_cmp_eq_u32 s70, 12
	s_cselect_b32 s43, s9, s41
	s_cselect_b32 s42, s14, s40
	s_cselect_b32 s41, s29, s45
	s_cselect_b32 s40, s31, s44
	v_lshl_add_u64 v[226:227], s[38:39], 0, v[132:133]
	s_add_i32 m0, s52, 0xc000
	global_load_lds_dwordx4 v[226:227], off
	v_lshl_add_u64 v[226:227], s[38:39], 0, v[134:135]
	s_add_i32 m0, s52, 0xe000
	s_nop 0
	global_load_lds_dwordx4 v[226:227], off
	s_waitcnt vmcnt(8)
	s_waitcnt lgkmcnt(0)
	s_barrier
	s_setprio 1
	s_waitcnt lgkmcnt(0)
	v_mfma_f32_16x16x32_bf16 v[124:127], v[148:151], v[194:197], 0
	v_mfma_f32_16x16x32_bf16 v[120:123], v[170:173], v[194:197], 0
	v_mfma_f32_16x16x32_bf16 v[108:111], v[148:151], v[202:205], 0
	v_mfma_f32_16x16x32_bf16 v[104:107], v[170:173], v[202:205], 0
	v_mfma_f32_16x16x32_bf16 v[92:95], v[148:151], v[210:213], 0
	v_mfma_f32_16x16x32_bf16 v[88:91], v[170:173], v[210:213], 0
	v_mfma_f32_16x16x32_bf16 v[76:79], v[148:151], v[218:221], 0
	v_mfma_f32_16x16x32_bf16 v[72:75], v[170:173], v[218:221], 0
	v_mfma_f32_16x16x32_bf16 v[124:127], v[166:169], v[198:201], v[124:127]
	v_mfma_f32_16x16x32_bf16 v[120:123], v[174:177], v[198:201], v[120:123]
	v_mfma_f32_16x16x32_bf16 v[108:111], v[166:169], v[206:209], v[108:111]
	v_mfma_f32_16x16x32_bf16 v[104:107], v[174:177], v[206:209], v[104:107]
	v_mfma_f32_16x16x32_bf16 v[92:95], v[166:169], v[214:217], v[92:95]
	v_mfma_f32_16x16x32_bf16 v[88:91], v[174:177], v[214:217], v[88:91]
	v_mfma_f32_16x16x32_bf16 v[76:79], v[166:169], v[222:225], v[76:79]
	v_mfma_f32_16x16x32_bf16 v[72:75], v[174:177], v[222:225], v[72:75]
	s_setprio 0
	s_setprio 1
	v_mfma_f32_16x16x32_bf16 v[116:119], v[178:181], v[194:197], 0
	v_mfma_f32_16x16x32_bf16 v[112:115], v[186:189], v[194:197], 0
	v_mfma_f32_16x16x32_bf16 v[100:103], v[178:181], v[202:205], 0
	v_mfma_f32_16x16x32_bf16 v[96:99], v[186:189], v[202:205], 0
	v_mfma_f32_16x16x32_bf16 v[84:87], v[178:181], v[210:213], 0
	v_mfma_f32_16x16x32_bf16 v[80:83], v[186:189], v[210:213], 0
	v_mfma_f32_16x16x32_bf16 v[68:71], v[178:181], v[218:221], 0
	v_mfma_f32_16x16x32_bf16 v[64:67], v[186:189], v[218:221], 0
	v_mfma_f32_16x16x32_bf16 v[116:119], v[182:185], v[198:201], v[116:119]
	v_mfma_f32_16x16x32_bf16 v[112:115], v[190:193], v[198:201], v[112:115]
	v_mfma_f32_16x16x32_bf16 v[100:103], v[182:185], v[206:209], v[100:103]
	v_mfma_f32_16x16x32_bf16 v[96:99], v[190:193], v[206:209], v[96:99]
	v_mfma_f32_16x16x32_bf16 v[84:87], v[182:185], v[214:217], v[84:87]
	v_mfma_f32_16x16x32_bf16 v[80:83], v[190:193], v[214:217], v[80:83]
	v_mfma_f32_16x16x32_bf16 v[68:71], v[182:185], v[222:225], v[68:71]
	v_mfma_f32_16x16x32_bf16 v[64:67], v[190:193], v[222:225], v[64:67]
	s_setprio 0
	s_barrier
	s_add_i32 s71, s61, s33
	v_lshl_add_u64 v[226:227], s[40:41], 0, v[138:139]
	s_mov_b32 m0, s71
	ds_read_b128 v[194:197], v164 offset:16384
	ds_read_b128 v[198:201], v164 offset:17408
	ds_read_b128 v[202:205], v164 offset:18432
	ds_read_b128 v[206:209], v164 offset:19456
	ds_read_b128 v[210:213], v164 offset:20480
	ds_read_b128 v[214:217], v164 offset:21504
	ds_read_b128 v[218:221], v164 offset:22528
	ds_read_b128 v[222:225], v164 offset:23552
	global_load_lds_dwordx4 v[226:227], off
	s_add_i32 m0, s71, 0x2000
	s_add_u32 s72, s40, 0x40000
	v_lshl_add_u64 v[228:229], s[40:41], 0, v[142:143]
	s_addc_u32 s73, s41, 0
	s_add_i32 s71, s62, s33
	global_load_lds_dwordx4 v[228:229], off
	v_lshl_add_u64 v[230:231], s[72:73], 0, v[138:139]
	s_mov_b32 m0, s71
	v_lshl_add_u64 v[232:233], s[42:43], 0, v[140:141]
	global_load_lds_dwordx4 v[230:231], off
	v_lshl_add_u64 v[230:231], s[72:73], 0, v[142:143]
	s_add_i32 m0, s71, 0x2000
	s_nop 0
	global_load_lds_dwordx4 v[230:231], off
	v_lshl_add_u64 v[230:231], s[42:43], 0, v[136:137]
	s_mov_b32 m0, s52
	s_nop 0
	global_load_lds_dwordx4 v[230:231], off
	s_mov_b32 m0, s53
	s_nop 0
	global_load_lds_dwordx4 v[232:233], off
	s_waitcnt vmcnt(8)
	s_waitcnt lgkmcnt(0)
	s_barrier
	s_setprio 1
	s_waitcnt lgkmcnt(0)
	v_mfma_f32_16x16x32_bf16 v[60:63], v[148:151], v[194:197], 0
	v_mfma_f32_16x16x32_bf16 v[56:59], v[170:173], v[194:197], 0
	v_mfma_f32_16x16x32_bf16 v[44:47], v[148:151], v[202:205], 0
	v_mfma_f32_16x16x32_bf16 v[40:43], v[170:173], v[202:205], 0
	v_mfma_f32_16x16x32_bf16 v[28:31], v[148:151], v[210:213], 0
	v_mfma_f32_16x16x32_bf16 v[24:27], v[170:173], v[210:213], 0
	v_mfma_f32_16x16x32_bf16 v[12:15], v[148:151], v[218:221], 0
	v_mfma_f32_16x16x32_bf16 v[8:11], v[170:173], v[218:221], 0
	v_mfma_f32_16x16x32_bf16 v[60:63], v[166:169], v[198:201], v[60:63]
	v_mfma_f32_16x16x32_bf16 v[56:59], v[174:177], v[198:201], v[56:59]
	v_mfma_f32_16x16x32_bf16 v[44:47], v[166:169], v[206:209], v[44:47]
	v_mfma_f32_16x16x32_bf16 v[40:43], v[174:177], v[206:209], v[40:43]
	v_mfma_f32_16x16x32_bf16 v[28:31], v[166:169], v[214:217], v[28:31]
	v_mfma_f32_16x16x32_bf16 v[24:27], v[174:177], v[214:217], v[24:27]
	v_mfma_f32_16x16x32_bf16 v[12:15], v[166:169], v[222:225], v[12:15]
	v_mfma_f32_16x16x32_bf16 v[8:11], v[174:177], v[222:225], v[8:11]
	s_setprio 0
	s_setprio 1
	v_mfma_f32_16x16x32_bf16 v[52:55], v[178:181], v[194:197], 0
	v_mfma_f32_16x16x32_bf16 v[48:51], v[186:189], v[194:197], 0
	v_mfma_f32_16x16x32_bf16 v[36:39], v[178:181], v[202:205], 0
	v_mfma_f32_16x16x32_bf16 v[32:35], v[186:189], v[202:205], 0
	v_mfma_f32_16x16x32_bf16 v[20:23], v[178:181], v[210:213], 0
	v_mfma_f32_16x16x32_bf16 v[16:19], v[186:189], v[210:213], 0
	v_mfma_f32_16x16x32_bf16 v[4:7], v[178:181], v[218:221], 0
	v_mfma_f32_16x16x32_bf16 v[0:3], v[186:189], v[218:221], 0
	v_mfma_f32_16x16x32_bf16 v[52:55], v[182:185], v[198:201], v[52:55]
	v_mfma_f32_16x16x32_bf16 v[48:51], v[190:193], v[198:201], v[48:51]
	v_mfma_f32_16x16x32_bf16 v[36:39], v[182:185], v[206:209], v[36:39]
	v_mfma_f32_16x16x32_bf16 v[32:35], v[190:193], v[206:209], v[32:35]
	v_mfma_f32_16x16x32_bf16 v[20:23], v[182:185], v[214:217], v[20:23]
	v_mfma_f32_16x16x32_bf16 v[16:19], v[190:193], v[214:217], v[16:19]
	v_mfma_f32_16x16x32_bf16 v[4:7], v[182:185], v[222:225], v[4:7]
	v_mfma_f32_16x16x32_bf16 v[0:3], v[190:193], v[222:225], v[0:3]
	s_setprio 0
	s_barrier
	s_add_i32 s71, 0, 0x18000
	v_add_u32_e32 v130, s71, v160
	s_add_i32 s72, 0, 0x1c000
	ds_read_b128 v[148:151], v130
	ds_read_b128 v[166:169], v130 offset:1024
	ds_read_b128 v[170:173], v130 offset:2048
	ds_read_b128 v[174:177], v130 offset:3072
	v_add_u32_e32 v130, s72, v160
	ds_read_b128 v[178:181], v130
	ds_read_b128 v[182:185], v130 offset:1024
	ds_read_b128 v[186:189], v130 offset:2048
	ds_read_b128 v[190:193], v130 offset:3072
	s_add_u32 s42, s42, 0x40000
	s_addc_u32 s43, s43, 0
	s_mov_b32 m0, s54
	v_lshl_add_u64 v[234:235], s[42:43], 0, v[136:137]
	ds_read_b128 v[194:197], v164 offset:32768
	ds_read_b128 v[198:201], v164 offset:33792
	ds_read_b128 v[202:205], v164 offset:34816
	ds_read_b128 v[206:209], v164 offset:35840
	ds_read_b128 v[210:213], v164 offset:36864
	ds_read_b128 v[214:217], v164 offset:37888
	ds_read_b128 v[218:221], v164 offset:38912
	ds_read_b128 v[222:225], v164 offset:39936
	global_load_lds_dwordx4 v[234:235], off
	v_lshl_add_u64 v[234:235], s[42:43], 0, v[140:141]
	s_mov_b32 m0, s55
	s_nop 0
	global_load_lds_dwordx4 v[234:235], off
	s_waitcnt vmcnt(8)
	s_waitcnt lgkmcnt(0)
	s_barrier
; #define PG8_STAGE(bufoff, gbase, voff) do { _Pragma("unroll") for (int _i = 0; _i < 2; ++_i) \
;         __builtin_amdgcn_global_load_lds((const unsigned*)((const char*)(gbase) + (voff)[_i]), (PG8_LAS unsigned*)(lds + (bufoff) + ldsw + _i * 8192), 16, 0, 0); } while (0)
; #define PG8_LDA(dst, b, h) do { _Pragma("unroll") for (int m = 0; m < 4; ++m) _Pragma("unroll") for (int k = 0; k < 2; ++k) dst[m][k] = *(const PG8_LAS bf16x8*)(lds + PG8_SA(b, h) + aoff + m * 2048 + k * 1024); } while (0)
; #define PG8_LDB(dst, b, h) do { _Pragma("unroll") for (int n = 0; n < 2; ++n) _Pragma("unroll") for (int k = 0; k < 2; ++k) dst[n][k] = *(const PG8_LAS bf16x8*)(lds + PG8_SB(b, h) + boff + n * 2048 + k * 1024); } while (0)
; #define PG8_MMA(ai, bj, At, Bt) do { __builtin_amdgcn_s_setprio(1); _Pragma("unroll") for (int m = 0; m < 4; ++m) _Pragma("unroll") for (int n = 0; n < 2; ++n) _Pragma("unroll") for (int k = 0; k < 2; ++k) \
;         acc[ai][bj][m][n] = __builtin_amdgcn_mfma_f32_16x16x32_bf16(Bt[n][k], At[m][k], acc[ai][bj][m][n], 0, 0, 0); __builtin_amdgcn_s_setprio(0); } while (0)
; #define PG8_WAIT_V(n) asm volatile("s_waitcnt vmcnt(" #n ")" ::: "memory")
; #define PG8_WAIT_L(n) asm volatile("s_waitcnt lgkmcnt(" #n ")" ::: "memory")
; #define PG8_BAR __builtin_amdgcn_s_barrier()
; #define PG8_SCHED __builtin_amdgcn_sched_barrier(0)
; template <class Epi, class Sched, bool ALIGN_EPI = false, bool SP2 = false>
; __device__ __forceinline__ void gemm_phase(PG8_LAS unsigned char* lds, const Gemm g, const Sched& S, const Epi& E) {
;     ...
;             PG8_LDB(B0, 1, 0); PG8_LDB(B1, 1, 1); PG8_SCHED; PG8_LDA(At, 1, 0); PG8_STAGE(PG8_SA(0, 1), a2 + hstep, voffA);
;             PG8_WAIT_V(8); PG8_WAIT_L(0); PG8_BAR; PG8_MMA(0, 0, At, B0); PG8_MMA(0, 1, At, B1); PG8_BAR; PG8_SCHED;
;             PG8_LDA(At, 1, 1); PG8_STAGE(PG8_SB(1, 0), b3, voffB); PG8_STAGE(PG8_SB(1, 1), b3 + hstep, voffB); PG8_STAGE(PG8_SA(1, 0), a3, voffA);
;             PG8_WAIT_V(8); PG8_WAIT_L(0); PG8_BAR; PG8_MMA(1, 0, At, B0); PG8_MMA(1, 1, At, B1); PG8_BAR; PG8_SCHED;
	s_setprio 1
	s_waitcnt lgkmcnt(0)
	v_mfma_f32_16x16x32_bf16 v[124:127], v[148:151], v[194:197], v[124:127]
	v_mfma_f32_16x16x32_bf16 v[120:123], v[170:173], v[194:197], v[120:123]
	v_mfma_f32_16x16x32_bf16 v[108:111], v[148:151], v[202:205], v[108:111]
	v_mfma_f32_16x16x32_bf16 v[104:107], v[170:173], v[202:205], v[104:107]
	v_mfma_f32_16x16x32_bf16 v[92:95], v[148:151], v[210:213], v[92:95]
	v_mfma_f32_16x16x32_bf16 v[88:91], v[170:173], v[210:213], v[88:91]
	v_mfma_f32_16x16x32_bf16 v[76:79], v[148:151], v[218:221], v[76:79]
	v_mfma_f32_16x16x32_bf16 v[72:75], v[170:173], v[218:221], v[72:75]
	v_mfma_f32_16x16x32_bf16 v[124:127], v[166:169], v[198:201], v[124:127]
	v_mfma_f32_16x16x32_bf16 v[120:123], v[174:177], v[198:201], v[120:123]
	v_mfma_f32_16x16x32_bf16 v[108:111], v[166:169], v[206:209], v[108:111]
	v_mfma_f32_16x16x32_bf16 v[104:107], v[174:177], v[206:209], v[104:107]
	v_mfma_f32_16x16x32_bf16 v[92:95], v[166:169], v[214:217], v[92:95]
	v_mfma_f32_16x16x32_bf16 v[88:91], v[174:177], v[214:217], v[88:91]
	v_mfma_f32_16x16x32_bf16 v[76:79], v[166:169], v[222:225], v[76:79]
	v_mfma_f32_16x16x32_bf16 v[72:75], v[174:177], v[222:225], v[72:75]
	s_setprio 0
	s_setprio 1
	v_mfma_f32_16x16x32_bf16 v[116:119], v[178:181], v[194:197], v[116:119]
	v_mfma_f32_16x16x32_bf16 v[112:115], v[186:189], v[194:197], v[112:115]
	v_mfma_f32_16x16x32_bf16 v[100:103], v[178:181], v[202:205], v[100:103]
	v_mfma_f32_16x16x32_bf16 v[96:99], v[186:189], v[202:205], v[96:99]
	v_mfma_f32_16x16x32_bf16 v[84:87], v[178:181], v[210:213], v[84:87]
	v_mfma_f32_16x16x32_bf16 v[80:83], v[186:189], v[210:213], v[80:83]
	v_mfma_f32_16x16x32_bf16 v[68:71], v[178:181], v[218:221], v[68:71]
	v_mfma_f32_16x16x32_bf16 v[64:67], v[186:189], v[218:221], v[64:67]
	v_mfma_f32_16x16x32_bf16 v[116:119], v[182:185], v[198:201], v[116:119]
	v_mfma_f32_16x16x32_bf16 v[112:115], v[190:193], v[198:201], v[112:115]
	v_mfma_f32_16x16x32_bf16 v[100:103], v[182:185], v[206:209], v[100:103]
	v_mfma_f32_16x16x32_bf16 v[96:99], v[190:193], v[206:209], v[96:99]
	v_mfma_f32_16x16x32_bf16 v[84:87], v[182:185], v[214:217], v[84:87]
	v_mfma_f32_16x16x32_bf16 v[80:83], v[190:193], v[214:217], v[80:83]
	v_mfma_f32_16x16x32_bf16 v[68:71], v[182:185], v[222:225], v[68:71]
	v_mfma_f32_16x16x32_bf16 v[64:67], v[190:193], v[222:225], v[64:67]
	s_setprio 0
	s_barrier
	s_add_i32 s42, s71, s33
	v_lshl_add_u64 v[226:227], v[226:227], 0, s[24:25]
	s_mov_b32 m0, s42
	ds_read_b128 v[194:197], v164 offset:49152
	ds_read_b128 v[198:201], v164 offset:50176
	ds_read_b128 v[202:205], v164 offset:51200
	ds_read_b128 v[206:209], v164 offset:52224
	ds_read_b128 v[210:213], v164 offset:53248
	ds_read_b128 v[214:217], v164 offset:54272
	ds_read_b128 v[218:221], v164 offset:55296
	ds_read_b128 v[222:225], v164 offset:56320
	global_load_lds_dwordx4 v[226:227], off
	s_add_i32 m0, s42, 0x2000
	s_add_u32 s40, s40, 0x40080
	v_lshl_add_u64 v[226:227], v[228:229], 0, s[24:25]
	s_addc_u32 s41, s41, 0
	s_add_i32 s42, s72, s33
	global_load_lds_dwordx4 v[226:227], off
	v_lshl_add_u64 v[226:227], s[40:41], 0, v[138:139]
	s_mov_b32 m0, s42
	s_nop 0
	global_load_lds_dwordx4 v[226:227], off
	v_lshl_add_u64 v[226:227], s[40:41], 0, v[142:143]
	s_add_i32 m0, s42, 0x2000
	s_nop 0
	global_load_lds_dwordx4 v[226:227], off
	v_lshl_add_u64 v[226:227], v[230:231], 0, s[24:25]
	s_mov_b32 m0, s57
	s_nop 0
	global_load_lds_dwordx4 v[226:227], off
	v_lshl_add_u64 v[226:227], v[232:233], 0, s[24:25]
	s_mov_b32 m0, s58
	s_nop 0
	global_load_lds_dwordx4 v[226:227], off
	s_waitcnt vmcnt(8)
	s_waitcnt lgkmcnt(0)
	s_barrier
	s_setprio 1
	s_waitcnt lgkmcnt(0)
	v_mfma_f32_16x16x32_bf16 v[60:63], v[148:151], v[194:197], v[60:63]
	v_mfma_f32_16x16x32_bf16 v[56:59], v[170:173], v[194:197], v[56:59]
	v_mfma_f32_16x16x32_bf16 v[44:47], v[148:151], v[202:205], v[44:47]
	v_mfma_f32_16x16x32_bf16 v[40:43], v[170:173], v[202:205], v[40:43]
	v_mfma_f32_16x16x32_bf16 v[28:31], v[148:151], v[210:213], v[28:31]
	v_mfma_f32_16x16x32_bf16 v[24:27], v[170:173], v[210:213], v[24:27]
	v_mfma_f32_16x16x32_bf16 v[12:15], v[148:151], v[218:221], v[12:15]
	v_mfma_f32_16x16x32_bf16 v[8:11], v[170:173], v[218:221], v[8:11]
	v_mfma_f32_16x16x32_bf16 v[60:63], v[166:169], v[198:201], v[60:63]
	v_mfma_f32_16x16x32_bf16 v[56:59], v[174:177], v[198:201], v[56:59]
	v_mfma_f32_16x16x32_bf16 v[44:47], v[166:169], v[206:209], v[44:47]
	v_mfma_f32_16x16x32_bf16 v[40:43], v[174:177], v[206:209], v[40:43]
	v_mfma_f32_16x16x32_bf16 v[28:31], v[166:169], v[214:217], v[28:31]
	v_mfma_f32_16x16x32_bf16 v[24:27], v[174:177], v[214:217], v[24:27]
	v_mfma_f32_16x16x32_bf16 v[12:15], v[166:169], v[222:225], v[12:15]
	v_mfma_f32_16x16x32_bf16 v[8:11], v[174:177], v[222:225], v[8:11]
	s_setprio 0
	s_setprio 1
	v_mfma_f32_16x16x32_bf16 v[52:55], v[178:181], v[194:197], v[52:55]
	v_mfma_f32_16x16x32_bf16 v[48:51], v[186:189], v[194:197], v[48:51]
	v_mfma_f32_16x16x32_bf16 v[36:39], v[178:181], v[202:205], v[36:39]
	v_mfma_f32_16x16x32_bf16 v[32:35], v[186:189], v[202:205], v[32:35]
	v_mfma_f32_16x16x32_bf16 v[20:23], v[178:181], v[210:213], v[20:23]
	v_mfma_f32_16x16x32_bf16 v[16:19], v[186:189], v[210:213], v[16:19]
	v_mfma_f32_16x16x32_bf16 v[4:7], v[178:181], v[218:221], v[4:7]
	v_mfma_f32_16x16x32_bf16 v[0:3], v[186:189], v[218:221], v[0:3]
	v_mfma_f32_16x16x32_bf16 v[52:55], v[182:185], v[198:201], v[52:55]
	v_mfma_f32_16x16x32_bf16 v[48:51], v[190:193], v[198:201], v[48:51]
	v_mfma_f32_16x16x32_bf16 v[36:39], v[182:185], v[206:209], v[36:39]
	v_mfma_f32_16x16x32_bf16 v[32:35], v[190:193], v[206:209], v[32:35]
	v_mfma_f32_16x16x32_bf16 v[20:23], v[182:185], v[214:217], v[20:23]
	v_mfma_f32_16x16x32_bf16 v[16:19], v[190:193], v[214:217], v[16:19]
	v_mfma_f32_16x16x32_bf16 v[4:7], v[182:185], v[222:225], v[4:7]
	v_mfma_f32_16x16x32_bf16 v[0:3], v[190:193], v[222:225], v[0:3]
	s_setprio 0
	s_barrier
	s_add_i32 s70, s70, 2
	s_add_u32 s38, s38, 0x100
	s_addc_u32 s39, s39, 0
	s_add_u32 s44, s44, 0x100
	s_addc_u32 s45, s45, 0
	s_cmp_gt_u32 s70, 13

; #define PG8_STAGE(bufoff, gbase, voff) do { _Pragma("unroll") for (int _i = 0; _i < 2; ++_i) \
;         __builtin_amdgcn_global_load_lds((const unsigned*)((const char*)(gbase) + (voff)[_i]), (PG8_LAS unsigned*)(lds + (bufoff) + ldsw + _i * 8192), 16, 0, 0); } while (0)
; #define PG8_LDA(dst, b, h) do { _Pragma("unroll") for (int m = 0; m < 4; ++m) _Pragma("unroll") for (int k = 0; k < 2; ++k) dst[m][k] = *(const PG8_LAS bf16x8*)(lds + PG8_SA(b, h) + aoff + m * 2048 + k * 1024); } while (0)
; #define PG8_LDB(dst, b, h) do { _Pragma("unroll") for (int n = 0; n < 2; ++n) _Pragma("unroll") for (int k = 0; k < 2; ++k) dst[n][k] = *(const PG8_LAS bf16x8*)(lds + PG8_SB(b, h) + boff + n * 2048 + k * 1024); } while (0)
; #define PG8_SCHED __builtin_amdgcn_sched_barrier(0)
; template <class Epi, class Sched, bool ALIGN_EPI = false, bool SP2 = false>
; __device__ __forceinline__ void gemm_phase(PG8_LAS unsigned char* lds, const Gemm g, const Sched& S, const Epi& E) {
;     ...
;         const bool has_next = S.next(ui + 1, nxt);
;         const char* nA = has_next ? (const char*)g.A + (size_t)nxt.pm * tstep : cA; const char* nB = has_next ? (const char*)g.Bt + (size_t)nxt.pn * tstep : cB;
;         for (int t = 0; t < nt; t += 2) {
;             const bool last = (t == nt - 2);
;             const char* a1 = cA + (size_t)(t + 1) * kstep;
;             const char* a2 = last ? nA : cA + (size_t)(t + 2) * kstep; const char* b2 = last ? nB : cB + (size_t)(t + 2) * kstep;
;             const char* a3 = a2 + kstep; const char* b3 = b2 + kstep;
;             if (last && has_next) S.a_ready(nxt, ui + 1);
;             if constexpr (SP2) {
;             PG8_LDB(B0, 0, 0); PG8_LDB(B1, 0, 1); PG8_SCHED; PG8_LDA(At, 0, 0); PG8_STAGE(PG8_SA(1, 1), a1 + hstep, voffA);
.LBB0_600:
	ds_read_b128 v[128:131], v170
	ds_read_b128 v[132:135], v170 offset:1024
	ds_read_b128 v[174:177], v170 offset:2048
	ds_read_b128 v[178:181], v170 offset:3072
	ds_read_b128 v[182:185], v171
	ds_read_b128 v[186:189], v171 offset:1024
	ds_read_b128 v[190:193], v171 offset:2048
	ds_read_b128 v[194:197], v171 offset:3072
	ds_read_b128 v[198:201], v172
	ds_read_b128 v[202:205], v172 offset:1024
	ds_read_b128 v[206:209], v172 offset:2048
	ds_read_b128 v[210:213], v172 offset:3072
	ds_read_b128 v[214:217], v172 offset:4096
	ds_read_b128 v[218:221], v172 offset:5120
	ds_read_b128 v[222:225], v172 offset:6144
	ds_read_b128 v[226:229], v172 offset:7168
	s_add_i32 s53, s27, 1
	s_mul_i32 s4, s53, s46
	s_mul_hi_u32 s5, s53, s47
	s_add_i32 s5, s5, s4
	s_mul_i32 s4, s53, s47
	s_add_u32 s22, s4, s2
	s_addc_u32 s23, s5, s3
	v_cmp_gt_i64_e32 vcc, s[22:23], v[158:159]
	v_cmp_lt_i64_e64 s[4:5], s[22:23], v[156:157]
	s_cbranch_vccnz .LBB0_606
	s_ashr_i32 s18, s22, 31
	s_lshr_b32 s18, s18, 29
	s_add_i32 s20, s22, s18
	s_and_b32 s18, s20, -8
	s_sub_i32 s21, s22, s18
	s_cmp_gt_i32 s21, -1
	s_mov_b64 s[18:19], -1
	s_cbranch_scc0 .LBB0_603
	s_lshl_b32 s22, s21, 6
	s_mov_b64 s[18:19], 0

; #define PG8_STAGE(bufoff, gbase, voff) do { _Pragma("unroll") for (int _i = 0; _i < 2; ++_i) \
;         __builtin_amdgcn_global_load_lds((const unsigned*)((const char*)(gbase) + (voff)[_i]), (PG8_LAS unsigned*)(lds + (bufoff) + ldsw + _i * 8192), 16, 0, 0); } while (0)
; #define PG8_LDA(dst, b, h) do { _Pragma("unroll") for (int m = 0; m < 4; ++m) _Pragma("unroll") for (int k = 0; k < 2; ++k) dst[m][k] = *(const PG8_LAS bf16x8*)(lds + PG8_SA(b, h) + aoff + m * 2048 + k * 1024); } while (0)
; #define PG8_LDB(dst, b, h) do { _Pragma("unroll") for (int n = 0; n < 2; ++n) _Pragma("unroll") for (int k = 0; k < 2; ++k) dst[n][k] = *(const PG8_LAS bf16x8*)(lds + PG8_SB(b, h) + boff + n * 2048 + k * 1024); } while (0)
; #define PG8_WAIT_V(n) asm volatile("s_waitcnt vmcnt(" #n ")" ::: "memory")
; #define PG8_WAIT_L(n) asm volatile("s_waitcnt lgkmcnt(" #n ")" ::: "memory")
; #define PG8_BAR __builtin_amdgcn_s_barrier()
; #define PG8_SCHED __builtin_amdgcn_sched_barrier(0)
; template <class Epi, class Sched, bool ALIGN_EPI = false, bool SP2 = false>
; __device__ __forceinline__ void gemm_phase(PG8_LAS unsigned char* lds, const Gemm g, const Sched& S, const Epi& E) {
;     ...
;         const char* nA = has_next ? (const char*)g.A + (size_t)nxt.pm * tstep : cA; const char* nB = has_next ? (const char*)g.Bt + (size_t)nxt.pn * tstep : cB;
;         for (int t = 0; t < nt; t += 2) {
;             const bool last = (t == nt - 2);
;             const char* a1 = cA + (size_t)(t + 1) * kstep;
;             const char* a2 = last ? nA : cA + (size_t)(t + 2) * kstep; const char* b2 = last ? nB : cB + (size_t)(t + 2) * kstep;
;             const char* a3 = a2 + kstep; const char* b3 = b2 + kstep;
;             if (last && has_next) S.a_ready(nxt, ui + 1);
;             if constexpr (SP2) {
;             PG8_LDB(B0, 0, 0); PG8_LDB(B1, 0, 1); PG8_SCHED; PG8_LDA(At, 0, 0); PG8_STAGE(PG8_SA(1, 1), a1 + hstep, voffA);
;             PG8_WAIT_V(8); PG8_WAIT_L(0); PG8_BAR; PG8_MMA(0, 0, At, B0); PG8_MMA(0, 1, At, B1); PG8_BAR; PG8_SCHED;
;             PG8_LDA(At, 0, 1); PG8_STAGE(PG8_SB(0, 0), b2, voffB); PG8_STAGE(PG8_SB(0, 1), b2 + hstep, voffB); PG8_STAGE(PG8_SA(0, 0), a2, voffA);
;             PG8_WAIT_V(8); PG8_WAIT_L(0); PG8_BAR; PG8_MMA(1, 0, At, B0); PG8_MMA(1, 1, At, B1); PG8_BAR; PG8_SCHED;
.LBB0_606:
	s_ashr_i32 s21, s20, 31
	s_lshl_b64 s[22:23], s[20:21], 19
	s_add_u32 s22, s36, s22
	s_addc_u32 s23, s37, s23
	s_and_b64 s[24:25], s[4:5], exec
	s_cselect_b32 s21, s23, s29
	s_cselect_b32 s55, s22, s28
	s_ashr_i32 s19, s18, 31
	s_lshl_b64 s[24:25], s[18:19], 19
	s_add_u32 s24, s48, s24
	s_addc_u32 s25, s49, s25
	s_and_b64 s[34:35], s[4:5], exec
	s_cselect_b32 s19, s25, s31
	s_cselect_b32 s56, s24, s30
	s_add_u32 s28, s28, 0x40080
	s_addc_u32 s29, s29, 0
	s_add_u32 s57, s30, 0x100
	s_addc_u32 s58, s31, 0
	s_mov_b32 s59, -2
	s_add_u32 s30, s28, 0xfffc0080
	s_addc_u32 s31, s29, -1
	s_cmp_eq_u32 s59, 12
	s_cselect_b32 s35, s21, s31
	s_cselect_b32 s34, s55, s30
	s_cselect_b32 s31, s19, s58
	s_cselect_b32 s30, s56, s57
	v_lshl_add_u64 v[160:161], s[28:29], 0, v[152:153]
	s_add_i32 m0, s38, 0xc000
	global_load_lds_dwordx4 v[160:161], off
	v_lshl_add_u64 v[160:161], s[28:29], 0, v[154:155]
	s_add_i32 m0, s38, 0xe000
	s_nop 0
	global_load_lds_dwordx4 v[160:161], off
	s_waitcnt vmcnt(8)
	s_waitcnt lgkmcnt(0)
	s_barrier
	s_setprio 1
	s_waitcnt lgkmcnt(0)
	v_mfma_f32_16x16x32_bf16 v[124:127], v[128:131], v[198:201], 0
	v_mfma_f32_16x16x32_bf16 v[120:123], v[174:177], v[198:201], 0
	v_mfma_f32_16x16x32_bf16 v[116:119], v[128:131], v[206:209], 0
	v_mfma_f32_16x16x32_bf16 v[112:115], v[174:177], v[206:209], 0
	v_mfma_f32_16x16x32_bf16 v[108:111], v[128:131], v[214:217], 0
	v_mfma_f32_16x16x32_bf16 v[104:107], v[174:177], v[214:217], 0
	v_mfma_f32_16x16x32_bf16 v[100:103], v[128:131], v[222:225], 0
	v_mfma_f32_16x16x32_bf16 v[96:99], v[174:177], v[222:225], 0
	v_mfma_f32_16x16x32_bf16 v[124:127], v[132:135], v[202:205], v[124:127]
	v_mfma_f32_16x16x32_bf16 v[120:123], v[178:181], v[202:205], v[120:123]
	v_mfma_f32_16x16x32_bf16 v[116:119], v[132:135], v[210:213], v[116:119]
	v_mfma_f32_16x16x32_bf16 v[112:115], v[178:181], v[210:213], v[112:115]
	v_mfma_f32_16x16x32_bf16 v[108:111], v[132:135], v[218:221], v[108:111]
	v_mfma_f32_16x16x32_bf16 v[104:107], v[178:181], v[218:221], v[104:107]
	v_mfma_f32_16x16x32_bf16 v[100:103], v[132:135], v[226:229], v[100:103]
	v_mfma_f32_16x16x32_bf16 v[96:99], v[178:181], v[226:229], v[96:99]
	s_setprio 0
	s_setprio 1
	v_mfma_f32_16x16x32_bf16 v[60:63], v[182:185], v[198:201], 0
	v_mfma_f32_16x16x32_bf16 v[56:59], v[190:193], v[198:201], 0
	v_mfma_f32_16x16x32_bf16 v[52:55], v[182:185], v[206:209], 0
	v_mfma_f32_16x16x32_bf16 v[48:51], v[190:193], v[206:209], 0
	v_mfma_f32_16x16x32_bf16 v[44:47], v[182:185], v[214:217], 0
	v_mfma_f32_16x16x32_bf16 v[40:43], v[190:193], v[214:217], 0
	v_mfma_f32_16x16x32_bf16 v[36:39], v[182:185], v[222:225], 0
	v_mfma_f32_16x16x32_bf16 v[32:35], v[190:193], v[222:225], 0
	v_mfma_f32_16x16x32_bf16 v[60:63], v[186:189], v[202:205], v[60:63]
	v_mfma_f32_16x16x32_bf16 v[56:59], v[194:197], v[202:205], v[56:59]
	v_mfma_f32_16x16x32_bf16 v[52:55], v[186:189], v[210:213], v[52:55]
	v_mfma_f32_16x16x32_bf16 v[48:51], v[194:197], v[210:213], v[48:51]
	v_mfma_f32_16x16x32_bf16 v[44:47], v[186:189], v[218:221], v[44:47]
	v_mfma_f32_16x16x32_bf16 v[40:43], v[194:197], v[218:221], v[40:43]
	v_mfma_f32_16x16x32_bf16 v[36:39], v[186:189], v[226:229], v[36:39]
	v_mfma_f32_16x16x32_bf16 v[32:35], v[194:197], v[226:229], v[32:35]
	s_setprio 0
	s_barrier
	s_add_i32 s60, s45, s33
	v_lshl_add_u64 v[160:161], s[30:31], 0, v[138:139]
	s_mov_b32 m0, s60
	ds_read_b128 v[198:201], v172 offset:16384
	ds_read_b128 v[202:205], v172 offset:17408
	ds_read_b128 v[206:209], v172 offset:18432
	ds_read_b128 v[210:213], v172 offset:19456
	ds_read_b128 v[214:217], v172 offset:20480
	ds_read_b128 v[218:221], v172 offset:21504
	ds_read_b128 v[222:225], v172 offset:22528
	ds_read_b128 v[226:229], v172 offset:23552
	global_load_lds_dwordx4 v[160:161], off
	s_add_i32 m0, s60, 0x2000
	s_add_u32 s60, s30, 0x40000
	v_lshl_add_u64 v[230:231], s[30:31], 0, v[142:143]
	s_addc_u32 s61, s31, 0
	s_add_i32 s62, s50, s33
	global_load_lds_dwordx4 v[230:231], off
	v_lshl_add_u64 v[232:233], s[60:61], 0, v[138:139]
	s_mov_b32 m0, s62
	v_lshl_add_u64 v[234:235], s[34:35], 0, v[140:141]
	global_load_lds_dwordx4 v[232:233], off
	v_lshl_add_u64 v[232:233], s[60:61], 0, v[142:143]
	s_add_i32 m0, s62, 0x2000
	s_nop 0
	global_load_lds_dwordx4 v[232:233], off
	v_lshl_add_u64 v[232:233], s[34:35], 0, v[136:137]
	s_mov_b32 m0, s38
	s_nop 0
	global_load_lds_dwordx4 v[232:233], off
	s_mov_b32 m0, s39
	s_nop 0
	global_load_lds_dwordx4 v[234:235], off
	s_waitcnt vmcnt(8)
	s_waitcnt lgkmcnt(0)
	s_barrier
	s_setprio 1
	s_waitcnt lgkmcnt(0)
	v_mfma_f32_16x16x32_bf16 v[92:95], v[128:131], v[198:201], 0
	v_mfma_f32_16x16x32_bf16 v[88:91], v[174:177], v[198:201], 0
	v_mfma_f32_16x16x32_bf16 v[84:87], v[128:131], v[206:209], 0
	v_mfma_f32_16x16x32_bf16 v[80:83], v[174:177], v[206:209], 0
	v_mfma_f32_16x16x32_bf16 v[76:79], v[128:131], v[214:217], 0
	v_mfma_f32_16x16x32_bf16 v[72:75], v[174:177], v[214:217], 0
	v_mfma_f32_16x16x32_bf16 v[68:71], v[128:131], v[222:225], 0
	v_mfma_f32_16x16x32_bf16 v[64:67], v[174:177], v[222:225], 0
	v_mfma_f32_16x16x32_bf16 v[92:95], v[132:135], v[202:205], v[92:95]
	v_mfma_f32_16x16x32_bf16 v[88:91], v[178:181], v[202:205], v[88:91]
	v_mfma_f32_16x16x32_bf16 v[84:87], v[132:135], v[210:213], v[84:87]
	v_mfma_f32_16x16x32_bf16 v[80:83], v[178:181], v[210:213], v[80:83]
	v_mfma_f32_16x16x32_bf16 v[76:79], v[132:135], v[218:221], v[76:79]
	v_mfma_f32_16x16x32_bf16 v[72:75], v[178:181], v[218:221], v[72:75]
	v_mfma_f32_16x16x32_bf16 v[68:71], v[132:135], v[226:229], v[68:71]
	v_mfma_f32_16x16x32_bf16 v[64:67], v[178:181], v[226:229], v[64:67]
	s_setprio 0
	s_setprio 1
	v_mfma_f32_16x16x32_bf16 v[28:31], v[182:185], v[198:201], 0
	v_mfma_f32_16x16x32_bf16 v[24:27], v[190:193], v[198:201], 0
	v_mfma_f32_16x16x32_bf16 v[20:23], v[182:185], v[206:209], 0
	v_mfma_f32_16x16x32_bf16 v[16:19], v[190:193], v[206:209], 0
	v_mfma_f32_16x16x32_bf16 v[12:15], v[182:185], v[214:217], 0
	v_mfma_f32_16x16x32_bf16 v[8:11], v[190:193], v[214:217], 0
	v_mfma_f32_16x16x32_bf16 v[4:7], v[182:185], v[222:225], 0
	v_mfma_f32_16x16x32_bf16 v[0:3], v[190:193], v[222:225], 0
	v_mfma_f32_16x16x32_bf16 v[28:31], v[186:189], v[202:205], v[28:31]
	v_mfma_f32_16x16x32_bf16 v[24:27], v[194:197], v[202:205], v[24:27]
	v_mfma_f32_16x16x32_bf16 v[20:23], v[186:189], v[210:213], v[20:23]
	v_mfma_f32_16x16x32_bf16 v[16:19], v[194:197], v[210:213], v[16:19]
	v_mfma_f32_16x16x32_bf16 v[12:15], v[186:189], v[218:221], v[12:15]
	v_mfma_f32_16x16x32_bf16 v[8:11], v[194:197], v[218:221], v[8:11]
	v_mfma_f32_16x16x32_bf16 v[4:7], v[186:189], v[226:229], v[4:7]
	v_mfma_f32_16x16x32_bf16 v[0:3], v[194:197], v[226:229], v[0:3]
	s_setprio 0
	s_barrier
; #define PG8_STAGE(bufoff, gbase, voff) do { _Pragma("unroll") for (int _i = 0; _i < 2; ++_i) \
;         __builtin_amdgcn_global_load_lds((const unsigned*)((const char*)(gbase) + (voff)[_i]), (PG8_LAS unsigned*)(lds + (bufoff) + ldsw + _i * 8192), 16, 0, 0); } while (0)
; #define PG8_LDA(dst, b, h) do { _Pragma("unroll") for (int m = 0; m < 4; ++m) _Pragma("unroll") for (int k = 0; k < 2; ++k) dst[m][k] = *(const PG8_LAS bf16x8*)(lds + PG8_SA(b, h) + aoff + m * 2048 + k * 1024); } while (0)
; #define PG8_LDB(dst, b, h) do { _Pragma("unroll") for (int n = 0; n < 2; ++n) _Pragma("unroll") for (int k = 0; k < 2; ++k) dst[n][k] = *(const PG8_LAS bf16x8*)(lds + PG8_SB(b, h) + boff + n * 2048 + k * 1024); } while (0)
; #define PG8_MMA(ai, bj, At, Bt) do { __builtin_amdgcn_s_setprio(1); _Pragma("unroll") for (int m = 0; m < 4; ++m) _Pragma("unroll") for (int n = 0; n < 2; ++n) _Pragma("unroll") for (int k = 0; k < 2; ++k) \
;         acc[ai][bj][m][n] = __builtin_amdgcn_mfma_f32_16x16x32_bf16(Bt[n][k], At[m][k], acc[ai][bj][m][n], 0, 0, 0); __builtin_amdgcn_s_setprio(0); } while (0)
; #define PG8_WAIT_V(n) asm volatile("s_waitcnt vmcnt(" #n ")" ::: "memory")
; #define PG8_WAIT_L(n) asm volatile("s_waitcnt lgkmcnt(" #n ")" ::: "memory")
; #define PG8_BAR __builtin_amdgcn_s_barrier()
; #define PG8_SCHED __builtin_amdgcn_sched_barrier(0)
; template <class Epi, class Sched, bool ALIGN_EPI = false, bool SP2 = false>
; __device__ __forceinline__ void gemm_phase(PG8_LAS unsigned char* lds, const Gemm g, const Sched& S, const Epi& E) {
;     ...
;             PG8_LDB(B0, 1, 0); PG8_LDB(B1, 1, 1); PG8_SCHED; PG8_LDA(At, 1, 0); PG8_STAGE(PG8_SA(0, 1), a2 + hstep, voffA);
;             PG8_WAIT_V(8); PG8_WAIT_L(0); PG8_BAR; PG8_MMA(0, 0, At, B0); PG8_MMA(0, 1, At, B1); PG8_BAR; PG8_SCHED;
	s_add_i32 s60, 0, 0x18000
	s_add_i32 s61, 0, 0x1c000
	v_add_u32_e32 v178, s60, v163
	v_add_u32_e32 v194, s61, v163
	ds_read_b128 v[128:131], v178
	ds_read_b128 v[132:135], v178 offset:1024
	ds_read_b128 v[174:177], v178 offset:2048
	ds_read_b128 v[178:181], v178 offset:3072
	ds_read_b128 v[182:185], v194
	ds_read_b128 v[186:189], v194 offset:1024
	ds_read_b128 v[190:193], v194 offset:2048
	ds_read_b128 v[194:197], v194 offset:3072
	s_add_u32 s34, s34, 0x40000
	s_addc_u32 s35, s35, 0
	s_mov_b32 m0, s40
	v_lshl_add_u64 v[236:237], s[34:35], 0, v[136:137]
	ds_read_b128 v[198:201], v172 offset:32768
	ds_read_b128 v[202:205], v172 offset:33792
	ds_read_b128 v[206:209], v172 offset:34816
	ds_read_b128 v[210:213], v172 offset:35840
	ds_read_b128 v[214:217], v172 offset:36864
	ds_read_b128 v[218:221], v172 offset:37888
	ds_read_b128 v[222:225], v172 offset:38912
	ds_read_b128 v[226:229], v172 offset:39936
	global_load_lds_dwordx4 v[236:237], off
	v_lshl_add_u64 v[236:237], s[34:35], 0, v[140:141]
	s_mov_b32 m0, s41
	s_nop 0
	global_load_lds_dwordx4 v[236:237], off
	s_waitcnt vmcnt(8)
	s_waitcnt lgkmcnt(0)
	s_barrier
	s_setprio 1
	s_waitcnt lgkmcnt(0)
	v_mfma_f32_16x16x32_bf16 v[124:127], v[128:131], v[198:201], v[124:127]
	v_mfma_f32_16x16x32_bf16 v[120:123], v[174:177], v[198:201], v[120:123]
	v_mfma_f32_16x16x32_bf16 v[116:119], v[128:131], v[206:209], v[116:119]
	v_mfma_f32_16x16x32_bf16 v[112:115], v[174:177], v[206:209], v[112:115]
	v_mfma_f32_16x16x32_bf16 v[108:111], v[128:131], v[214:217], v[108:111]
	v_mfma_f32_16x16x32_bf16 v[104:107], v[174:177], v[214:217], v[104:107]
	v_mfma_f32_16x16x32_bf16 v[100:103], v[128:131], v[222:225], v[100:103]
	v_mfma_f32_16x16x32_bf16 v[96:99], v[174:177], v[222:225], v[96:99]
	v_mfma_f32_16x16x32_bf16 v[124:127], v[132:135], v[202:205], v[124:127]
	v_mfma_f32_16x16x32_bf16 v[120:123], v[178:181], v[202:205], v[120:123]
	v_mfma_f32_16x16x32_bf16 v[116:119], v[132:135], v[210:213], v[116:119]
	v_mfma_f32_16x16x32_bf16 v[112:115], v[178:181], v[210:213], v[112:115]
	v_mfma_f32_16x16x32_bf16 v[108:111], v[132:135], v[218:221], v[108:111]
	v_mfma_f32_16x16x32_bf16 v[104:107], v[178:181], v[218:221], v[104:107]
	v_mfma_f32_16x16x32_bf16 v[100:103], v[132:135], v[226:229], v[100:103]
	v_mfma_f32_16x16x32_bf16 v[96:99], v[178:181], v[226:229], v[96:99]
	s_setprio 0
	s_setprio 1
	v_mfma_f32_16x16x32_bf16 v[60:63], v[182:185], v[198:201], v[60:63]
	v_mfma_f32_16x16x32_bf16 v[56:59], v[190:193], v[198:201], v[56:59]
	v_mfma_f32_16x16x32_bf16 v[52:55], v[182:185], v[206:209], v[52:55]
	v_mfma_f32_16x16x32_bf16 v[48:51], v[190:193], v[206:209], v[48:51]
	v_mfma_f32_16x16x32_bf16 v[44:47], v[182:185], v[214:217], v[44:47]
	v_mfma_f32_16x16x32_bf16 v[40:43], v[190:193], v[214:217], v[40:43]
	v_mfma_f32_16x16x32_bf16 v[36:39], v[182:185], v[222:225], v[36:39]
	v_mfma_f32_16x16x32_bf16 v[32:35], v[190:193], v[222:225], v[32:35]
	v_mfma_f32_16x16x32_bf16 v[60:63], v[186:189], v[202:205], v[60:63]
	v_mfma_f32_16x16x32_bf16 v[56:59], v[194:197], v[202:205], v[56:59]
	v_mfma_f32_16x16x32_bf16 v[52:55], v[186:189], v[210:213], v[52:55]
	v_mfma_f32_16x16x32_bf16 v[48:51], v[194:197], v[210:213], v[48:51]
	v_mfma_f32_16x16x32_bf16 v[44:47], v[186:189], v[218:221], v[44:47]
	v_mfma_f32_16x16x32_bf16 v[40:43], v[194:197], v[218:221], v[40:43]
	v_mfma_f32_16x16x32_bf16 v[36:39], v[186:189], v[226:229], v[36:39]
	v_mfma_f32_16x16x32_bf16 v[32:35], v[194:197], v[226:229], v[32:35]
	s_setprio 0
	s_barrier
; #define PG8_STAGE(bufoff, gbase, voff) do { _Pragma("unroll") for (int _i = 0; _i < 2; ++_i) \
;         __builtin_amdgcn_global_load_lds((const unsigned*)((const char*)(gbase) + (voff)[_i]), (PG8_LAS unsigned*)(lds + (bufoff) + ldsw + _i * 8192), 16, 0, 0); } while (0)
; #define PG8_LDA(dst, b, h) do { _Pragma("unroll") for (int m = 0; m < 4; ++m) _Pragma("unroll") for (int k = 0; k < 2; ++k) dst[m][k] = *(const PG8_LAS bf16x8*)(lds + PG8_SA(b, h) + aoff + m * 2048 + k * 1024); } while (0)
; #define PG8_MMA(ai, bj, At, Bt) do { __builtin_amdgcn_s_setprio(1); _Pragma("unroll") for (int m = 0; m < 4; ++m) _Pragma("unroll") for (int n = 0; n < 2; ++n) _Pragma("unroll") for (int k = 0; k < 2; ++k) \
;         acc[ai][bj][m][n] = __builtin_amdgcn_mfma_f32_16x16x32_bf16(Bt[n][k], At[m][k], acc[ai][bj][m][n], 0, 0, 0); __builtin_amdgcn_s_setprio(0); } while (0)
; #define PG8_WAIT_V(n) asm volatile("s_waitcnt vmcnt(" #n ")" ::: "memory")
; #define PG8_WAIT_L(n) asm volatile("s_waitcnt lgkmcnt(" #n ")" ::: "memory")
; #define PG8_BAR __builtin_amdgcn_s_barrier()
; #define PG8_SCHED __builtin_amdgcn_sched_barrier(0)
; template <class Epi, class Sched, bool ALIGN_EPI = false, bool SP2 = false>
; __device__ __forceinline__ void gemm_phase(PG8_LAS unsigned char* lds, const Gemm g, const Sched& S, const Epi& E) {
;     ...
;             PG8_LDA(At, 1, 1); PG8_STAGE(PG8_SB(1, 0), b3, voffB); PG8_STAGE(PG8_SB(1, 1), b3 + hstep, voffB); PG8_STAGE(PG8_SA(1, 0), a3, voffA);
;             PG8_WAIT_V(8); PG8_WAIT_L(0); PG8_BAR; PG8_MMA(1, 0, At, B0); PG8_MMA(1, 1, At, B1); PG8_BAR; PG8_SCHED;
	s_add_i32 s34, s60, s33
	v_lshl_add_u64 v[160:161], v[160:161], 0, s[16:17]
	s_mov_b32 m0, s34
	ds_read_b128 v[198:201], v172 offset:49152
	ds_read_b128 v[202:205], v172 offset:50176
	ds_read_b128 v[206:209], v172 offset:51200
	ds_read_b128 v[210:213], v172 offset:52224
	ds_read_b128 v[214:217], v172 offset:53248
	ds_read_b128 v[218:221], v172 offset:54272
	ds_read_b128 v[222:225], v172 offset:55296
	ds_read_b128 v[226:229], v172 offset:56320
	global_load_lds_dwordx4 v[160:161], off
	s_add_i32 m0, s34, 0x2000
	s_add_u32 s30, s30, 0x40080
	v_lshl_add_u64 v[160:161], v[230:231], 0, s[16:17]
	s_addc_u32 s31, s31, 0
	s_add_i32 s34, s61, s33
	global_load_lds_dwordx4 v[160:161], off
	v_lshl_add_u64 v[160:161], s[30:31], 0, v[138:139]
	s_mov_b32 m0, s34
	s_nop 0
	global_load_lds_dwordx4 v[160:161], off
	v_lshl_add_u64 v[160:161], s[30:31], 0, v[142:143]
	s_add_i32 m0, s34, 0x2000
	s_nop 0
	global_load_lds_dwordx4 v[160:161], off
	v_lshl_add_u64 v[160:161], v[232:233], 0, s[16:17]
	s_mov_b32 m0, s42
	s_nop 0
	global_load_lds_dwordx4 v[160:161], off
	v_lshl_add_u64 v[160:161], v[234:235], 0, s[16:17]
	s_mov_b32 m0, s43
	s_nop 0
	global_load_lds_dwordx4 v[160:161], off
	s_waitcnt vmcnt(8)
	s_waitcnt lgkmcnt(0)
	s_barrier
	s_setprio 1
	s_waitcnt lgkmcnt(0)
	v_mfma_f32_16x16x32_bf16 v[92:95], v[128:131], v[198:201], v[92:95]
	v_mfma_f32_16x16x32_bf16 v[88:91], v[174:177], v[198:201], v[88:91]
	v_mfma_f32_16x16x32_bf16 v[84:87], v[128:131], v[206:209], v[84:87]
	v_mfma_f32_16x16x32_bf16 v[80:83], v[174:177], v[206:209], v[80:83]
	v_mfma_f32_16x16x32_bf16 v[76:79], v[128:131], v[214:217], v[76:79]
	v_mfma_f32_16x16x32_bf16 v[72:75], v[174:177], v[214:217], v[72:75]
	v_mfma_f32_16x16x32_bf16 v[68:71], v[128:131], v[222:225], v[68:71]
	v_mfma_f32_16x16x32_bf16 v[64:67], v[174:177], v[222:225], v[64:67]
	v_mfma_f32_16x16x32_bf16 v[92:95], v[132:135], v[202:205], v[92:95]
	v_mfma_f32_16x16x32_bf16 v[88:91], v[178:181], v[202:205], v[88:91]
	v_mfma_f32_16x16x32_bf16 v[84:87], v[132:135], v[210:213], v[84:87]
	v_mfma_f32_16x16x32_bf16 v[80:83], v[178:181], v[210:213], v[80:83]
	v_mfma_f32_16x16x32_bf16 v[76:79], v[132:135], v[218:221], v[76:79]
	v_mfma_f32_16x16x32_bf16 v[72:75], v[178:181], v[218:221], v[72:75]
	v_mfma_f32_16x16x32_bf16 v[68:71], v[132:135], v[226:229], v[68:71]
	v_mfma_f32_16x16x32_bf16 v[64:67], v[178:181], v[226:229], v[64:67]
	s_setprio 0
	s_setprio 1
	v_mfma_f32_16x16x32_bf16 v[28:31], v[182:185], v[198:201], v[28:31]
	v_mfma_f32_16x16x32_bf16 v[24:27], v[190:193], v[198:201], v[24:27]
	v_mfma_f32_16x16x32_bf16 v[20:23], v[182:185], v[206:209], v[20:23]
	v_mfma_f32_16x16x32_bf16 v[16:19], v[190:193], v[206:209], v[16:19]
	v_mfma_f32_16x16x32_bf16 v[12:15], v[182:185], v[214:217], v[12:15]
	v_mfma_f32_16x16x32_bf16 v[8:11], v[190:193], v[214:217], v[8:11]
	v_mfma_f32_16x16x32_bf16 v[4:7], v[182:185], v[222:225], v[4:7]
	v_mfma_f32_16x16x32_bf16 v[0:3], v[190:193], v[222:225], v[0:3]
	v_mfma_f32_16x16x32_bf16 v[28:31], v[186:189], v[202:205], v[28:31]
	v_mfma_f32_16x16x32_bf16 v[24:27], v[194:197], v[202:205], v[24:27]
	v_mfma_f32_16x16x32_bf16 v[20:23], v[186:189], v[210:213], v[20:23]
	v_mfma_f32_16x16x32_bf16 v[16:19], v[194:197], v[210:213], v[16:19]
	v_mfma_f32_16x16x32_bf16 v[12:15], v[186:189], v[218:221], v[12:15]
	v_mfma_f32_16x16x32_bf16 v[8:11], v[194:197], v[218:221], v[8:11]
	v_mfma_f32_16x16x32_bf16 v[4:7], v[186:189], v[226:229], v[4:7]
	v_mfma_f32_16x16x32_bf16 v[0:3], v[194:197], v[226:229], v[0:3]
	s_setprio 0
	s_barrier
	s_add_i32 s59, s59, 2
	s_add_u32 s28, s28, 0x100
	s_addc_u32 s29, s29, 0
	s_add_u32 s57, s57, 0x100
	s_addc_u32 s58, s58, 0
	s_cmp_gt_u32 s59, 13

; #define PG8_STAGE(bufoff, gbase, voff) do { _Pragma("unroll") for (int _i = 0; _i < 2; ++_i) \
;         __builtin_amdgcn_global_load_lds((const unsigned*)((const char*)(gbase) + (voff)[_i]), (PG8_LAS unsigned*)(lds + (bufoff) + ldsw + _i * 8192), 16, 0, 0); } while (0)
; #define PG8_LDA(dst, b, h) do { _Pragma("unroll") for (int m = 0; m < 4; ++m) _Pragma("unroll") for (int k = 0; k < 2; ++k) dst[m][k] = *(const PG8_LAS bf16x8*)(lds + PG8_SA(b, h) + aoff + m * 2048 + k * 1024); } while (0)
; #define PG8_LDB(dst, b, h) do { _Pragma("unroll") for (int n = 0; n < 2; ++n) _Pragma("unroll") for (int k = 0; k < 2; ++k) dst[n][k] = *(const PG8_LAS bf16x8*)(lds + PG8_SB(b, h) + boff + n * 2048 + k * 1024); } while (0)
; #define PG8_SCHED __builtin_amdgcn_sched_barrier(0)
; template <class Epi, class Sched, bool ALIGN_EPI = false, bool SP2 = false>
; __device__ __forceinline__ void gemm_phase(PG8_LAS unsigned char* lds, const Gemm g, const Sched& S, const Epi& E) {
;     ...
;         const bool has_next = S.next(ui + 1, nxt);
;         const char* nA = has_next ? (const char*)g.A + (size_t)nxt.pm * tstep : cA; const char* nB = has_next ? (const char*)g.Bt + (size_t)nxt.pn * tstep : cB;
;         for (int t = 0; t < nt; t += 2) {
;             const bool last = (t == nt - 2);
;             const char* a1 = cA + (size_t)(t + 1) * kstep;
;             const char* a2 = last ? nA : cA + (size_t)(t + 2) * kstep; const char* b2 = last ? nB : cB + (size_t)(t + 2) * kstep;
;             const char* a3 = a2 + kstep; const char* b3 = b2 + kstep;
;             if (last && has_next) S.a_ready(nxt, ui + 1);
;             if constexpr (SP2) {
;             PG8_LDB(B0, 0, 0); PG8_LDB(B1, 0, 1); PG8_SCHED; PG8_LDA(At, 0, 0); PG8_STAGE(PG8_SA(1, 1), a1 + hstep, voffA);
.LBB0_953:
	ds_read_b128 v[120:123], v245
	ds_read_b128 v[128:131], v245 offset:1024
	ds_read_b128 v[136:139], v245 offset:2048
	ds_read_b128 v[140:143], v245 offset:3072
	ds_read_b128 v[144:147], v246
	ds_read_b128 v[148:151], v246 offset:1024
	ds_read_b128 v[152:155], v246 offset:2048
	ds_read_b128 v[156:159], v246 offset:3072
	ds_read_b128 v[160:163], v247
	ds_read_b128 v[164:167], v247 offset:1024
	ds_read_b128 v[168:171], v247 offset:2048
	ds_read_b128 v[172:175], v247 offset:3072
	ds_read_b128 v[176:179], v247 offset:4096
	ds_read_b128 v[180:183], v247 offset:5120
	ds_read_b128 v[184:187], v247 offset:6144
	ds_read_b128 v[188:191], v247 offset:7168
	s_add_i32 s53, s53, 1
	s_mul_i32 s4, s53, s48
	s_mul_hi_u32 s5, s53, s49
	s_add_i32 s5, s5, s4
	s_mul_i32 s4, s53, s49
	s_add_u32 s24, s4, s2
	s_addc_u32 s25, s5, s50
	s_waitcnt lgkmcnt(0)
	v_mov_b64_e32 v[0:1], 0x200
	v_cmp_lt_i64_e64 s[4:5], s[24:25], v[0:1]
	v_mov_b64_e32 v[0:1], 0x1ff
	v_cmp_gt_i64_e32 vcc, s[24:25], v[0:1]
	s_cbranch_vccnz .LBB0_959
	s_ashr_i32 s20, s24, 31
	s_lshr_b32 s20, s20, 29
	s_add_i32 s22, s24, s20
	s_and_b32 s20, s22, -8
	s_sub_i32 s23, s24, s20
	s_cmp_gt_i32 s23, -1
	s_mov_b64 s[20:21], -1
	s_cbranch_scc0 .LBB0_956
	s_lshl_b32 s24, s23, 6
	s_mov_b64 s[20:21], 0

; #define PG8_STAGE(bufoff, gbase, voff) do { _Pragma("unroll") for (int _i = 0; _i < 2; ++_i) \
;         __builtin_amdgcn_global_load_lds((const unsigned*)((const char*)(gbase) + (voff)[_i]), (PG8_LAS unsigned*)(lds + (bufoff) + ldsw + _i * 8192), 16, 0, 0); } while (0)
; #define PG8_LDA(dst, b, h) do { _Pragma("unroll") for (int m = 0; m < 4; ++m) _Pragma("unroll") for (int k = 0; k < 2; ++k) dst[m][k] = *(const PG8_LAS bf16x8*)(lds + PG8_SA(b, h) + aoff + m * 2048 + k * 1024); } while (0)
; #define PG8_LDB(dst, b, h) do { _Pragma("unroll") for (int n = 0; n < 2; ++n) _Pragma("unroll") for (int k = 0; k < 2; ++k) dst[n][k] = *(const PG8_LAS bf16x8*)(lds + PG8_SB(b, h) + boff + n * 2048 + k * 1024); } while (0)
; #define PG8_WAIT_V(n) asm volatile("s_waitcnt vmcnt(" #n ")" ::: "memory")
; #define PG8_WAIT_L(n) asm volatile("s_waitcnt lgkmcnt(" #n ")" ::: "memory")
; #define PG8_BAR __builtin_amdgcn_s_barrier()
; #define PG8_SCHED __builtin_amdgcn_sched_barrier(0)
; template <class Epi, class Sched, bool ALIGN_EPI = false, bool SP2 = false>
; __device__ __forceinline__ void gemm_phase(PG8_LAS unsigned char* lds, const Gemm g, const Sched& S, const Epi& E) {
;     ...
;         const char* nA = has_next ? (const char*)g.A + (size_t)nxt.pm * tstep : cA; const char* nB = has_next ? (const char*)g.Bt + (size_t)nxt.pn * tstep : cB;
;         for (int t = 0; t < nt; t += 2) {
;             const bool last = (t == nt - 2);
;             const char* a1 = cA + (size_t)(t + 1) * kstep;
;             const char* a2 = last ? nA : cA + (size_t)(t + 2) * kstep; const char* b2 = last ? nB : cB + (size_t)(t + 2) * kstep;
;             const char* a3 = a2 + kstep; const char* b3 = b2 + kstep;
;             if (last && has_next) S.a_ready(nxt, ui + 1);
;             if constexpr (SP2) {
;             PG8_LDB(B0, 0, 0); PG8_LDB(B1, 0, 1); PG8_SCHED; PG8_LDA(At, 0, 0); PG8_STAGE(PG8_SA(1, 1), a1 + hstep, voffA);
;             PG8_WAIT_V(8); PG8_WAIT_L(0); PG8_BAR; PG8_MMA(0, 0, At, B0); PG8_MMA(0, 1, At, B1); PG8_BAR; PG8_SCHED;
;             PG8_LDA(At, 0, 1); PG8_STAGE(PG8_SB(0, 0), b2, voffB); PG8_STAGE(PG8_SB(0, 1), b2 + hstep, voffB); PG8_STAGE(PG8_SA(0, 0), a2, voffA);
;             PG8_WAIT_V(8); PG8_WAIT_L(0); PG8_BAR; PG8_MMA(1, 0, At, B0); PG8_MMA(1, 1, At, B1); PG8_BAR; PG8_SCHED;
.LBB0_959:
	s_ashr_i32 s23, s22, 31
	s_lshl_b64 s[24:25], s[22:23], 19
	s_add_u32 s24, s3, s24
	s_addc_u32 s25, s33, s25
	s_and_b64 s[26:27], s[4:5], exec
	s_cselect_b32 s23, s25, s31
	s_cselect_b32 s29, s24, s30
	s_ashr_i32 s21, s20, 31
	s_lshl_b64 s[26:27], s[20:21], 19
	s_add_u32 s26, s38, s26
	s_addc_u32 s27, s39, s27
	s_and_b64 s[36:37], s[4:5], exec
	s_cselect_b32 s21, s27, s35
	s_cselect_b32 s54, s26, s34
	s_add_u32 s30, s30, 0x40080
	s_addc_u32 s31, s31, 0
	s_add_u32 s55, s34, 0x100
	s_addc_u32 s56, s35, 0
	s_mov_b32 s57, -2
	s_add_u32 s34, s30, 0xfffc0080
	s_addc_u32 s35, s31, -1
	s_cmp_eq_u32 s57, 12
	s_cselect_b32 s37, s23, s35
	s_cselect_b32 s36, s29, s34
	s_cselect_b32 s35, s21, s56
	s_cselect_b32 s34, s54, s55
	v_lshl_add_u64 v[204:205], s[30:31], 0, v[200:201]
	s_add_i32 m0, s41, 0xc000
	global_load_lds_dwordx4 v[204:205], off
	v_lshl_add_u64 v[204:205], s[30:31], 0, v[202:203]
	s_add_i32 m0, s41, 0xe000
	s_nop 0
	global_load_lds_dwordx4 v[204:205], off
	s_waitcnt vmcnt(8)
	s_waitcnt lgkmcnt(0)
	s_barrier
	s_setprio 1
	s_waitcnt lgkmcnt(0)
	v_mfma_f32_16x16x32_bf16 v[132:135], v[120:123], v[160:163], 0
	v_mfma_f32_16x16x32_bf16 v[124:127], v[136:139], v[160:163], 0
	v_mfma_f32_16x16x32_bf16 v[108:111], v[120:123], v[168:171], 0
	v_mfma_f32_16x16x32_bf16 v[104:107], v[136:139], v[168:171], 0
	v_mfma_f32_16x16x32_bf16 v[92:95], v[120:123], v[176:179], 0
	v_mfma_f32_16x16x32_bf16 v[88:91], v[136:139], v[176:179], 0
	v_mfma_f32_16x16x32_bf16 v[76:79], v[120:123], v[184:187], 0
	v_mfma_f32_16x16x32_bf16 v[72:75], v[136:139], v[184:187], 0
	v_mfma_f32_16x16x32_bf16 v[132:135], v[128:131], v[164:167], v[132:135]
	v_mfma_f32_16x16x32_bf16 v[124:127], v[140:143], v[164:167], v[124:127]
	v_mfma_f32_16x16x32_bf16 v[108:111], v[128:131], v[172:175], v[108:111]
	v_mfma_f32_16x16x32_bf16 v[104:107], v[140:143], v[172:175], v[104:107]
	v_mfma_f32_16x16x32_bf16 v[92:95], v[128:131], v[180:183], v[92:95]
	v_mfma_f32_16x16x32_bf16 v[88:91], v[140:143], v[180:183], v[88:91]
	v_mfma_f32_16x16x32_bf16 v[76:79], v[128:131], v[188:191], v[76:79]
	v_mfma_f32_16x16x32_bf16 v[72:75], v[140:143], v[188:191], v[72:75]
	s_setprio 0
	s_setprio 1
	v_mfma_f32_16x16x32_bf16 v[116:119], v[144:147], v[160:163], 0
	v_mfma_f32_16x16x32_bf16 v[112:115], v[152:155], v[160:163], 0
	v_mfma_f32_16x16x32_bf16 v[100:103], v[144:147], v[168:171], 0
	v_mfma_f32_16x16x32_bf16 v[96:99], v[152:155], v[168:171], 0
	v_mfma_f32_16x16x32_bf16 v[84:87], v[144:147], v[176:179], 0
	v_mfma_f32_16x16x32_bf16 v[80:83], v[152:155], v[176:179], 0
	v_mfma_f32_16x16x32_bf16 v[68:71], v[144:147], v[184:187], 0
	v_mfma_f32_16x16x32_bf16 v[64:67], v[152:155], v[184:187], 0
	v_mfma_f32_16x16x32_bf16 v[116:119], v[148:151], v[164:167], v[116:119]
	v_mfma_f32_16x16x32_bf16 v[112:115], v[156:159], v[164:167], v[112:115]
	v_mfma_f32_16x16x32_bf16 v[100:103], v[148:151], v[172:175], v[100:103]
	v_mfma_f32_16x16x32_bf16 v[96:99], v[156:159], v[172:175], v[96:99]
	v_mfma_f32_16x16x32_bf16 v[84:87], v[148:151], v[180:183], v[84:87]
	v_mfma_f32_16x16x32_bf16 v[80:83], v[156:159], v[180:183], v[80:83]
	v_mfma_f32_16x16x32_bf16 v[68:71], v[148:151], v[188:191], v[68:71]
	v_mfma_f32_16x16x32_bf16 v[64:67], v[156:159], v[188:191], v[64:67]
	s_setprio 0
	s_barrier
	s_add_i32 s58, s51, s40
	v_lshl_add_u64 v[204:205], s[34:35], 0, v[194:195]
	s_mov_b32 m0, s58
	ds_read_b128 v[160:163], v247 offset:16384
	ds_read_b128 v[164:167], v247 offset:17408
	ds_read_b128 v[168:171], v247 offset:18432
	ds_read_b128 v[172:175], v247 offset:19456
	ds_read_b128 v[176:179], v247 offset:20480
	ds_read_b128 v[180:183], v247 offset:21504
	ds_read_b128 v[184:187], v247 offset:22528
	ds_read_b128 v[188:191], v247 offset:23552
	global_load_lds_dwordx4 v[204:205], off
	s_add_i32 m0, s58, 0x2000
	s_add_u32 s58, s34, 0x40000
	v_lshl_add_u64 v[206:207], s[34:35], 0, v[198:199]
	s_addc_u32 s59, s35, 0
	s_add_i32 s60, s52, s40
	global_load_lds_dwordx4 v[206:207], off
	v_lshl_add_u64 v[208:209], s[58:59], 0, v[194:195]
	s_mov_b32 m0, s60
	v_lshl_add_u64 v[210:211], s[36:37], 0, v[196:197]
	global_load_lds_dwordx4 v[208:209], off
	v_lshl_add_u64 v[208:209], s[58:59], 0, v[198:199]
	s_add_i32 m0, s60, 0x2000
	s_nop 0
	global_load_lds_dwordx4 v[208:209], off
	v_lshl_add_u64 v[208:209], s[36:37], 0, v[192:193]
	s_mov_b32 m0, s41
	s_nop 0
	global_load_lds_dwordx4 v[208:209], off
	s_mov_b32 m0, s42
	s_nop 0
	global_load_lds_dwordx4 v[210:211], off
	s_waitcnt vmcnt(8)
	s_waitcnt lgkmcnt(0)
	s_barrier
	s_setprio 1
	s_waitcnt lgkmcnt(0)
	v_mfma_f32_16x16x32_bf16 v[60:63], v[120:123], v[160:163], 0
	v_mfma_f32_16x16x32_bf16 v[56:59], v[136:139], v[160:163], 0
	v_mfma_f32_16x16x32_bf16 v[44:47], v[120:123], v[168:171], 0
	v_mfma_f32_16x16x32_bf16 v[40:43], v[136:139], v[168:171], 0
	v_mfma_f32_16x16x32_bf16 v[28:31], v[120:123], v[176:179], 0
	v_mfma_f32_16x16x32_bf16 v[24:27], v[136:139], v[176:179], 0
	v_mfma_f32_16x16x32_bf16 v[12:15], v[120:123], v[184:187], 0
	v_mfma_f32_16x16x32_bf16 v[8:11], v[136:139], v[184:187], 0
	v_mfma_f32_16x16x32_bf16 v[60:63], v[128:131], v[164:167], v[60:63]
	v_mfma_f32_16x16x32_bf16 v[56:59], v[140:143], v[164:167], v[56:59]
	v_mfma_f32_16x16x32_bf16 v[44:47], v[128:131], v[172:175], v[44:47]
	v_mfma_f32_16x16x32_bf16 v[40:43], v[140:143], v[172:175], v[40:43]
	v_mfma_f32_16x16x32_bf16 v[28:31], v[128:131], v[180:183], v[28:31]
	v_mfma_f32_16x16x32_bf16 v[24:27], v[140:143], v[180:183], v[24:27]
	v_mfma_f32_16x16x32_bf16 v[12:15], v[128:131], v[188:191], v[12:15]
	v_mfma_f32_16x16x32_bf16 v[8:11], v[140:143], v[188:191], v[8:11]
	s_setprio 0
	s_setprio 1
	v_mfma_f32_16x16x32_bf16 v[52:55], v[144:147], v[160:163], 0
	v_mfma_f32_16x16x32_bf16 v[48:51], v[152:155], v[160:163], 0
	v_mfma_f32_16x16x32_bf16 v[36:39], v[144:147], v[168:171], 0
	v_mfma_f32_16x16x32_bf16 v[32:35], v[152:155], v[168:171], 0
	v_mfma_f32_16x16x32_bf16 v[20:23], v[144:147], v[176:179], 0
	v_mfma_f32_16x16x32_bf16 v[16:19], v[152:155], v[176:179], 0
	v_mfma_f32_16x16x32_bf16 v[4:7], v[144:147], v[184:187], 0
	v_mfma_f32_16x16x32_bf16 v[0:3], v[152:155], v[184:187], 0
	v_mfma_f32_16x16x32_bf16 v[52:55], v[148:151], v[164:167], v[52:55]
	v_mfma_f32_16x16x32_bf16 v[48:51], v[156:159], v[164:167], v[48:51]
	v_mfma_f32_16x16x32_bf16 v[36:39], v[148:151], v[172:175], v[36:39]
	v_mfma_f32_16x16x32_bf16 v[32:35], v[156:159], v[172:175], v[32:35]
	v_mfma_f32_16x16x32_bf16 v[20:23], v[148:151], v[180:183], v[20:23]
	v_mfma_f32_16x16x32_bf16 v[16:19], v[156:159], v[180:183], v[16:19]
	v_mfma_f32_16x16x32_bf16 v[4:7], v[148:151], v[188:191], v[4:7]
	v_mfma_f32_16x16x32_bf16 v[0:3], v[156:159], v[188:191], v[0:3]
	s_setprio 0
	s_barrier
; #define PG8_STAGE(bufoff, gbase, voff) do { _Pragma("unroll") for (int _i = 0; _i < 2; ++_i) \
;         __builtin_amdgcn_global_load_lds((const unsigned*)((const char*)(gbase) + (voff)[_i]), (PG8_LAS unsigned*)(lds + (bufoff) + ldsw + _i * 8192), 16, 0, 0); } while (0)
; #define PG8_LDA(dst, b, h) do { _Pragma("unroll") for (int m = 0; m < 4; ++m) _Pragma("unroll") for (int k = 0; k < 2; ++k) dst[m][k] = *(const PG8_LAS bf16x8*)(lds + PG8_SA(b, h) + aoff + m * 2048 + k * 1024); } while (0)
; #define PG8_LDB(dst, b, h) do { _Pragma("unroll") for (int n = 0; n < 2; ++n) _Pragma("unroll") for (int k = 0; k < 2; ++k) dst[n][k] = *(const PG8_LAS bf16x8*)(lds + PG8_SB(b, h) + boff + n * 2048 + k * 1024); } while (0)
; #define PG8_MMA(ai, bj, At, Bt) do { __builtin_amdgcn_s_setprio(1); _Pragma("unroll") for (int m = 0; m < 4; ++m) _Pragma("unroll") for (int n = 0; n < 2; ++n) _Pragma("unroll") for (int k = 0; k < 2; ++k) \
;         acc[ai][bj][m][n] = __builtin_amdgcn_mfma_f32_16x16x32_bf16(Bt[n][k], At[m][k], acc[ai][bj][m][n], 0, 0, 0); __builtin_amdgcn_s_setprio(0); } while (0)
; #define PG8_WAIT_V(n) asm volatile("s_waitcnt vmcnt(" #n ")" ::: "memory")
; #define PG8_WAIT_L(n) asm volatile("s_waitcnt lgkmcnt(" #n ")" ::: "memory")
; #define PG8_BAR __builtin_amdgcn_s_barrier()
; #define PG8_SCHED __builtin_amdgcn_sched_barrier(0)
; template <class Epi, class Sched, bool ALIGN_EPI = false, bool SP2 = false>
; __device__ __forceinline__ void gemm_phase(PG8_LAS unsigned char* lds, const Gemm g, const Sched& S, const Epi& E) {
;     ...
;             PG8_LDB(B0, 1, 0); PG8_LDB(B1, 1, 1); PG8_SCHED; PG8_LDA(At, 1, 0); PG8_STAGE(PG8_SA(0, 1), a2 + hstep, voffA);
;             PG8_WAIT_V(8); PG8_WAIT_L(0); PG8_BAR; PG8_MMA(0, 0, At, B0); PG8_MMA(0, 1, At, B1); PG8_BAR; PG8_SCHED;
	s_add_i32 s58, 0, 0x18000
	s_add_i32 s59, 0, 0x1c000
	v_add_u32_e32 v140, s58, v243
	v_add_u32_e32 v156, s59, v243
	ds_read_b128 v[120:123], v140
	ds_read_b128 v[128:131], v140 offset:1024
	ds_read_b128 v[136:139], v140 offset:2048
	ds_read_b128 v[140:143], v140 offset:3072
	ds_read_b128 v[144:147], v156
	ds_read_b128 v[148:151], v156 offset:1024
	ds_read_b128 v[152:155], v156 offset:2048
	ds_read_b128 v[156:159], v156 offset:3072
	s_add_u32 s36, s36, 0x40000
	s_addc_u32 s37, s37, 0
	s_mov_b32 m0, s43
	v_lshl_add_u64 v[212:213], s[36:37], 0, v[192:193]
	ds_read_b128 v[160:163], v247 offset:32768
	ds_read_b128 v[164:167], v247 offset:33792
	ds_read_b128 v[168:171], v247 offset:34816
	ds_read_b128 v[172:175], v247 offset:35840
	ds_read_b128 v[176:179], v247 offset:36864
	ds_read_b128 v[180:183], v247 offset:37888
	ds_read_b128 v[184:187], v247 offset:38912
	ds_read_b128 v[188:191], v247 offset:39936
	global_load_lds_dwordx4 v[212:213], off
	v_lshl_add_u64 v[212:213], s[36:37], 0, v[196:197]
	s_mov_b32 m0, s44
	s_nop 0
	global_load_lds_dwordx4 v[212:213], off
	s_waitcnt vmcnt(8)
	s_waitcnt lgkmcnt(0)
	s_barrier
	s_setprio 1
	s_waitcnt lgkmcnt(0)
	v_mfma_f32_16x16x32_bf16 v[132:135], v[120:123], v[160:163], v[132:135]
	v_mfma_f32_16x16x32_bf16 v[124:127], v[136:139], v[160:163], v[124:127]
	v_mfma_f32_16x16x32_bf16 v[108:111], v[120:123], v[168:171], v[108:111]
	v_mfma_f32_16x16x32_bf16 v[104:107], v[136:139], v[168:171], v[104:107]
	v_mfma_f32_16x16x32_bf16 v[92:95], v[120:123], v[176:179], v[92:95]
	v_mfma_f32_16x16x32_bf16 v[88:91], v[136:139], v[176:179], v[88:91]
	v_mfma_f32_16x16x32_bf16 v[76:79], v[120:123], v[184:187], v[76:79]
	v_mfma_f32_16x16x32_bf16 v[72:75], v[136:139], v[184:187], v[72:75]
	v_mfma_f32_16x16x32_bf16 v[132:135], v[128:131], v[164:167], v[132:135]
	v_mfma_f32_16x16x32_bf16 v[124:127], v[140:143], v[164:167], v[124:127]
	v_mfma_f32_16x16x32_bf16 v[108:111], v[128:131], v[172:175], v[108:111]
	v_mfma_f32_16x16x32_bf16 v[104:107], v[140:143], v[172:175], v[104:107]
	v_mfma_f32_16x16x32_bf16 v[92:95], v[128:131], v[180:183], v[92:95]
	v_mfma_f32_16x16x32_bf16 v[88:91], v[140:143], v[180:183], v[88:91]
	v_mfma_f32_16x16x32_bf16 v[76:79], v[128:131], v[188:191], v[76:79]
	v_mfma_f32_16x16x32_bf16 v[72:75], v[140:143], v[188:191], v[72:75]
	s_setprio 0
	s_setprio 1
	v_mfma_f32_16x16x32_bf16 v[116:119], v[144:147], v[160:163], v[116:119]
	v_mfma_f32_16x16x32_bf16 v[112:115], v[152:155], v[160:163], v[112:115]
	v_mfma_f32_16x16x32_bf16 v[100:103], v[144:147], v[168:171], v[100:103]
	v_mfma_f32_16x16x32_bf16 v[96:99], v[152:155], v[168:171], v[96:99]
	v_mfma_f32_16x16x32_bf16 v[84:87], v[144:147], v[176:179], v[84:87]
	v_mfma_f32_16x16x32_bf16 v[80:83], v[152:155], v[176:179], v[80:83]
	v_mfma_f32_16x16x32_bf16 v[68:71], v[144:147], v[184:187], v[68:71]
	v_mfma_f32_16x16x32_bf16 v[64:67], v[152:155], v[184:187], v[64:67]
	v_mfma_f32_16x16x32_bf16 v[116:119], v[148:151], v[164:167], v[116:119]
	v_mfma_f32_16x16x32_bf16 v[112:115], v[156:159], v[164:167], v[112:115]
	v_mfma_f32_16x16x32_bf16 v[100:103], v[148:151], v[172:175], v[100:103]
	v_mfma_f32_16x16x32_bf16 v[96:99], v[156:159], v[172:175], v[96:99]
	v_mfma_f32_16x16x32_bf16 v[84:87], v[148:151], v[180:183], v[84:87]
	v_mfma_f32_16x16x32_bf16 v[80:83], v[156:159], v[180:183], v[80:83]
	v_mfma_f32_16x16x32_bf16 v[68:71], v[148:151], v[188:191], v[68:71]
	v_mfma_f32_16x16x32_bf16 v[64:67], v[156:159], v[188:191], v[64:67]
	s_setprio 0
	s_barrier
; #define PG8_STAGE(bufoff, gbase, voff) do { _Pragma("unroll") for (int _i = 0; _i < 2; ++_i) \
;         __builtin_amdgcn_global_load_lds((const unsigned*)((const char*)(gbase) + (voff)[_i]), (PG8_LAS unsigned*)(lds + (bufoff) + ldsw + _i * 8192), 16, 0, 0); } while (0)
; #define PG8_LDA(dst, b, h) do { _Pragma("unroll") for (int m = 0; m < 4; ++m) _Pragma("unroll") for (int k = 0; k < 2; ++k) dst[m][k] = *(const PG8_LAS bf16x8*)(lds + PG8_SA(b, h) + aoff + m * 2048 + k * 1024); } while (0)
; #define PG8_MMA(ai, bj, At, Bt) do { __builtin_amdgcn_s_setprio(1); _Pragma("unroll") for (int m = 0; m < 4; ++m) _Pragma("unroll") for (int n = 0; n < 2; ++n) _Pragma("unroll") for (int k = 0; k < 2; ++k) \
;         acc[ai][bj][m][n] = __builtin_amdgcn_mfma_f32_16x16x32_bf16(Bt[n][k], At[m][k], acc[ai][bj][m][n], 0, 0, 0); __builtin_amdgcn_s_setprio(0); } while (0)
; #define PG8_WAIT_V(n) asm volatile("s_waitcnt vmcnt(" #n ")" ::: "memory")
; #define PG8_WAIT_L(n) asm volatile("s_waitcnt lgkmcnt(" #n ")" ::: "memory")
; #define PG8_BAR __builtin_amdgcn_s_barrier()
; #define PG8_SCHED __builtin_amdgcn_sched_barrier(0)
; template <class Epi, class Sched, bool ALIGN_EPI = false, bool SP2 = false>
; __device__ __forceinline__ void gemm_phase(PG8_LAS unsigned char* lds, const Gemm g, const Sched& S, const Epi& E) {
;     ...
;             PG8_LDA(At, 1, 1); PG8_STAGE(PG8_SB(1, 0), b3, voffB); PG8_STAGE(PG8_SB(1, 1), b3 + hstep, voffB); PG8_STAGE(PG8_SA(1, 0), a3, voffA);
;             PG8_WAIT_V(8); PG8_WAIT_L(0); PG8_BAR; PG8_MMA(1, 0, At, B0); PG8_MMA(1, 1, At, B1); PG8_BAR; PG8_SCHED;
	s_add_i32 s36, s58, s40
	v_lshl_add_u64 v[204:205], v[204:205], 0, s[16:17]
	s_mov_b32 m0, s36
	ds_read_b128 v[160:163], v247 offset:49152
	ds_read_b128 v[164:167], v247 offset:50176
	ds_read_b128 v[168:171], v247 offset:51200
	ds_read_b128 v[172:175], v247 offset:52224
	ds_read_b128 v[176:179], v247 offset:53248
	ds_read_b128 v[180:183], v247 offset:54272
	ds_read_b128 v[184:187], v247 offset:55296
	ds_read_b128 v[188:191], v247 offset:56320
	global_load_lds_dwordx4 v[204:205], off
	s_add_i32 m0, s36, 0x2000
	s_add_u32 s34, s34, 0x40080
	v_lshl_add_u64 v[204:205], v[206:207], 0, s[16:17]
	s_addc_u32 s35, s35, 0
	s_add_i32 s36, s59, s40
	global_load_lds_dwordx4 v[204:205], off
	v_lshl_add_u64 v[204:205], s[34:35], 0, v[194:195]
	s_mov_b32 m0, s36
	s_nop 0
	global_load_lds_dwordx4 v[204:205], off
	v_lshl_add_u64 v[204:205], s[34:35], 0, v[198:199]
	s_add_i32 m0, s36, 0x2000
	s_nop 0
	global_load_lds_dwordx4 v[204:205], off
	v_lshl_add_u64 v[204:205], v[208:209], 0, s[16:17]
	s_mov_b32 m0, s46
	s_nop 0
	global_load_lds_dwordx4 v[204:205], off
	v_lshl_add_u64 v[204:205], v[210:211], 0, s[16:17]
	s_mov_b32 m0, s47
	s_nop 0
	global_load_lds_dwordx4 v[204:205], off
	s_waitcnt vmcnt(8)
	s_waitcnt lgkmcnt(0)
	s_barrier
	s_setprio 1
	s_waitcnt lgkmcnt(0)
	v_mfma_f32_16x16x32_bf16 v[60:63], v[120:123], v[160:163], v[60:63]
	v_mfma_f32_16x16x32_bf16 v[56:59], v[136:139], v[160:163], v[56:59]
	v_mfma_f32_16x16x32_bf16 v[44:47], v[120:123], v[168:171], v[44:47]
	v_mfma_f32_16x16x32_bf16 v[40:43], v[136:139], v[168:171], v[40:43]
	v_mfma_f32_16x16x32_bf16 v[28:31], v[120:123], v[176:179], v[28:31]
	v_mfma_f32_16x16x32_bf16 v[24:27], v[136:139], v[176:179], v[24:27]
	v_mfma_f32_16x16x32_bf16 v[12:15], v[120:123], v[184:187], v[12:15]
	v_mfma_f32_16x16x32_bf16 v[8:11], v[136:139], v[184:187], v[8:11]
	v_mfma_f32_16x16x32_bf16 v[60:63], v[128:131], v[164:167], v[60:63]
	v_mfma_f32_16x16x32_bf16 v[56:59], v[140:143], v[164:167], v[56:59]
	v_mfma_f32_16x16x32_bf16 v[44:47], v[128:131], v[172:175], v[44:47]
	v_mfma_f32_16x16x32_bf16 v[40:43], v[140:143], v[172:175], v[40:43]
	v_mfma_f32_16x16x32_bf16 v[28:31], v[128:131], v[180:183], v[28:31]
	v_mfma_f32_16x16x32_bf16 v[24:27], v[140:143], v[180:183], v[24:27]
	v_mfma_f32_16x16x32_bf16 v[12:15], v[128:131], v[188:191], v[12:15]
	v_mfma_f32_16x16x32_bf16 v[8:11], v[140:143], v[188:191], v[8:11]
	s_setprio 0
	s_setprio 1
	v_mfma_f32_16x16x32_bf16 v[52:55], v[144:147], v[160:163], v[52:55]
	v_mfma_f32_16x16x32_bf16 v[48:51], v[152:155], v[160:163], v[48:51]
	v_mfma_f32_16x16x32_bf16 v[36:39], v[144:147], v[168:171], v[36:39]
	v_mfma_f32_16x16x32_bf16 v[32:35], v[152:155], v[168:171], v[32:35]
	v_mfma_f32_16x16x32_bf16 v[20:23], v[144:147], v[176:179], v[20:23]
	v_mfma_f32_16x16x32_bf16 v[16:19], v[152:155], v[176:179], v[16:19]
	v_mfma_f32_16x16x32_bf16 v[4:7], v[144:147], v[184:187], v[4:7]
	v_mfma_f32_16x16x32_bf16 v[0:3], v[152:155], v[184:187], v[0:3]
	v_mfma_f32_16x16x32_bf16 v[52:55], v[148:151], v[164:167], v[52:55]
	v_mfma_f32_16x16x32_bf16 v[48:51], v[156:159], v[164:167], v[48:51]
	v_mfma_f32_16x16x32_bf16 v[36:39], v[148:151], v[172:175], v[36:39]
	v_mfma_f32_16x16x32_bf16 v[32:35], v[156:159], v[172:175], v[32:35]
	v_mfma_f32_16x16x32_bf16 v[20:23], v[148:151], v[180:183], v[20:23]
	v_mfma_f32_16x16x32_bf16 v[16:19], v[156:159], v[180:183], v[16:19]
	v_mfma_f32_16x16x32_bf16 v[4:7], v[148:151], v[188:191], v[4:7]
	v_mfma_f32_16x16x32_bf16 v[0:3], v[156:159], v[188:191], v[0:3]
	s_setprio 0
	s_barrier
	s_add_i32 s57, s57, 2
	s_add_u32 s30, s30, 0x100
	s_addc_u32 s31, s31, 0
	s_add_u32 s55, s55, 0x100
	s_addc_u32 s56, s56, 0
	s_cmp_gt_u32 s57, 13

; #define PG8_STAGE(bufoff, gbase, voff) do { _Pragma("unroll") for (int _i = 0; _i < 2; ++_i) \
;         __builtin_amdgcn_global_load_lds((const unsigned*)((const char*)(gbase) + (voff)[_i]), (PG8_LAS unsigned*)(lds + (bufoff) + ldsw + _i * 8192), 16, 0, 0); } while (0)
; #define PG8_LDA(dst, b, h) do { _Pragma("unroll") for (int m = 0; m < 4; ++m) _Pragma("unroll") for (int k = 0; k < 2; ++k) dst[m][k] = *(const PG8_LAS bf16x8*)(lds + PG8_SA(b, h) + aoff + m * 2048 + k * 1024); } while (0)
; #define PG8_LDB(dst, b, h) do { _Pragma("unroll") for (int n = 0; n < 2; ++n) _Pragma("unroll") for (int k = 0; k < 2; ++k) dst[n][k] = *(const PG8_LAS bf16x8*)(lds + PG8_SB(b, h) + boff + n * 2048 + k * 1024); } while (0)
; #define PG8_WAIT_V(n) asm volatile("s_waitcnt vmcnt(" #n ")" ::: "memory")
; #define PG8_WAIT_L(n) asm volatile("s_waitcnt lgkmcnt(" #n ")" ::: "memory")
; #define PG8_BAR __builtin_amdgcn_s_barrier()
; #define PG8_SCHED __builtin_amdgcn_sched_barrier(0)
; template <class Epi, class Sched, bool ALIGN_EPI = false, bool SP2 = false>
; __device__ __forceinline__ void gemm_phase(PG8_LAS unsigned char* lds, const Gemm g, const Sched& S, const Epi& E) {
;     ...
;         const char* nA = has_next ? (const char*)g.A + (size_t)nxt.pm * tstep : cA; const char* nB = has_next ? (const char*)g.Bt + (size_t)nxt.pn * tstep : cB;
;         for (int t = 0; t < nt; t += 2) {
;             const bool last = (t == nt - 2);
;             const char* a1 = cA + (size_t)(t + 1) * kstep;
;             const char* a2 = last ? nA : cA + (size_t)(t + 2) * kstep; const char* b2 = last ? nB : cB + (size_t)(t + 2) * kstep;
;             const char* a3 = a2 + kstep; const char* b3 = b2 + kstep;
;             if (last && has_next) S.a_ready(nxt, ui + 1);
;             if constexpr (SP2) {
;             PG8_LDB(B0, 0, 0); PG8_LDB(B1, 0, 1); PG8_SCHED; PG8_LDA(At, 0, 0); PG8_STAGE(PG8_SA(1, 1), a1 + hstep, voffA);
;             PG8_WAIT_V(8); PG8_WAIT_L(0); PG8_BAR; PG8_MMA(0, 0, At, B0); PG8_MMA(0, 1, At, B1); PG8_BAR; PG8_SCHED;
;             PG8_LDA(At, 0, 1); PG8_STAGE(PG8_SB(0, 0), b2, voffB); PG8_STAGE(PG8_SB(0, 1), b2 + hstep, voffB); PG8_STAGE(PG8_SA(0, 0), a2, voffA);
;             PG8_WAIT_V(8); PG8_WAIT_L(0); PG8_BAR; PG8_MMA(1, 0, At, B0); PG8_MMA(1, 1, At, B1); PG8_BAR; PG8_SCHED;
.LBB0_1048:
	s_ashr_i32 s17, s16, 31
	s_lshl_b64 s[18:19], s[16:17], 19
	s_add_u32 s18, s34, s18
	s_addc_u32 s19, s35, s19
	s_and_b64 s[20:21], s[0:1], exec
	s_cselect_b32 s17, s19, s25
	s_cselect_b32 s50, s18, s24
	s_ashr_i32 s15, s14, 31
	s_lshl_b64 s[20:21], s[14:15], 19
	s_add_u32 s20, s36, s20
	s_addc_u32 s21, s37, s21
	s_and_b64 s[28:29], s[0:1], exec
	s_cselect_b32 s15, s21, s27
	s_cselect_b32 s51, s20, s26
	s_add_u32 s24, s24, 0x40080
	s_addc_u32 s25, s25, 0
	s_add_u32 s52, s26, 0x100
	s_addc_u32 s53, s27, 0
	s_mov_b32 s54, -2
	s_add_u32 s26, s24, 0xfffc0080
	s_addc_u32 s27, s25, -1
	s_cmp_eq_u32 s54, 12
	s_cselect_b32 s29, s17, s27
	s_cselect_b32 s28, s50, s26
	s_cselect_b32 s27, s15, s53
	s_cselect_b32 s26, s51, s52
	v_lshl_add_u64 v[216:217], s[24:25], 0, v[136:137]
	s_add_i32 m0, s23, 0xc000
	global_load_lds_dwordx4 v[216:217], off
	v_lshl_add_u64 v[216:217], s[24:25], 0, v[138:139]
	s_add_i32 m0, s23, 0xe000
	s_nop 0
	global_load_lds_dwordx4 v[216:217], off
	s_waitcnt vmcnt(8)
	s_waitcnt lgkmcnt(0)
	s_barrier
	s_setprio 1
	s_waitcnt lgkmcnt(0)
	v_mfma_f32_16x16x32_bf16 v[124:127], v[152:155], v[184:187], 0
	v_mfma_f32_16x16x32_bf16 v[120:123], v[160:163], v[184:187], 0
	v_mfma_f32_16x16x32_bf16 v[108:111], v[152:155], v[192:195], 0
	v_mfma_f32_16x16x32_bf16 v[104:107], v[160:163], v[192:195], 0
	v_mfma_f32_16x16x32_bf16 v[92:95], v[152:155], v[200:203], 0
	v_mfma_f32_16x16x32_bf16 v[88:91], v[160:163], v[200:203], 0
	v_mfma_f32_16x16x32_bf16 v[76:79], v[152:155], v[208:211], 0
	v_mfma_f32_16x16x32_bf16 v[72:75], v[160:163], v[208:211], 0
	v_mfma_f32_16x16x32_bf16 v[124:127], v[156:159], v[188:191], v[124:127]
	v_mfma_f32_16x16x32_bf16 v[120:123], v[164:167], v[188:191], v[120:123]
	v_mfma_f32_16x16x32_bf16 v[108:111], v[156:159], v[196:199], v[108:111]
	v_mfma_f32_16x16x32_bf16 v[104:107], v[164:167], v[196:199], v[104:107]
	v_mfma_f32_16x16x32_bf16 v[92:95], v[156:159], v[204:207], v[92:95]
	v_mfma_f32_16x16x32_bf16 v[88:91], v[164:167], v[204:207], v[88:91]
	v_mfma_f32_16x16x32_bf16 v[76:79], v[156:159], v[212:215], v[76:79]
	v_mfma_f32_16x16x32_bf16 v[72:75], v[164:167], v[212:215], v[72:75]
	s_setprio 0
	s_setprio 1
	v_mfma_f32_16x16x32_bf16 v[116:119], v[168:171], v[184:187], 0
	v_mfma_f32_16x16x32_bf16 v[112:115], v[176:179], v[184:187], 0
	v_mfma_f32_16x16x32_bf16 v[100:103], v[168:171], v[192:195], 0
	v_mfma_f32_16x16x32_bf16 v[96:99], v[176:179], v[192:195], 0
	v_mfma_f32_16x16x32_bf16 v[84:87], v[168:171], v[200:203], 0
	v_mfma_f32_16x16x32_bf16 v[80:83], v[176:179], v[200:203], 0
	v_mfma_f32_16x16x32_bf16 v[68:71], v[168:171], v[208:211], 0
	v_mfma_f32_16x16x32_bf16 v[64:67], v[176:179], v[208:211], 0
	v_mfma_f32_16x16x32_bf16 v[116:119], v[172:175], v[188:191], v[116:119]
	v_mfma_f32_16x16x32_bf16 v[112:115], v[180:183], v[188:191], v[112:115]
	v_mfma_f32_16x16x32_bf16 v[100:103], v[172:175], v[196:199], v[100:103]
	v_mfma_f32_16x16x32_bf16 v[96:99], v[180:183], v[196:199], v[96:99]
	v_mfma_f32_16x16x32_bf16 v[84:87], v[172:175], v[204:207], v[84:87]
	v_mfma_f32_16x16x32_bf16 v[80:83], v[180:183], v[204:207], v[80:83]
	v_mfma_f32_16x16x32_bf16 v[68:71], v[172:175], v[212:215], v[68:71]
	v_mfma_f32_16x16x32_bf16 v[64:67], v[180:183], v[212:215], v[64:67]
	s_setprio 0
	s_barrier
	s_add_i32 s55, s44, s33
	v_lshl_add_u64 v[216:217], s[26:27], 0, v[132:133]
	s_mov_b32 m0, s55
	ds_read_b128 v[184:187], v150 offset:16384
	ds_read_b128 v[188:191], v150 offset:17408
	ds_read_b128 v[192:195], v150 offset:18432
	ds_read_b128 v[196:199], v150 offset:19456
	ds_read_b128 v[200:203], v150 offset:20480
	ds_read_b128 v[204:207], v150 offset:21504
	ds_read_b128 v[208:211], v150 offset:22528
	ds_read_b128 v[212:215], v150 offset:23552
	global_load_lds_dwordx4 v[216:217], off
	s_add_i32 m0, s55, 0x2000
	s_add_u32 s56, s26, 0x40000
	v_lshl_add_u64 v[218:219], s[26:27], 0, v[128:129]
	s_addc_u32 s57, s27, 0
	s_add_i32 s55, s45, s33
	global_load_lds_dwordx4 v[218:219], off
	v_lshl_add_u64 v[220:221], s[56:57], 0, v[132:133]
	s_mov_b32 m0, s55
	v_lshl_add_u64 v[222:223], s[28:29], 0, v[130:131]
	global_load_lds_dwordx4 v[220:221], off
	v_lshl_add_u64 v[220:221], s[56:57], 0, v[128:129]
	s_add_i32 m0, s55, 0x2000
	s_nop 0
	global_load_lds_dwordx4 v[220:221], off
	v_lshl_add_u64 v[220:221], s[28:29], 0, v[134:135]
	s_mov_b32 m0, s23
	s_nop 0
	global_load_lds_dwordx4 v[220:221], off
	s_mov_b32 m0, s39
	s_nop 0
	global_load_lds_dwordx4 v[222:223], off
	s_waitcnt vmcnt(8)
	s_waitcnt lgkmcnt(0)
	s_barrier
	s_setprio 1
	s_waitcnt lgkmcnt(0)
	v_mfma_f32_16x16x32_bf16 v[60:63], v[152:155], v[184:187], 0
	v_mfma_f32_16x16x32_bf16 v[56:59], v[160:163], v[184:187], 0
	v_mfma_f32_16x16x32_bf16 v[44:47], v[152:155], v[192:195], 0
	v_mfma_f32_16x16x32_bf16 v[40:43], v[160:163], v[192:195], 0
	v_mfma_f32_16x16x32_bf16 v[28:31], v[152:155], v[200:203], 0
	v_mfma_f32_16x16x32_bf16 v[24:27], v[160:163], v[200:203], 0
	v_mfma_f32_16x16x32_bf16 v[12:15], v[152:155], v[208:211], 0
	v_mfma_f32_16x16x32_bf16 v[8:11], v[160:163], v[208:211], 0
	v_mfma_f32_16x16x32_bf16 v[60:63], v[156:159], v[188:191], v[60:63]
	v_mfma_f32_16x16x32_bf16 v[56:59], v[164:167], v[188:191], v[56:59]
	v_mfma_f32_16x16x32_bf16 v[44:47], v[156:159], v[196:199], v[44:47]
	v_mfma_f32_16x16x32_bf16 v[40:43], v[164:167], v[196:199], v[40:43]
	v_mfma_f32_16x16x32_bf16 v[28:31], v[156:159], v[204:207], v[28:31]
	v_mfma_f32_16x16x32_bf16 v[24:27], v[164:167], v[204:207], v[24:27]
	v_mfma_f32_16x16x32_bf16 v[12:15], v[156:159], v[212:215], v[12:15]
	v_mfma_f32_16x16x32_bf16 v[8:11], v[164:167], v[212:215], v[8:11]
	s_setprio 0
	s_setprio 1
	v_mfma_f32_16x16x32_bf16 v[52:55], v[168:171], v[184:187], 0
	v_mfma_f32_16x16x32_bf16 v[48:51], v[176:179], v[184:187], 0
	v_mfma_f32_16x16x32_bf16 v[36:39], v[168:171], v[192:195], 0
	v_mfma_f32_16x16x32_bf16 v[32:35], v[176:179], v[192:195], 0
	v_mfma_f32_16x16x32_bf16 v[20:23], v[168:171], v[200:203], 0
	v_mfma_f32_16x16x32_bf16 v[16:19], v[176:179], v[200:203], 0
	v_mfma_f32_16x16x32_bf16 v[4:7], v[168:171], v[208:211], 0
	v_mfma_f32_16x16x32_bf16 v[0:3], v[176:179], v[208:211], 0
	v_mfma_f32_16x16x32_bf16 v[52:55], v[172:175], v[188:191], v[52:55]
	v_mfma_f32_16x16x32_bf16 v[48:51], v[180:183], v[188:191], v[48:51]
	v_mfma_f32_16x16x32_bf16 v[36:39], v[172:175], v[196:199], v[36:39]
	v_mfma_f32_16x16x32_bf16 v[32:35], v[180:183], v[196:199], v[32:35]
	v_mfma_f32_16x16x32_bf16 v[20:23], v[172:175], v[204:207], v[20:23]
	v_mfma_f32_16x16x32_bf16 v[16:19], v[180:183], v[204:207], v[16:19]
	v_mfma_f32_16x16x32_bf16 v[4:7], v[172:175], v[212:215], v[4:7]
	v_mfma_f32_16x16x32_bf16 v[0:3], v[180:183], v[212:215], v[0:3]
	s_setprio 0
	s_barrier
; #define PG8_STAGE(bufoff, gbase, voff) do { _Pragma("unroll") for (int _i = 0; _i < 2; ++_i) \
;         __builtin_amdgcn_global_load_lds((const unsigned*)((const char*)(gbase) + (voff)[_i]), (PG8_LAS unsigned*)(lds + (bufoff) + ldsw + _i * 8192), 16, 0, 0); } while (0)
; #define PG8_LDA(dst, b, h) do { _Pragma("unroll") for (int m = 0; m < 4; ++m) _Pragma("unroll") for (int k = 0; k < 2; ++k) dst[m][k] = *(const PG8_LAS bf16x8*)(lds + PG8_SA(b, h) + aoff + m * 2048 + k * 1024); } while (0)
; #define PG8_LDB(dst, b, h) do { _Pragma("unroll") for (int n = 0; n < 2; ++n) _Pragma("unroll") for (int k = 0; k < 2; ++k) dst[n][k] = *(const PG8_LAS bf16x8*)(lds + PG8_SB(b, h) + boff + n * 2048 + k * 1024); } while (0)
; #define PG8_MMA(ai, bj, At, Bt) do { __builtin_amdgcn_s_setprio(1); _Pragma("unroll") for (int m = 0; m < 4; ++m) _Pragma("unroll") for (int n = 0; n < 2; ++n) _Pragma("unroll") for (int k = 0; k < 2; ++k) \
;         acc[ai][bj][m][n] = __builtin_amdgcn_mfma_f32_16x16x32_bf16(Bt[n][k], At[m][k], acc[ai][bj][m][n], 0, 0, 0); __builtin_amdgcn_s_setprio(0); } while (0)
; #define PG8_WAIT_V(n) asm volatile("s_waitcnt vmcnt(" #n ")" ::: "memory")
; #define PG8_WAIT_L(n) asm volatile("s_waitcnt lgkmcnt(" #n ")" ::: "memory")
; #define PG8_BAR __builtin_amdgcn_s_barrier()
; #define PG8_SCHED __builtin_amdgcn_sched_barrier(0)
; template <class Epi, class Sched, bool ALIGN_EPI = false, bool SP2 = false>
; __device__ __forceinline__ void gemm_phase(PG8_LAS unsigned char* lds, const Gemm g, const Sched& S, const Epi& E) {
;     ...
;             PG8_LDB(B0, 1, 0); PG8_LDB(B1, 1, 1); PG8_SCHED; PG8_LDA(At, 1, 0); PG8_STAGE(PG8_SA(0, 1), a2 + hstep, voffA);
;             PG8_WAIT_V(8); PG8_WAIT_L(0); PG8_BAR; PG8_MMA(0, 0, At, B0); PG8_MMA(0, 1, At, B1); PG8_BAR; PG8_SCHED;
	s_add_i32 s55, 0, 0x18000
	v_add_u32_e32 v151, s55, v145
	s_add_i32 s56, 0, 0x1c000
	ds_read_b128 v[152:155], v151
	ds_read_b128 v[156:159], v151 offset:1024
	ds_read_b128 v[160:163], v151 offset:2048
	ds_read_b128 v[164:167], v151 offset:3072
	v_add_u32_e32 v151, s56, v145
	ds_read_b128 v[168:171], v151
	ds_read_b128 v[172:175], v151 offset:1024
	ds_read_b128 v[176:179], v151 offset:2048
	ds_read_b128 v[180:183], v151 offset:3072
	s_add_u32 s28, s28, 0x40000
	s_addc_u32 s29, s29, 0
	s_mov_b32 m0, s40
	v_lshl_add_u64 v[224:225], s[28:29], 0, v[134:135]
	ds_read_b128 v[184:187], v150 offset:32768
	ds_read_b128 v[188:191], v150 offset:33792
	ds_read_b128 v[192:195], v150 offset:34816
	ds_read_b128 v[196:199], v150 offset:35840
	ds_read_b128 v[200:203], v150 offset:36864
	ds_read_b128 v[204:207], v150 offset:37888
	ds_read_b128 v[208:211], v150 offset:38912
	ds_read_b128 v[212:215], v150 offset:39936
	global_load_lds_dwordx4 v[224:225], off
	v_lshl_add_u64 v[224:225], s[28:29], 0, v[130:131]
	s_mov_b32 m0, s41
	s_nop 0
	global_load_lds_dwordx4 v[224:225], off
	s_waitcnt vmcnt(8)
	s_waitcnt lgkmcnt(0)
	s_barrier
	s_setprio 1
	s_waitcnt lgkmcnt(0)
	v_mfma_f32_16x16x32_bf16 v[124:127], v[152:155], v[184:187], v[124:127]
	v_mfma_f32_16x16x32_bf16 v[120:123], v[160:163], v[184:187], v[120:123]
	v_mfma_f32_16x16x32_bf16 v[108:111], v[152:155], v[192:195], v[108:111]
	v_mfma_f32_16x16x32_bf16 v[104:107], v[160:163], v[192:195], v[104:107]
	v_mfma_f32_16x16x32_bf16 v[92:95], v[152:155], v[200:203], v[92:95]
	v_mfma_f32_16x16x32_bf16 v[88:91], v[160:163], v[200:203], v[88:91]
	v_mfma_f32_16x16x32_bf16 v[76:79], v[152:155], v[208:211], v[76:79]
	v_mfma_f32_16x16x32_bf16 v[72:75], v[160:163], v[208:211], v[72:75]
	v_mfma_f32_16x16x32_bf16 v[124:127], v[156:159], v[188:191], v[124:127]
	v_mfma_f32_16x16x32_bf16 v[120:123], v[164:167], v[188:191], v[120:123]
	v_mfma_f32_16x16x32_bf16 v[108:111], v[156:159], v[196:199], v[108:111]
	v_mfma_f32_16x16x32_bf16 v[104:107], v[164:167], v[196:199], v[104:107]
	v_mfma_f32_16x16x32_bf16 v[92:95], v[156:159], v[204:207], v[92:95]
	v_mfma_f32_16x16x32_bf16 v[88:91], v[164:167], v[204:207], v[88:91]
	v_mfma_f32_16x16x32_bf16 v[76:79], v[156:159], v[212:215], v[76:79]
	v_mfma_f32_16x16x32_bf16 v[72:75], v[164:167], v[212:215], v[72:75]
	s_setprio 0
	s_setprio 1
	v_mfma_f32_16x16x32_bf16 v[116:119], v[168:171], v[184:187], v[116:119]
	v_mfma_f32_16x16x32_bf16 v[112:115], v[176:179], v[184:187], v[112:115]
	v_mfma_f32_16x16x32_bf16 v[100:103], v[168:171], v[192:195], v[100:103]
	v_mfma_f32_16x16x32_bf16 v[96:99], v[176:179], v[192:195], v[96:99]
	v_mfma_f32_16x16x32_bf16 v[84:87], v[168:171], v[200:203], v[84:87]
	v_mfma_f32_16x16x32_bf16 v[80:83], v[176:179], v[200:203], v[80:83]
	v_mfma_f32_16x16x32_bf16 v[68:71], v[168:171], v[208:211], v[68:71]
	v_mfma_f32_16x16x32_bf16 v[64:67], v[176:179], v[208:211], v[64:67]
	v_mfma_f32_16x16x32_bf16 v[116:119], v[172:175], v[188:191], v[116:119]
	v_mfma_f32_16x16x32_bf16 v[112:115], v[180:183], v[188:191], v[112:115]
	v_mfma_f32_16x16x32_bf16 v[100:103], v[172:175], v[196:199], v[100:103]
	v_mfma_f32_16x16x32_bf16 v[96:99], v[180:183], v[196:199], v[96:99]
	v_mfma_f32_16x16x32_bf16 v[84:87], v[172:175], v[204:207], v[84:87]
	v_mfma_f32_16x16x32_bf16 v[80:83], v[180:183], v[204:207], v[80:83]
	v_mfma_f32_16x16x32_bf16 v[68:71], v[172:175], v[212:215], v[68:71]
	v_mfma_f32_16x16x32_bf16 v[64:67], v[180:183], v[212:215], v[64:67]
	s_setprio 0
	s_barrier
; #define PG8_STAGE(bufoff, gbase, voff) do { _Pragma("unroll") for (int _i = 0; _i < 2; ++_i) \
;         __builtin_amdgcn_global_load_lds((const unsigned*)((const char*)(gbase) + (voff)[_i]), (PG8_LAS unsigned*)(lds + (bufoff) + ldsw + _i * 8192), 16, 0, 0); } while (0)
; #define PG8_LDA(dst, b, h) do { _Pragma("unroll") for (int m = 0; m < 4; ++m) _Pragma("unroll") for (int k = 0; k < 2; ++k) dst[m][k] = *(const PG8_LAS bf16x8*)(lds + PG8_SA(b, h) + aoff + m * 2048 + k * 1024); } while (0)
; #define PG8_MMA(ai, bj, At, Bt) do { __builtin_amdgcn_s_setprio(1); _Pragma("unroll") for (int m = 0; m < 4; ++m) _Pragma("unroll") for (int n = 0; n < 2; ++n) _Pragma("unroll") for (int k = 0; k < 2; ++k) \
;         acc[ai][bj][m][n] = __builtin_amdgcn_mfma_f32_16x16x32_bf16(Bt[n][k], At[m][k], acc[ai][bj][m][n], 0, 0, 0); __builtin_amdgcn_s_setprio(0); } while (0)
; #define PG8_WAIT_V(n) asm volatile("s_waitcnt vmcnt(" #n ")" ::: "memory")
; #define PG8_WAIT_L(n) asm volatile("s_waitcnt lgkmcnt(" #n ")" ::: "memory")
; #define PG8_BAR __builtin_amdgcn_s_barrier()
; #define PG8_SCHED __builtin_amdgcn_sched_barrier(0)
; template <class Epi, class Sched, bool ALIGN_EPI = false, bool SP2 = false>
; __device__ __forceinline__ void gemm_phase(PG8_LAS unsigned char* lds, const Gemm g, const Sched& S, const Epi& E) {
;     ...
;             PG8_LDA(At, 1, 1); PG8_STAGE(PG8_SB(1, 0), b3, voffB); PG8_STAGE(PG8_SB(1, 1), b3 + hstep, voffB); PG8_STAGE(PG8_SA(1, 0), a3, voffA);
;             PG8_WAIT_V(8); PG8_WAIT_L(0); PG8_BAR; PG8_MMA(1, 0, At, B0); PG8_MMA(1, 1, At, B1); PG8_BAR; PG8_SCHED;
	s_add_i32 s28, s55, s33
	v_lshl_add_u64 v[216:217], v[216:217], 0, s[8:9]
	s_mov_b32 m0, s28
	ds_read_b128 v[184:187], v150 offset:49152
	ds_read_b128 v[188:191], v150 offset:50176
	ds_read_b128 v[192:195], v150 offset:51200
	ds_read_b128 v[196:199], v150 offset:52224
	ds_read_b128 v[200:203], v150 offset:53248
	ds_read_b128 v[204:207], v150 offset:54272
	ds_read_b128 v[208:211], v150 offset:55296
	ds_read_b128 v[212:215], v150 offset:56320
	global_load_lds_dwordx4 v[216:217], off
	s_add_i32 m0, s28, 0x2000
	s_add_u32 s26, s26, 0x40080
	v_lshl_add_u64 v[216:217], v[218:219], 0, s[8:9]
	s_addc_u32 s27, s27, 0
	s_add_i32 s28, s56, s33
	global_load_lds_dwordx4 v[216:217], off
	v_lshl_add_u64 v[216:217], s[26:27], 0, v[132:133]
	s_mov_b32 m0, s28
	s_nop 0
	global_load_lds_dwordx4 v[216:217], off
	v_lshl_add_u64 v[216:217], s[26:27], 0, v[128:129]
	s_add_i32 m0, s28, 0x2000
	s_nop 0
	global_load_lds_dwordx4 v[216:217], off
	v_lshl_add_u64 v[216:217], v[220:221], 0, s[8:9]
	s_mov_b32 m0, s42
	s_nop 0
	global_load_lds_dwordx4 v[216:217], off
	v_lshl_add_u64 v[216:217], v[222:223], 0, s[8:9]
	s_mov_b32 m0, s43
	s_nop 0
	global_load_lds_dwordx4 v[216:217], off
	s_waitcnt vmcnt(8)
	s_waitcnt lgkmcnt(0)
	s_barrier
	s_setprio 1
	s_waitcnt lgkmcnt(0)
	v_mfma_f32_16x16x32_bf16 v[60:63], v[152:155], v[184:187], v[60:63]
	v_mfma_f32_16x16x32_bf16 v[56:59], v[160:163], v[184:187], v[56:59]
	v_mfma_f32_16x16x32_bf16 v[44:47], v[152:155], v[192:195], v[44:47]
	v_mfma_f32_16x16x32_bf16 v[40:43], v[160:163], v[192:195], v[40:43]
	v_mfma_f32_16x16x32_bf16 v[28:31], v[152:155], v[200:203], v[28:31]
	v_mfma_f32_16x16x32_bf16 v[24:27], v[160:163], v[200:203], v[24:27]
	v_mfma_f32_16x16x32_bf16 v[12:15], v[152:155], v[208:211], v[12:15]
	v_mfma_f32_16x16x32_bf16 v[8:11], v[160:163], v[208:211], v[8:11]
	v_mfma_f32_16x16x32_bf16 v[60:63], v[156:159], v[188:191], v[60:63]
	v_mfma_f32_16x16x32_bf16 v[56:59], v[164:167], v[188:191], v[56:59]
	v_mfma_f32_16x16x32_bf16 v[44:47], v[156:159], v[196:199], v[44:47]
	v_mfma_f32_16x16x32_bf16 v[40:43], v[164:167], v[196:199], v[40:43]
	v_mfma_f32_16x16x32_bf16 v[28:31], v[156:159], v[204:207], v[28:31]
	v_mfma_f32_16x16x32_bf16 v[24:27], v[164:167], v[204:207], v[24:27]
	v_mfma_f32_16x16x32_bf16 v[12:15], v[156:159], v[212:215], v[12:15]
	v_mfma_f32_16x16x32_bf16 v[8:11], v[164:167], v[212:215], v[8:11]
	s_setprio 0
	s_setprio 1
	v_mfma_f32_16x16x32_bf16 v[52:55], v[168:171], v[184:187], v[52:55]
	v_mfma_f32_16x16x32_bf16 v[48:51], v[176:179], v[184:187], v[48:51]
	v_mfma_f32_16x16x32_bf16 v[36:39], v[168:171], v[192:195], v[36:39]
	v_mfma_f32_16x16x32_bf16 v[32:35], v[176:179], v[192:195], v[32:35]
	v_mfma_f32_16x16x32_bf16 v[20:23], v[168:171], v[200:203], v[20:23]
	v_mfma_f32_16x16x32_bf16 v[16:19], v[176:179], v[200:203], v[16:19]
	v_mfma_f32_16x16x32_bf16 v[4:7], v[168:171], v[208:211], v[4:7]
	v_mfma_f32_16x16x32_bf16 v[0:3], v[176:179], v[208:211], v[0:3]
	v_mfma_f32_16x16x32_bf16 v[52:55], v[172:175], v[188:191], v[52:55]
	v_mfma_f32_16x16x32_bf16 v[48:51], v[180:183], v[188:191], v[48:51]
	v_mfma_f32_16x16x32_bf16 v[36:39], v[172:175], v[196:199], v[36:39]
	v_mfma_f32_16x16x32_bf16 v[32:35], v[180:183], v[196:199], v[32:35]
	v_mfma_f32_16x16x32_bf16 v[20:23], v[172:175], v[204:207], v[20:23]
	v_mfma_f32_16x16x32_bf16 v[16:19], v[180:183], v[204:207], v[16:19]
	v_mfma_f32_16x16x32_bf16 v[4:7], v[172:175], v[212:215], v[4:7]
	v_mfma_f32_16x16x32_bf16 v[0:3], v[180:183], v[212:215], v[0:3]
	s_setprio 0
	s_barrier
	s_add_i32 s54, s54, 2
	s_add_u32 s24, s24, 0x100
	s_addc_u32 s25, s25, 0
	s_add_u32 s52, s52, 0x100
	s_addc_u32 s53, s53, 0
	s_cmp_gt_u32 s54, 13

; #define PG8_STAGE(bufoff, gbase, voff) do { _Pragma("unroll") for (int _i = 0; _i < 2; ++_i) \
;         __builtin_amdgcn_global_load_lds((const unsigned*)((const char*)(gbase) + (voff)[_i]), (PG8_LAS unsigned*)(lds + (bufoff) + ldsw + _i * 8192), 16, 0, 0); } while (0)
; #define PG8_LDA(dst, b, h) do { _Pragma("unroll") for (int m = 0; m < 4; ++m) _Pragma("unroll") for (int k = 0; k < 2; ++k) dst[m][k] = *(const PG8_LAS bf16x8*)(lds + PG8_SA(b, h) + aoff + m * 2048 + k * 1024); } while (0)
; #define PG8_LDB(dst, b, h) do { _Pragma("unroll") for (int n = 0; n < 2; ++n) _Pragma("unroll") for (int k = 0; k < 2; ++k) dst[n][k] = *(const PG8_LAS bf16x8*)(lds + PG8_SB(b, h) + boff + n * 2048 + k * 1024); } while (0)
; #define PG8_MMA(ai, bj, At, Bt) do { __builtin_amdgcn_s_setprio(1); _Pragma("unroll") for (int m = 0; m < 4; ++m) _Pragma("unroll") for (int n = 0; n < 2; ++n) _Pragma("unroll") for (int k = 0; k < 2; ++k) \
;         acc[ai][bj][m][n] = __builtin_amdgcn_mfma_f32_16x16x32_bf16(Bt[n][k], At[m][k], acc[ai][bj][m][n], 0, 0, 0); __builtin_amdgcn_s_setprio(0); } while (0)
; #define PG8_WAIT_V(n) asm volatile("s_waitcnt vmcnt(" #n ")" ::: "memory")
; #define PG8_WAIT_L(n) asm volatile("s_waitcnt lgkmcnt(" #n ")" ::: "memory")
; template <class Epi, class Sched, bool ALIGN_EPI = false, bool SP2 = false>
; __device__ __forceinline__ void gemm_phase(PG8_LAS unsigned char* lds, const Gemm g, const Sched& S, const Epi& E) {
;     ...
;             const bool last = (t == nt - 2);
;             const char* a1 = cA + (size_t)(t + 1) * kstep;
;             const char* a2 = last ? nA : cA + (size_t)(t + 2) * kstep; const char* b2 = last ? nB : cB + (size_t)(t + 2) * kstep;
;             const char* a3 = a2 + kstep; const char* b3 = b2 + kstep;
;             if (last && has_next) S.a_ready(nxt, ui + 1);
;             if constexpr (SP2) {
;             PG8_LDB(B0, 0, 0); PG8_LDB(B1, 0, 1); PG8_SCHED; PG8_LDA(At, 0, 0); PG8_STAGE(PG8_SA(1, 1), a1 + hstep, voffA);
;             PG8_WAIT_V(8); PG8_WAIT_L(0); PG8_BAR; PG8_MMA(0, 0, At, B0); PG8_MMA(0, 1, At, B1); PG8_BAR; PG8_SCHED;
;             PG8_LDA(At, 0, 1); PG8_STAGE(PG8_SB(0, 0), b2, voffB); PG8_STAGE(PG8_SB(0, 1), b2 + hstep, voffB); PG8_STAGE(PG8_SA(0, 0), a2, voffA);
;             PG8_WAIT_V(8); PG8_WAIT_L(0); PG8_BAR; PG8_MMA(1, 0, At, B0); PG8_MMA(1, 1, At, B1); PG8_BAR; PG8_SCHED;
.LBB0_1129:
	s_add_u32 s24, s24, 0xb0080
	s_addc_u32 s25, s25, 0
	s_add_u32 s51, s26, 0x100
	s_addc_u32 s52, s27, 0
	s_mov_b32 s53, -2
	s_add_u32 s26, s24, 0xfff50080
	s_addc_u32 s27, s25, -1
	s_cmp_eq_u32 s53, 40
	s_cselect_b32 s29, s7, s27
	s_cselect_b32 s28, s6, s26
	s_cselect_b32 s27, s23, s52
	s_cselect_b32 s26, s22, s51
	v_lshl_add_u64 v[204:205], s[24:25], 0, v[200:201]
	s_add_i32 m0, s35, 0xc000
	global_load_lds_dwordx4 v[204:205], off
	v_lshl_add_u64 v[204:205], s[24:25], 0, v[202:203]
	s_add_i32 m0, s35, 0xe000
	s_nop 0
	global_load_lds_dwordx4 v[204:205], off
	s_waitcnt vmcnt(8)
	s_waitcnt lgkmcnt(0)
	s_barrier
	s_setprio 1
	s_waitcnt lgkmcnt(0)
	v_mfma_f32_16x16x32_bf16 v[132:135], v[120:123], v[160:163], 0
	v_mfma_f32_16x16x32_bf16 v[124:127], v[136:139], v[160:163], 0
	v_mfma_f32_16x16x32_bf16 v[108:111], v[120:123], v[168:171], 0
	v_mfma_f32_16x16x32_bf16 v[104:107], v[136:139], v[168:171], 0
	v_mfma_f32_16x16x32_bf16 v[92:95], v[120:123], v[176:179], 0
	v_mfma_f32_16x16x32_bf16 v[88:91], v[136:139], v[176:179], 0
	v_mfma_f32_16x16x32_bf16 v[76:79], v[120:123], v[184:187], 0
	v_mfma_f32_16x16x32_bf16 v[72:75], v[136:139], v[184:187], 0
	v_mfma_f32_16x16x32_bf16 v[132:135], v[128:131], v[164:167], v[132:135]
	v_mfma_f32_16x16x32_bf16 v[124:127], v[140:143], v[164:167], v[124:127]
	v_mfma_f32_16x16x32_bf16 v[108:111], v[128:131], v[172:175], v[108:111]
	v_mfma_f32_16x16x32_bf16 v[104:107], v[140:143], v[172:175], v[104:107]
	v_mfma_f32_16x16x32_bf16 v[92:95], v[128:131], v[180:183], v[92:95]
	v_mfma_f32_16x16x32_bf16 v[88:91], v[140:143], v[180:183], v[88:91]
	v_mfma_f32_16x16x32_bf16 v[76:79], v[128:131], v[188:191], v[76:79]
	v_mfma_f32_16x16x32_bf16 v[72:75], v[140:143], v[188:191], v[72:75]
	s_setprio 0
	s_setprio 1
	v_mfma_f32_16x16x32_bf16 v[116:119], v[144:147], v[160:163], 0
	v_mfma_f32_16x16x32_bf16 v[112:115], v[152:155], v[160:163], 0
	v_mfma_f32_16x16x32_bf16 v[100:103], v[144:147], v[168:171], 0
	v_mfma_f32_16x16x32_bf16 v[96:99], v[152:155], v[168:171], 0
	v_mfma_f32_16x16x32_bf16 v[84:87], v[144:147], v[176:179], 0
	v_mfma_f32_16x16x32_bf16 v[80:83], v[152:155], v[176:179], 0
	v_mfma_f32_16x16x32_bf16 v[68:71], v[144:147], v[184:187], 0
	v_mfma_f32_16x16x32_bf16 v[64:67], v[152:155], v[184:187], 0
	v_mfma_f32_16x16x32_bf16 v[116:119], v[148:151], v[164:167], v[116:119]
	v_mfma_f32_16x16x32_bf16 v[112:115], v[156:159], v[164:167], v[112:115]
	v_mfma_f32_16x16x32_bf16 v[100:103], v[148:151], v[172:175], v[100:103]
	v_mfma_f32_16x16x32_bf16 v[96:99], v[156:159], v[172:175], v[96:99]
	v_mfma_f32_16x16x32_bf16 v[84:87], v[148:151], v[180:183], v[84:87]
	v_mfma_f32_16x16x32_bf16 v[80:83], v[156:159], v[180:183], v[80:83]
	v_mfma_f32_16x16x32_bf16 v[68:71], v[148:151], v[188:191], v[68:71]
	v_mfma_f32_16x16x32_bf16 v[64:67], v[156:159], v[188:191], v[64:67]
	s_setprio 0
	s_barrier
	s_add_i32 s54, s45, s34
	v_lshl_add_u64 v[204:205], s[26:27], 0, v[194:195]
	s_mov_b32 m0, s54
	ds_read_b128 v[160:163], v247 offset:16384
	ds_read_b128 v[164:167], v247 offset:17408
	ds_read_b128 v[168:171], v247 offset:18432
	ds_read_b128 v[172:175], v247 offset:19456
	ds_read_b128 v[176:179], v247 offset:20480
	ds_read_b128 v[180:183], v247 offset:21504
	ds_read_b128 v[184:187], v247 offset:22528
	ds_read_b128 v[188:191], v247 offset:23552
	global_load_lds_dwordx4 v[204:205], off
	s_add_i32 m0, s54, 0x2000
	s_add_u32 s54, s26, 0xb0000
	v_lshl_add_u64 v[206:207], s[26:27], 0, v[198:199]
	s_addc_u32 s55, s27, 0
	s_add_i32 s56, s46, s34
	global_load_lds_dwordx4 v[206:207], off
	v_lshl_add_u64 v[208:209], s[54:55], 0, v[194:195]
	s_mov_b32 m0, s56
	v_lshl_add_u64 v[210:211], s[28:29], 0, v[196:197]
	global_load_lds_dwordx4 v[208:209], off
	v_lshl_add_u64 v[208:209], s[54:55], 0, v[198:199]
	s_add_i32 m0, s56, 0x2000
	s_nop 0
	global_load_lds_dwordx4 v[208:209], off
	v_lshl_add_u64 v[208:209], s[28:29], 0, v[192:193]
	s_mov_b32 m0, s35
	s_nop 0
	global_load_lds_dwordx4 v[208:209], off
	s_mov_b32 m0, s36
	s_nop 0
	global_load_lds_dwordx4 v[210:211], off
	s_waitcnt vmcnt(8)
	s_waitcnt lgkmcnt(0)
	s_barrier
	s_setprio 1
	s_waitcnt lgkmcnt(0)
	v_mfma_f32_16x16x32_bf16 v[60:63], v[120:123], v[160:163], 0
	v_mfma_f32_16x16x32_bf16 v[56:59], v[136:139], v[160:163], 0
	v_mfma_f32_16x16x32_bf16 v[44:47], v[120:123], v[168:171], 0
	v_mfma_f32_16x16x32_bf16 v[40:43], v[136:139], v[168:171], 0
	v_mfma_f32_16x16x32_bf16 v[28:31], v[120:123], v[176:179], 0
	v_mfma_f32_16x16x32_bf16 v[24:27], v[136:139], v[176:179], 0
	v_mfma_f32_16x16x32_bf16 v[12:15], v[120:123], v[184:187], 0
	v_mfma_f32_16x16x32_bf16 v[8:11], v[136:139], v[184:187], 0
	v_mfma_f32_16x16x32_bf16 v[60:63], v[128:131], v[164:167], v[60:63]
	v_mfma_f32_16x16x32_bf16 v[56:59], v[140:143], v[164:167], v[56:59]
	v_mfma_f32_16x16x32_bf16 v[44:47], v[128:131], v[172:175], v[44:47]
	v_mfma_f32_16x16x32_bf16 v[40:43], v[140:143], v[172:175], v[40:43]
	v_mfma_f32_16x16x32_bf16 v[28:31], v[128:131], v[180:183], v[28:31]
	v_mfma_f32_16x16x32_bf16 v[24:27], v[140:143], v[180:183], v[24:27]
	v_mfma_f32_16x16x32_bf16 v[12:15], v[128:131], v[188:191], v[12:15]
	v_mfma_f32_16x16x32_bf16 v[8:11], v[140:143], v[188:191], v[8:11]
	s_setprio 0
	s_setprio 1
	v_mfma_f32_16x16x32_bf16 v[52:55], v[144:147], v[160:163], 0
	v_mfma_f32_16x16x32_bf16 v[48:51], v[152:155], v[160:163], 0
	v_mfma_f32_16x16x32_bf16 v[36:39], v[144:147], v[168:171], 0
	v_mfma_f32_16x16x32_bf16 v[32:35], v[152:155], v[168:171], 0
	v_mfma_f32_16x16x32_bf16 v[20:23], v[144:147], v[176:179], 0
	v_mfma_f32_16x16x32_bf16 v[16:19], v[152:155], v[176:179], 0
	v_mfma_f32_16x16x32_bf16 v[4:7], v[144:147], v[184:187], 0
	v_mfma_f32_16x16x32_bf16 v[0:3], v[152:155], v[184:187], 0
	v_mfma_f32_16x16x32_bf16 v[52:55], v[148:151], v[164:167], v[52:55]
	v_mfma_f32_16x16x32_bf16 v[48:51], v[156:159], v[164:167], v[48:51]
	v_mfma_f32_16x16x32_bf16 v[36:39], v[148:151], v[172:175], v[36:39]
	v_mfma_f32_16x16x32_bf16 v[32:35], v[156:159], v[172:175], v[32:35]
	v_mfma_f32_16x16x32_bf16 v[20:23], v[148:151], v[180:183], v[20:23]
	v_mfma_f32_16x16x32_bf16 v[16:19], v[156:159], v[180:183], v[16:19]
	v_mfma_f32_16x16x32_bf16 v[4:7], v[148:151], v[188:191], v[4:7]
	v_mfma_f32_16x16x32_bf16 v[0:3], v[156:159], v[188:191], v[0:3]
	s_setprio 0
	s_barrier
; #define PG8_STAGE(bufoff, gbase, voff) do { _Pragma("unroll") for (int _i = 0; _i < 2; ++_i) \
;         __builtin_amdgcn_global_load_lds((const unsigned*)((const char*)(gbase) + (voff)[_i]), (PG8_LAS unsigned*)(lds + (bufoff) + ldsw + _i * 8192), 16, 0, 0); } while (0)
; #define PG8_LDA(dst, b, h) do { _Pragma("unroll") for (int m = 0; m < 4; ++m) _Pragma("unroll") for (int k = 0; k < 2; ++k) dst[m][k] = *(const PG8_LAS bf16x8*)(lds + PG8_SA(b, h) + aoff + m * 2048 + k * 1024); } while (0)
; #define PG8_LDB(dst, b, h) do { _Pragma("unroll") for (int n = 0; n < 2; ++n) _Pragma("unroll") for (int k = 0; k < 2; ++k) dst[n][k] = *(const PG8_LAS bf16x8*)(lds + PG8_SB(b, h) + boff + n * 2048 + k * 1024); } while (0)
; #define PG8_MMA(ai, bj, At, Bt) do { __builtin_amdgcn_s_setprio(1); _Pragma("unroll") for (int m = 0; m < 4; ++m) _Pragma("unroll") for (int n = 0; n < 2; ++n) _Pragma("unroll") for (int k = 0; k < 2; ++k) \
;         acc[ai][bj][m][n] = __builtin_amdgcn_mfma_f32_16x16x32_bf16(Bt[n][k], At[m][k], acc[ai][bj][m][n], 0, 0, 0); __builtin_amdgcn_s_setprio(0); } while (0)
; #define PG8_WAIT_V(n) asm volatile("s_waitcnt vmcnt(" #n ")" ::: "memory")
; #define PG8_WAIT_L(n) asm volatile("s_waitcnt lgkmcnt(" #n ")" ::: "memory")
; #define PG8_BAR __builtin_amdgcn_s_barrier()
; #define PG8_SCHED __builtin_amdgcn_sched_barrier(0)
; template <class Epi, class Sched, bool ALIGN_EPI = false, bool SP2 = false>
; __device__ __forceinline__ void gemm_phase(PG8_LAS unsigned char* lds, const Gemm g, const Sched& S, const Epi& E) {
;     ...
;             PG8_LDB(B0, 1, 0); PG8_LDB(B1, 1, 1); PG8_SCHED; PG8_LDA(At, 1, 0); PG8_STAGE(PG8_SA(0, 1), a2 + hstep, voffA);
;             PG8_WAIT_V(8); PG8_WAIT_L(0); PG8_BAR; PG8_MMA(0, 0, At, B0); PG8_MMA(0, 1, At, B1); PG8_BAR; PG8_SCHED;
	s_add_i32 s54, 0, 0x18000
	s_add_i32 s55, 0, 0x1c000
	v_add_u32_e32 v140, s54, v243
	v_add_u32_e32 v156, s55, v243
	ds_read_b128 v[120:123], v140
	ds_read_b128 v[128:131], v140 offset:1024
	ds_read_b128 v[136:139], v140 offset:2048
	ds_read_b128 v[140:143], v140 offset:3072
	ds_read_b128 v[144:147], v156
	ds_read_b128 v[148:151], v156 offset:1024
	ds_read_b128 v[152:155], v156 offset:2048
	ds_read_b128 v[156:159], v156 offset:3072
	s_add_u32 s28, s28, 0xb0000
	s_addc_u32 s29, s29, 0
	s_mov_b32 m0, s37
	v_lshl_add_u64 v[212:213], s[28:29], 0, v[192:193]
	ds_read_b128 v[160:163], v247 offset:32768
	ds_read_b128 v[164:167], v247 offset:33792
	ds_read_b128 v[168:171], v247 offset:34816
	ds_read_b128 v[172:175], v247 offset:35840
	ds_read_b128 v[176:179], v247 offset:36864
	ds_read_b128 v[180:183], v247 offset:37888
	ds_read_b128 v[184:187], v247 offset:38912
	ds_read_b128 v[188:191], v247 offset:39936
	global_load_lds_dwordx4 v[212:213], off
	v_lshl_add_u64 v[212:213], s[28:29], 0, v[196:197]
	s_mov_b32 m0, s38
	s_nop 0
	global_load_lds_dwordx4 v[212:213], off
	s_waitcnt vmcnt(8)
	s_waitcnt lgkmcnt(0)
	s_barrier
	s_setprio 1
	s_waitcnt lgkmcnt(0)
	v_mfma_f32_16x16x32_bf16 v[132:135], v[120:123], v[160:163], v[132:135]
	v_mfma_f32_16x16x32_bf16 v[124:127], v[136:139], v[160:163], v[124:127]
	v_mfma_f32_16x16x32_bf16 v[108:111], v[120:123], v[168:171], v[108:111]
	v_mfma_f32_16x16x32_bf16 v[104:107], v[136:139], v[168:171], v[104:107]
	v_mfma_f32_16x16x32_bf16 v[92:95], v[120:123], v[176:179], v[92:95]
	v_mfma_f32_16x16x32_bf16 v[88:91], v[136:139], v[176:179], v[88:91]
	v_mfma_f32_16x16x32_bf16 v[76:79], v[120:123], v[184:187], v[76:79]
	v_mfma_f32_16x16x32_bf16 v[72:75], v[136:139], v[184:187], v[72:75]
	v_mfma_f32_16x16x32_bf16 v[132:135], v[128:131], v[164:167], v[132:135]
	v_mfma_f32_16x16x32_bf16 v[124:127], v[140:143], v[164:167], v[124:127]
	v_mfma_f32_16x16x32_bf16 v[108:111], v[128:131], v[172:175], v[108:111]
	v_mfma_f32_16x16x32_bf16 v[104:107], v[140:143], v[172:175], v[104:107]
	v_mfma_f32_16x16x32_bf16 v[92:95], v[128:131], v[180:183], v[92:95]
	v_mfma_f32_16x16x32_bf16 v[88:91], v[140:143], v[180:183], v[88:91]
	v_mfma_f32_16x16x32_bf16 v[76:79], v[128:131], v[188:191], v[76:79]
	v_mfma_f32_16x16x32_bf16 v[72:75], v[140:143], v[188:191], v[72:75]
	s_setprio 0
	s_setprio 1
	v_mfma_f32_16x16x32_bf16 v[116:119], v[144:147], v[160:163], v[116:119]
	v_mfma_f32_16x16x32_bf16 v[112:115], v[152:155], v[160:163], v[112:115]
	v_mfma_f32_16x16x32_bf16 v[100:103], v[144:147], v[168:171], v[100:103]
	v_mfma_f32_16x16x32_bf16 v[96:99], v[152:155], v[168:171], v[96:99]
	v_mfma_f32_16x16x32_bf16 v[84:87], v[144:147], v[176:179], v[84:87]
	v_mfma_f32_16x16x32_bf16 v[80:83], v[152:155], v[176:179], v[80:83]
	v_mfma_f32_16x16x32_bf16 v[68:71], v[144:147], v[184:187], v[68:71]
	v_mfma_f32_16x16x32_bf16 v[64:67], v[152:155], v[184:187], v[64:67]
	v_mfma_f32_16x16x32_bf16 v[116:119], v[148:151], v[164:167], v[116:119]
	v_mfma_f32_16x16x32_bf16 v[112:115], v[156:159], v[164:167], v[112:115]
	v_mfma_f32_16x16x32_bf16 v[100:103], v[148:151], v[172:175], v[100:103]
	v_mfma_f32_16x16x32_bf16 v[96:99], v[156:159], v[172:175], v[96:99]
	v_mfma_f32_16x16x32_bf16 v[84:87], v[148:151], v[180:183], v[84:87]
	v_mfma_f32_16x16x32_bf16 v[80:83], v[156:159], v[180:183], v[80:83]
	v_mfma_f32_16x16x32_bf16 v[68:71], v[148:151], v[188:191], v[68:71]
	v_mfma_f32_16x16x32_bf16 v[64:67], v[156:159], v[188:191], v[64:67]
	s_setprio 0
	s_barrier
; #define PG8_STAGE(bufoff, gbase, voff) do { _Pragma("unroll") for (int _i = 0; _i < 2; ++_i) \
;         __builtin_amdgcn_global_load_lds((const unsigned*)((const char*)(gbase) + (voff)[_i]), (PG8_LAS unsigned*)(lds + (bufoff) + ldsw + _i * 8192), 16, 0, 0); } while (0)
; #define PG8_LDA(dst, b, h) do { _Pragma("unroll") for (int m = 0; m < 4; ++m) _Pragma("unroll") for (int k = 0; k < 2; ++k) dst[m][k] = *(const PG8_LAS bf16x8*)(lds + PG8_SA(b, h) + aoff + m * 2048 + k * 1024); } while (0)
; #define PG8_MMA(ai, bj, At, Bt) do { __builtin_amdgcn_s_setprio(1); _Pragma("unroll") for (int m = 0; m < 4; ++m) _Pragma("unroll") for (int n = 0; n < 2; ++n) _Pragma("unroll") for (int k = 0; k < 2; ++k) \
;         acc[ai][bj][m][n] = __builtin_amdgcn_mfma_f32_16x16x32_bf16(Bt[n][k], At[m][k], acc[ai][bj][m][n], 0, 0, 0); __builtin_amdgcn_s_setprio(0); } while (0)
; #define PG8_WAIT_V(n) asm volatile("s_waitcnt vmcnt(" #n ")" ::: "memory")
; #define PG8_WAIT_L(n) asm volatile("s_waitcnt lgkmcnt(" #n ")" ::: "memory")
; #define PG8_BAR __builtin_amdgcn_s_barrier()
; #define PG8_SCHED __builtin_amdgcn_sched_barrier(0)
; template <class Epi, class Sched, bool ALIGN_EPI = false, bool SP2 = false>
; __device__ __forceinline__ void gemm_phase(PG8_LAS unsigned char* lds, const Gemm g, const Sched& S, const Epi& E) {
;     ...
;             PG8_LDA(At, 1, 1); PG8_STAGE(PG8_SB(1, 0), b3, voffB); PG8_STAGE(PG8_SB(1, 1), b3 + hstep, voffB); PG8_STAGE(PG8_SA(1, 0), a3, voffA);
;             PG8_WAIT_V(8); PG8_WAIT_L(0); PG8_BAR; PG8_MMA(1, 0, At, B0); PG8_MMA(1, 1, At, B1); PG8_BAR; PG8_SCHED;
	s_add_i32 s28, s54, s34
	v_lshl_add_u64 v[204:205], v[204:205], 0, s[18:19]
	s_mov_b32 m0, s28
	ds_read_b128 v[160:163], v247 offset:49152
	ds_read_b128 v[164:167], v247 offset:50176
	ds_read_b128 v[168:171], v247 offset:51200
	ds_read_b128 v[172:175], v247 offset:52224
	ds_read_b128 v[176:179], v247 offset:53248
	ds_read_b128 v[180:183], v247 offset:54272
	ds_read_b128 v[184:187], v247 offset:55296
	ds_read_b128 v[188:191], v247 offset:56320
	global_load_lds_dwordx4 v[204:205], off
	s_add_i32 m0, s28, 0x2000
	s_add_u32 s26, s26, 0xb0080
	v_lshl_add_u64 v[204:205], v[206:207], 0, s[18:19]
	s_addc_u32 s27, s27, 0
	s_add_i32 s28, s55, s34
	global_load_lds_dwordx4 v[204:205], off
	v_lshl_add_u64 v[204:205], s[26:27], 0, v[194:195]
	s_mov_b32 m0, s28
	s_nop 0
	global_load_lds_dwordx4 v[204:205], off
	v_lshl_add_u64 v[204:205], s[26:27], 0, v[198:199]
	s_add_i32 m0, s28, 0x2000
	s_nop 0
	global_load_lds_dwordx4 v[204:205], off
	v_lshl_add_u64 v[204:205], v[208:209], 0, s[18:19]
	s_mov_b32 m0, s40
	s_nop 0
	global_load_lds_dwordx4 v[204:205], off
	v_lshl_add_u64 v[204:205], v[210:211], 0, s[18:19]
	s_mov_b32 m0, s41
	s_nop 0
	global_load_lds_dwordx4 v[204:205], off
	s_waitcnt vmcnt(8)
	s_waitcnt lgkmcnt(0)
	s_barrier
	s_setprio 1
	s_waitcnt lgkmcnt(0)
	v_mfma_f32_16x16x32_bf16 v[60:63], v[120:123], v[160:163], v[60:63]
	v_mfma_f32_16x16x32_bf16 v[56:59], v[136:139], v[160:163], v[56:59]
	v_mfma_f32_16x16x32_bf16 v[44:47], v[120:123], v[168:171], v[44:47]
	v_mfma_f32_16x16x32_bf16 v[40:43], v[136:139], v[168:171], v[40:43]
	v_mfma_f32_16x16x32_bf16 v[28:31], v[120:123], v[176:179], v[28:31]
	v_mfma_f32_16x16x32_bf16 v[24:27], v[136:139], v[176:179], v[24:27]
	v_mfma_f32_16x16x32_bf16 v[12:15], v[120:123], v[184:187], v[12:15]
	v_mfma_f32_16x16x32_bf16 v[8:11], v[136:139], v[184:187], v[8:11]
	v_mfma_f32_16x16x32_bf16 v[60:63], v[128:131], v[164:167], v[60:63]
	v_mfma_f32_16x16x32_bf16 v[56:59], v[140:143], v[164:167], v[56:59]
	v_mfma_f32_16x16x32_bf16 v[44:47], v[128:131], v[172:175], v[44:47]
	v_mfma_f32_16x16x32_bf16 v[40:43], v[140:143], v[172:175], v[40:43]
	v_mfma_f32_16x16x32_bf16 v[28:31], v[128:131], v[180:183], v[28:31]
	v_mfma_f32_16x16x32_bf16 v[24:27], v[140:143], v[180:183], v[24:27]
	v_mfma_f32_16x16x32_bf16 v[12:15], v[128:131], v[188:191], v[12:15]
	v_mfma_f32_16x16x32_bf16 v[8:11], v[140:143], v[188:191], v[8:11]
	s_setprio 0
	s_setprio 1
	v_mfma_f32_16x16x32_bf16 v[52:55], v[144:147], v[160:163], v[52:55]
	v_mfma_f32_16x16x32_bf16 v[48:51], v[152:155], v[160:163], v[48:51]
	v_mfma_f32_16x16x32_bf16 v[36:39], v[144:147], v[168:171], v[36:39]
	v_mfma_f32_16x16x32_bf16 v[32:35], v[152:155], v[168:171], v[32:35]
	v_mfma_f32_16x16x32_bf16 v[20:23], v[144:147], v[176:179], v[20:23]
	v_mfma_f32_16x16x32_bf16 v[16:19], v[152:155], v[176:179], v[16:19]
	v_mfma_f32_16x16x32_bf16 v[4:7], v[144:147], v[184:187], v[4:7]
	v_mfma_f32_16x16x32_bf16 v[0:3], v[152:155], v[184:187], v[0:3]
	v_mfma_f32_16x16x32_bf16 v[52:55], v[148:151], v[164:167], v[52:55]
	v_mfma_f32_16x16x32_bf16 v[48:51], v[156:159], v[164:167], v[48:51]
	v_mfma_f32_16x16x32_bf16 v[36:39], v[148:151], v[172:175], v[36:39]
	v_mfma_f32_16x16x32_bf16 v[32:35], v[156:159], v[172:175], v[32:35]
	v_mfma_f32_16x16x32_bf16 v[20:23], v[148:151], v[180:183], v[20:23]
	v_mfma_f32_16x16x32_bf16 v[16:19], v[156:159], v[180:183], v[16:19]
	v_mfma_f32_16x16x32_bf16 v[4:7], v[148:151], v[188:191], v[4:7]
	v_mfma_f32_16x16x32_bf16 v[0:3], v[156:159], v[188:191], v[0:3]
	s_setprio 0
	s_barrier
	s_add_i32 s53, s53, 2
	s_add_u32 s24, s24, 0x100
	s_addc_u32 s25, s25, 0
	s_add_u32 s51, s51, 0x100
	s_addc_u32 s52, s52, 0
	s_cmp_gt_u32 s53, 41

; #define PG8_STAGE(bufoff, gbase, voff) do { _Pragma("unroll") for (int _i = 0; _i < 2; ++_i) \
;         __builtin_amdgcn_global_load_lds((const unsigned*)((const char*)(gbase) + (voff)[_i]), (PG8_LAS unsigned*)(lds + (bufoff) + ldsw + _i * 8192), 16, 0, 0); } while (0)
; #define PG8_LDA(dst, b, h) do { _Pragma("unroll") for (int m = 0; m < 4; ++m) _Pragma("unroll") for (int k = 0; k < 2; ++k) dst[m][k] = *(const PG8_LAS bf16x8*)(lds + PG8_SA(b, h) + aoff + m * 2048 + k * 1024); } while (0)
; #define PG8_LDB(dst, b, h) do { _Pragma("unroll") for (int n = 0; n < 2; ++n) _Pragma("unroll") for (int k = 0; k < 2; ++k) dst[n][k] = *(const PG8_LAS bf16x8*)(lds + PG8_SB(b, h) + boff + n * 2048 + k * 1024); } while (0)
; #define PG8_WAIT_V(n) asm volatile("s_waitcnt vmcnt(" #n ")" ::: "memory")
; #define PG8_WAIT_L(n) asm volatile("s_waitcnt lgkmcnt(" #n ")" ::: "memory")
; #define PG8_BAR __builtin_amdgcn_s_barrier()
; #define PG8_SCHED __builtin_amdgcn_sched_barrier(0)
; template <class Epi, class Sched, bool ALIGN_EPI = false, bool SP2 = false>
; __device__ __forceinline__ void gemm_phase(PG8_LAS unsigned char* lds, const Gemm g, const Sched& S, const Epi& E) {
;     ...
;         const char* nA = has_next ? (const char*)g.A + (size_t)nxt.pm * tstep : cA; const char* nB = has_next ? (const char*)g.Bt + (size_t)nxt.pn * tstep : cB;
;         for (int t = 0; t < nt; t += 2) {
;             const bool last = (t == nt - 2);
;             const char* a1 = cA + (size_t)(t + 1) * kstep;
;             const char* a2 = last ? nA : cA + (size_t)(t + 2) * kstep; const char* b2 = last ? nB : cB + (size_t)(t + 2) * kstep;
;             const char* a3 = a2 + kstep; const char* b3 = b2 + kstep;
;             if (last && has_next) S.a_ready(nxt, ui + 1);
;             if constexpr (SP2) {
;             PG8_LDB(B0, 0, 0); PG8_LDB(B1, 0, 1); PG8_SCHED; PG8_LDA(At, 0, 0); PG8_STAGE(PG8_SA(1, 1), a1 + hstep, voffA);
;             PG8_WAIT_V(8); PG8_WAIT_L(0); PG8_BAR; PG8_MMA(0, 0, At, B0); PG8_MMA(0, 1, At, B1); PG8_BAR; PG8_SCHED;
;             PG8_LDA(At, 0, 1); PG8_STAGE(PG8_SB(0, 0), b2, voffB); PG8_STAGE(PG8_SB(0, 1), b2 + hstep, voffB); PG8_STAGE(PG8_SA(0, 0), a2, voffA);
;             PG8_WAIT_V(8); PG8_WAIT_L(0); PG8_BAR; PG8_MMA(1, 0, At, B0); PG8_MMA(1, 1, At, B1); PG8_BAR; PG8_SCHED;
.LBB0_1218:
	s_ashr_i32 s17, s16, 31
	s_lshl_b64 s[18:19], s[16:17], 19
	s_add_u32 s18, s36, s18
	s_addc_u32 s19, s37, s19
	s_and_b64 s[20:21], s[0:1], exec
	s_cselect_b32 s17, s19, s25
	s_cselect_b32 s50, s18, s24
	s_ashr_i32 s15, s14, 31
	s_lshl_b64 s[20:21], s[14:15], 19
	s_add_u32 s20, s34, s20
	s_addc_u32 s21, s35, s21
	s_and_b64 s[28:29], s[0:1], exec
	s_cselect_b32 s15, s21, s27
	s_cselect_b32 s51, s20, s26
	s_add_u32 s24, s24, 0x40080
	s_addc_u32 s25, s25, 0
	s_add_u32 s52, s26, 0x100
	s_addc_u32 s53, s27, 0
	s_mov_b32 s54, -2
	s_add_u32 s26, s24, 0xfffc0080
	s_addc_u32 s27, s25, -1
	s_cmp_eq_u32 s54, 12
	s_cselect_b32 s29, s17, s27
	s_cselect_b32 s28, s50, s26
	s_cselect_b32 s27, s15, s53
	s_cselect_b32 s26, s51, s52
	v_lshl_add_u64 v[216:217], s[24:25], 0, v[136:137]
	s_add_i32 m0, s23, 0xc000
	global_load_lds_dwordx4 v[216:217], off
	v_lshl_add_u64 v[216:217], s[24:25], 0, v[138:139]
	s_add_i32 m0, s23, 0xe000
	s_nop 0
	global_load_lds_dwordx4 v[216:217], off
	s_waitcnt vmcnt(8)
	s_waitcnt lgkmcnt(0)
	s_barrier
	s_setprio 1
	s_waitcnt lgkmcnt(0)
	v_mfma_f32_16x16x32_bf16 v[124:127], v[152:155], v[184:187], 0
	v_mfma_f32_16x16x32_bf16 v[120:123], v[160:163], v[184:187], 0
	v_mfma_f32_16x16x32_bf16 v[108:111], v[152:155], v[192:195], 0
	v_mfma_f32_16x16x32_bf16 v[104:107], v[160:163], v[192:195], 0
	v_mfma_f32_16x16x32_bf16 v[92:95], v[152:155], v[200:203], 0
	v_mfma_f32_16x16x32_bf16 v[88:91], v[160:163], v[200:203], 0
	v_mfma_f32_16x16x32_bf16 v[76:79], v[152:155], v[208:211], 0
	v_mfma_f32_16x16x32_bf16 v[72:75], v[160:163], v[208:211], 0
	v_mfma_f32_16x16x32_bf16 v[124:127], v[156:159], v[188:191], v[124:127]
	v_mfma_f32_16x16x32_bf16 v[120:123], v[164:167], v[188:191], v[120:123]
	v_mfma_f32_16x16x32_bf16 v[108:111], v[156:159], v[196:199], v[108:111]
	v_mfma_f32_16x16x32_bf16 v[104:107], v[164:167], v[196:199], v[104:107]
	v_mfma_f32_16x16x32_bf16 v[92:95], v[156:159], v[204:207], v[92:95]
	v_mfma_f32_16x16x32_bf16 v[88:91], v[164:167], v[204:207], v[88:91]
	v_mfma_f32_16x16x32_bf16 v[76:79], v[156:159], v[212:215], v[76:79]
	v_mfma_f32_16x16x32_bf16 v[72:75], v[164:167], v[212:215], v[72:75]
	s_setprio 0
	s_setprio 1
	v_mfma_f32_16x16x32_bf16 v[116:119], v[168:171], v[184:187], 0
	v_mfma_f32_16x16x32_bf16 v[112:115], v[176:179], v[184:187], 0
	v_mfma_f32_16x16x32_bf16 v[100:103], v[168:171], v[192:195], 0
	v_mfma_f32_16x16x32_bf16 v[96:99], v[176:179], v[192:195], 0
	v_mfma_f32_16x16x32_bf16 v[84:87], v[168:171], v[200:203], 0
	v_mfma_f32_16x16x32_bf16 v[80:83], v[176:179], v[200:203], 0
	v_mfma_f32_16x16x32_bf16 v[68:71], v[168:171], v[208:211], 0
	v_mfma_f32_16x16x32_bf16 v[64:67], v[176:179], v[208:211], 0
	v_mfma_f32_16x16x32_bf16 v[116:119], v[172:175], v[188:191], v[116:119]
	v_mfma_f32_16x16x32_bf16 v[112:115], v[180:183], v[188:191], v[112:115]
	v_mfma_f32_16x16x32_bf16 v[100:103], v[172:175], v[196:199], v[100:103]
	v_mfma_f32_16x16x32_bf16 v[96:99], v[180:183], v[196:199], v[96:99]
	v_mfma_f32_16x16x32_bf16 v[84:87], v[172:175], v[204:207], v[84:87]
	v_mfma_f32_16x16x32_bf16 v[80:83], v[180:183], v[204:207], v[80:83]
	v_mfma_f32_16x16x32_bf16 v[68:71], v[172:175], v[212:215], v[68:71]
	v_mfma_f32_16x16x32_bf16 v[64:67], v[180:183], v[212:215], v[64:67]
	s_setprio 0
	s_barrier
	s_add_i32 s55, s44, s33
	v_lshl_add_u64 v[216:217], s[26:27], 0, v[132:133]
	s_mov_b32 m0, s55
	ds_read_b128 v[184:187], v150 offset:16384
	ds_read_b128 v[188:191], v150 offset:17408
	ds_read_b128 v[192:195], v150 offset:18432
	ds_read_b128 v[196:199], v150 offset:19456
	ds_read_b128 v[200:203], v150 offset:20480
	ds_read_b128 v[204:207], v150 offset:21504
	ds_read_b128 v[208:211], v150 offset:22528
	ds_read_b128 v[212:215], v150 offset:23552
	global_load_lds_dwordx4 v[216:217], off
	s_add_i32 m0, s55, 0x2000
	s_add_u32 s56, s26, 0x40000
	v_lshl_add_u64 v[218:219], s[26:27], 0, v[128:129]
	s_addc_u32 s57, s27, 0
	s_add_i32 s55, s45, s33
	global_load_lds_dwordx4 v[218:219], off
	v_lshl_add_u64 v[220:221], s[56:57], 0, v[132:133]
	s_mov_b32 m0, s55
	v_lshl_add_u64 v[222:223], s[28:29], 0, v[130:131]
	global_load_lds_dwordx4 v[220:221], off
	v_lshl_add_u64 v[220:221], s[56:57], 0, v[128:129]
	s_add_i32 m0, s55, 0x2000
	s_nop 0
	global_load_lds_dwordx4 v[220:221], off
	v_lshl_add_u64 v[220:221], s[28:29], 0, v[134:135]
	s_mov_b32 m0, s23
	s_nop 0
	global_load_lds_dwordx4 v[220:221], off
	s_mov_b32 m0, s39
	s_nop 0
	global_load_lds_dwordx4 v[222:223], off
	s_waitcnt vmcnt(8)
	s_waitcnt lgkmcnt(0)
	s_barrier
	s_setprio 1
	s_waitcnt lgkmcnt(0)
	v_mfma_f32_16x16x32_bf16 v[60:63], v[152:155], v[184:187], 0
	v_mfma_f32_16x16x32_bf16 v[56:59], v[160:163], v[184:187], 0
	v_mfma_f32_16x16x32_bf16 v[44:47], v[152:155], v[192:195], 0
	v_mfma_f32_16x16x32_bf16 v[40:43], v[160:163], v[192:195], 0
	v_mfma_f32_16x16x32_bf16 v[28:31], v[152:155], v[200:203], 0
	v_mfma_f32_16x16x32_bf16 v[24:27], v[160:163], v[200:203], 0
	v_mfma_f32_16x16x32_bf16 v[12:15], v[152:155], v[208:211], 0
	v_mfma_f32_16x16x32_bf16 v[8:11], v[160:163], v[208:211], 0
	v_mfma_f32_16x16x32_bf16 v[60:63], v[156:159], v[188:191], v[60:63]
	v_mfma_f32_16x16x32_bf16 v[56:59], v[164:167], v[188:191], v[56:59]
	v_mfma_f32_16x16x32_bf16 v[44:47], v[156:159], v[196:199], v[44:47]
	v_mfma_f32_16x16x32_bf16 v[40:43], v[164:167], v[196:199], v[40:43]
	v_mfma_f32_16x16x32_bf16 v[28:31], v[156:159], v[204:207], v[28:31]
	v_mfma_f32_16x16x32_bf16 v[24:27], v[164:167], v[204:207], v[24:27]
	v_mfma_f32_16x16x32_bf16 v[12:15], v[156:159], v[212:215], v[12:15]
	v_mfma_f32_16x16x32_bf16 v[8:11], v[164:167], v[212:215], v[8:11]
	s_setprio 0
	s_setprio 1
	v_mfma_f32_16x16x32_bf16 v[52:55], v[168:171], v[184:187], 0
	v_mfma_f32_16x16x32_bf16 v[48:51], v[176:179], v[184:187], 0
	v_mfma_f32_16x16x32_bf16 v[36:39], v[168:171], v[192:195], 0
	v_mfma_f32_16x16x32_bf16 v[32:35], v[176:179], v[192:195], 0
	v_mfma_f32_16x16x32_bf16 v[20:23], v[168:171], v[200:203], 0
	v_mfma_f32_16x16x32_bf16 v[16:19], v[176:179], v[200:203], 0
	v_mfma_f32_16x16x32_bf16 v[4:7], v[168:171], v[208:211], 0
	v_mfma_f32_16x16x32_bf16 v[0:3], v[176:179], v[208:211], 0
	v_mfma_f32_16x16x32_bf16 v[52:55], v[172:175], v[188:191], v[52:55]
	v_mfma_f32_16x16x32_bf16 v[48:51], v[180:183], v[188:191], v[48:51]
	v_mfma_f32_16x16x32_bf16 v[36:39], v[172:175], v[196:199], v[36:39]
	v_mfma_f32_16x16x32_bf16 v[32:35], v[180:183], v[196:199], v[32:35]
	v_mfma_f32_16x16x32_bf16 v[20:23], v[172:175], v[204:207], v[20:23]
	v_mfma_f32_16x16x32_bf16 v[16:19], v[180:183], v[204:207], v[16:19]
	v_mfma_f32_16x16x32_bf16 v[4:7], v[172:175], v[212:215], v[4:7]
	v_mfma_f32_16x16x32_bf16 v[0:3], v[180:183], v[212:215], v[0:3]
	s_setprio 0
	s_barrier
; #define PG8_STAGE(bufoff, gbase, voff) do { _Pragma("unroll") for (int _i = 0; _i < 2; ++_i) \
;         __builtin_amdgcn_global_load_lds((const unsigned*)((const char*)(gbase) + (voff)[_i]), (PG8_LAS unsigned*)(lds + (bufoff) + ldsw + _i * 8192), 16, 0, 0); } while (0)
; #define PG8_LDA(dst, b, h) do { _Pragma("unroll") for (int m = 0; m < 4; ++m) _Pragma("unroll") for (int k = 0; k < 2; ++k) dst[m][k] = *(const PG8_LAS bf16x8*)(lds + PG8_SA(b, h) + aoff + m * 2048 + k * 1024); } while (0)
; #define PG8_LDB(dst, b, h) do { _Pragma("unroll") for (int n = 0; n < 2; ++n) _Pragma("unroll") for (int k = 0; k < 2; ++k) dst[n][k] = *(const PG8_LAS bf16x8*)(lds + PG8_SB(b, h) + boff + n * 2048 + k * 1024); } while (0)
; #define PG8_MMA(ai, bj, At, Bt) do { __builtin_amdgcn_s_setprio(1); _Pragma("unroll") for (int m = 0; m < 4; ++m) _Pragma("unroll") for (int n = 0; n < 2; ++n) _Pragma("unroll") for (int k = 0; k < 2; ++k) \
;         acc[ai][bj][m][n] = __builtin_amdgcn_mfma_f32_16x16x32_bf16(Bt[n][k], At[m][k], acc[ai][bj][m][n], 0, 0, 0); __builtin_amdgcn_s_setprio(0); } while (0)
; #define PG8_WAIT_V(n) asm volatile("s_waitcnt vmcnt(" #n ")" ::: "memory")
; #define PG8_WAIT_L(n) asm volatile("s_waitcnt lgkmcnt(" #n ")" ::: "memory")
; #define PG8_BAR __builtin_amdgcn_s_barrier()
; #define PG8_SCHED __builtin_amdgcn_sched_barrier(0)
; template <class Epi, class Sched, bool ALIGN_EPI = false, bool SP2 = false>
; __device__ __forceinline__ void gemm_phase(PG8_LAS unsigned char* lds, const Gemm g, const Sched& S, const Epi& E) {
;     ...
;             PG8_LDB(B0, 1, 0); PG8_LDB(B1, 1, 1); PG8_SCHED; PG8_LDA(At, 1, 0); PG8_STAGE(PG8_SA(0, 1), a2 + hstep, voffA);
;             PG8_WAIT_V(8); PG8_WAIT_L(0); PG8_BAR; PG8_MMA(0, 0, At, B0); PG8_MMA(0, 1, At, B1); PG8_BAR; PG8_SCHED;
	s_add_i32 s55, 0, 0x18000
	v_add_u32_e32 v151, s55, v145
	s_add_i32 s56, 0, 0x1c000
	ds_read_b128 v[152:155], v151
	ds_read_b128 v[156:159], v151 offset:1024
	ds_read_b128 v[160:163], v151 offset:2048
	ds_read_b128 v[164:167], v151 offset:3072
	v_add_u32_e32 v151, s56, v145
	ds_read_b128 v[168:171], v151
	ds_read_b128 v[172:175], v151 offset:1024
	ds_read_b128 v[176:179], v151 offset:2048
	ds_read_b128 v[180:183], v151 offset:3072
	s_add_u32 s28, s28, 0x40000
	s_addc_u32 s29, s29, 0
	s_mov_b32 m0, s40
	v_lshl_add_u64 v[224:225], s[28:29], 0, v[134:135]
	ds_read_b128 v[184:187], v150 offset:32768
	ds_read_b128 v[188:191], v150 offset:33792
	ds_read_b128 v[192:195], v150 offset:34816
	ds_read_b128 v[196:199], v150 offset:35840
	ds_read_b128 v[200:203], v150 offset:36864
	ds_read_b128 v[204:207], v150 offset:37888
	ds_read_b128 v[208:211], v150 offset:38912
	ds_read_b128 v[212:215], v150 offset:39936
	global_load_lds_dwordx4 v[224:225], off
	v_lshl_add_u64 v[224:225], s[28:29], 0, v[130:131]
	s_mov_b32 m0, s41
	s_nop 0
	global_load_lds_dwordx4 v[224:225], off
	s_waitcnt vmcnt(8)
	s_waitcnt lgkmcnt(0)
	s_barrier
	s_setprio 1
	s_waitcnt lgkmcnt(0)
	v_mfma_f32_16x16x32_bf16 v[124:127], v[152:155], v[184:187], v[124:127]
	v_mfma_f32_16x16x32_bf16 v[120:123], v[160:163], v[184:187], v[120:123]
	v_mfma_f32_16x16x32_bf16 v[108:111], v[152:155], v[192:195], v[108:111]
	v_mfma_f32_16x16x32_bf16 v[104:107], v[160:163], v[192:195], v[104:107]
	v_mfma_f32_16x16x32_bf16 v[92:95], v[152:155], v[200:203], v[92:95]
	v_mfma_f32_16x16x32_bf16 v[88:91], v[160:163], v[200:203], v[88:91]
	v_mfma_f32_16x16x32_bf16 v[76:79], v[152:155], v[208:211], v[76:79]
	v_mfma_f32_16x16x32_bf16 v[72:75], v[160:163], v[208:211], v[72:75]
	v_mfma_f32_16x16x32_bf16 v[124:127], v[156:159], v[188:191], v[124:127]
	v_mfma_f32_16x16x32_bf16 v[120:123], v[164:167], v[188:191], v[120:123]
	v_mfma_f32_16x16x32_bf16 v[108:111], v[156:159], v[196:199], v[108:111]
	v_mfma_f32_16x16x32_bf16 v[104:107], v[164:167], v[196:199], v[104:107]
	v_mfma_f32_16x16x32_bf16 v[92:95], v[156:159], v[204:207], v[92:95]
	v_mfma_f32_16x16x32_bf16 v[88:91], v[164:167], v[204:207], v[88:91]
	v_mfma_f32_16x16x32_bf16 v[76:79], v[156:159], v[212:215], v[76:79]
	v_mfma_f32_16x16x32_bf16 v[72:75], v[164:167], v[212:215], v[72:75]
	s_setprio 0
	s_setprio 1
	v_mfma_f32_16x16x32_bf16 v[116:119], v[168:171], v[184:187], v[116:119]
	v_mfma_f32_16x16x32_bf16 v[112:115], v[176:179], v[184:187], v[112:115]
	v_mfma_f32_16x16x32_bf16 v[100:103], v[168:171], v[192:195], v[100:103]
	v_mfma_f32_16x16x32_bf16 v[96:99], v[176:179], v[192:195], v[96:99]
	v_mfma_f32_16x16x32_bf16 v[84:87], v[168:171], v[200:203], v[84:87]
	v_mfma_f32_16x16x32_bf16 v[80:83], v[176:179], v[200:203], v[80:83]
	v_mfma_f32_16x16x32_bf16 v[68:71], v[168:171], v[208:211], v[68:71]
	v_mfma_f32_16x16x32_bf16 v[64:67], v[176:179], v[208:211], v[64:67]
	v_mfma_f32_16x16x32_bf16 v[116:119], v[172:175], v[188:191], v[116:119]
	v_mfma_f32_16x16x32_bf16 v[112:115], v[180:183], v[188:191], v[112:115]
	v_mfma_f32_16x16x32_bf16 v[100:103], v[172:175], v[196:199], v[100:103]
	v_mfma_f32_16x16x32_bf16 v[96:99], v[180:183], v[196:199], v[96:99]
	v_mfma_f32_16x16x32_bf16 v[84:87], v[172:175], v[204:207], v[84:87]
	v_mfma_f32_16x16x32_bf16 v[80:83], v[180:183], v[204:207], v[80:83]
	v_mfma_f32_16x16x32_bf16 v[68:71], v[172:175], v[212:215], v[68:71]
	v_mfma_f32_16x16x32_bf16 v[64:67], v[180:183], v[212:215], v[64:67]
	s_setprio 0
	s_barrier
; #define PG8_STAGE(bufoff, gbase, voff) do { _Pragma("unroll") for (int _i = 0; _i < 2; ++_i) \
;         __builtin_amdgcn_global_load_lds((const unsigned*)((const char*)(gbase) + (voff)[_i]), (PG8_LAS unsigned*)(lds + (bufoff) + ldsw + _i * 8192), 16, 0, 0); } while (0)
; #define PG8_LDA(dst, b, h) do { _Pragma("unroll") for (int m = 0; m < 4; ++m) _Pragma("unroll") for (int k = 0; k < 2; ++k) dst[m][k] = *(const PG8_LAS bf16x8*)(lds + PG8_SA(b, h) + aoff + m * 2048 + k * 1024); } while (0)
; #define PG8_MMA(ai, bj, At, Bt) do { __builtin_amdgcn_s_setprio(1); _Pragma("unroll") for (int m = 0; m < 4; ++m) _Pragma("unroll") for (int n = 0; n < 2; ++n) _Pragma("unroll") for (int k = 0; k < 2; ++k) \
;         acc[ai][bj][m][n] = __builtin_amdgcn_mfma_f32_16x16x32_bf16(Bt[n][k], At[m][k], acc[ai][bj][m][n], 0, 0, 0); __builtin_amdgcn_s_setprio(0); } while (0)
; #define PG8_WAIT_V(n) asm volatile("s_waitcnt vmcnt(" #n ")" ::: "memory")
; #define PG8_WAIT_L(n) asm volatile("s_waitcnt lgkmcnt(" #n ")" ::: "memory")
; #define PG8_BAR __builtin_amdgcn_s_barrier()
; #define PG8_SCHED __builtin_amdgcn_sched_barrier(0)
; template <class Epi, class Sched, bool ALIGN_EPI = false, bool SP2 = false>
; __device__ __forceinline__ void gemm_phase(PG8_LAS unsigned char* lds, const Gemm g, const Sched& S, const Epi& E) {
;     ...
;             PG8_LDA(At, 1, 1); PG8_STAGE(PG8_SB(1, 0), b3, voffB); PG8_STAGE(PG8_SB(1, 1), b3 + hstep, voffB); PG8_STAGE(PG8_SA(1, 0), a3, voffA);
;             PG8_WAIT_V(8); PG8_WAIT_L(0); PG8_BAR; PG8_MMA(1, 0, At, B0); PG8_MMA(1, 1, At, B1); PG8_BAR; PG8_SCHED;
	s_add_i32 s28, s55, s33
	v_lshl_add_u64 v[216:217], v[216:217], 0, s[10:11]
	s_mov_b32 m0, s28
	ds_read_b128 v[184:187], v150 offset:49152
	ds_read_b128 v[188:191], v150 offset:50176
	ds_read_b128 v[192:195], v150 offset:51200
	ds_read_b128 v[196:199], v150 offset:52224
	ds_read_b128 v[200:203], v150 offset:53248
	ds_read_b128 v[204:207], v150 offset:54272
	ds_read_b128 v[208:211], v150 offset:55296
	ds_read_b128 v[212:215], v150 offset:56320
	global_load_lds_dwordx4 v[216:217], off
	s_add_i32 m0, s28, 0x2000
	s_add_u32 s26, s26, 0x40080
	v_lshl_add_u64 v[216:217], v[218:219], 0, s[10:11]
	s_addc_u32 s27, s27, 0
	s_add_i32 s28, s56, s33
	global_load_lds_dwordx4 v[216:217], off
	v_lshl_add_u64 v[216:217], s[26:27], 0, v[132:133]
	s_mov_b32 m0, s28
	s_nop 0
	global_load_lds_dwordx4 v[216:217], off
	v_lshl_add_u64 v[216:217], s[26:27], 0, v[128:129]
	s_add_i32 m0, s28, 0x2000
	s_nop 0
	global_load_lds_dwordx4 v[216:217], off
	v_lshl_add_u64 v[216:217], v[220:221], 0, s[10:11]
	s_mov_b32 m0, s42
	s_nop 0
	global_load_lds_dwordx4 v[216:217], off
	v_lshl_add_u64 v[216:217], v[222:223], 0, s[10:11]
	s_mov_b32 m0, s43
	s_nop 0
	global_load_lds_dwordx4 v[216:217], off
	s_waitcnt vmcnt(8)
	s_waitcnt lgkmcnt(0)
	s_barrier
	s_setprio 1
	s_waitcnt lgkmcnt(0)
	v_mfma_f32_16x16x32_bf16 v[60:63], v[152:155], v[184:187], v[60:63]
	v_mfma_f32_16x16x32_bf16 v[56:59], v[160:163], v[184:187], v[56:59]
	v_mfma_f32_16x16x32_bf16 v[44:47], v[152:155], v[192:195], v[44:47]
	v_mfma_f32_16x16x32_bf16 v[40:43], v[160:163], v[192:195], v[40:43]
	v_mfma_f32_16x16x32_bf16 v[28:31], v[152:155], v[200:203], v[28:31]
	v_mfma_f32_16x16x32_bf16 v[24:27], v[160:163], v[200:203], v[24:27]
	v_mfma_f32_16x16x32_bf16 v[12:15], v[152:155], v[208:211], v[12:15]
	v_mfma_f32_16x16x32_bf16 v[8:11], v[160:163], v[208:211], v[8:11]
	v_mfma_f32_16x16x32_bf16 v[60:63], v[156:159], v[188:191], v[60:63]
	v_mfma_f32_16x16x32_bf16 v[56:59], v[164:167], v[188:191], v[56:59]
	v_mfma_f32_16x16x32_bf16 v[44:47], v[156:159], v[196:199], v[44:47]
	v_mfma_f32_16x16x32_bf16 v[40:43], v[164:167], v[196:199], v[40:43]
	v_mfma_f32_16x16x32_bf16 v[28:31], v[156:159], v[204:207], v[28:31]
	v_mfma_f32_16x16x32_bf16 v[24:27], v[164:167], v[204:207], v[24:27]
	v_mfma_f32_16x16x32_bf16 v[12:15], v[156:159], v[212:215], v[12:15]
	v_mfma_f32_16x16x32_bf16 v[8:11], v[164:167], v[212:215], v[8:11]
	s_setprio 0
	s_setprio 1
	v_mfma_f32_16x16x32_bf16 v[52:55], v[168:171], v[184:187], v[52:55]
	v_mfma_f32_16x16x32_bf16 v[48:51], v[176:179], v[184:187], v[48:51]
	v_mfma_f32_16x16x32_bf16 v[36:39], v[168:171], v[192:195], v[36:39]
	v_mfma_f32_16x16x32_bf16 v[32:35], v[176:179], v[192:195], v[32:35]
	v_mfma_f32_16x16x32_bf16 v[20:23], v[168:171], v[200:203], v[20:23]
	v_mfma_f32_16x16x32_bf16 v[16:19], v[176:179], v[200:203], v[16:19]
	v_mfma_f32_16x16x32_bf16 v[4:7], v[168:171], v[208:211], v[4:7]
	v_mfma_f32_16x16x32_bf16 v[0:3], v[176:179], v[208:211], v[0:3]
	v_mfma_f32_16x16x32_bf16 v[52:55], v[172:175], v[188:191], v[52:55]
	v_mfma_f32_16x16x32_bf16 v[48:51], v[180:183], v[188:191], v[48:51]
	v_mfma_f32_16x16x32_bf16 v[36:39], v[172:175], v[196:199], v[36:39]
	v_mfma_f32_16x16x32_bf16 v[32:35], v[180:183], v[196:199], v[32:35]
	v_mfma_f32_16x16x32_bf16 v[20:23], v[172:175], v[204:207], v[20:23]
	v_mfma_f32_16x16x32_bf16 v[16:19], v[180:183], v[204:207], v[16:19]
	v_mfma_f32_16x16x32_bf16 v[4:7], v[172:175], v[212:215], v[4:7]
	v_mfma_f32_16x16x32_bf16 v[0:3], v[180:183], v[212:215], v[0:3]
	s_setprio 0
	s_barrier
	s_add_i32 s54, s54, 2
	s_add_u32 s24, s24, 0x100
	s_addc_u32 s25, s25, 0
	s_add_u32 s52, s52, 0x100
	s_addc_u32 s53, s53, 0
	s_cmp_gt_u32 s54, 13
